# GEMM K-loops: LDS-DMA loads use SGPR base + 32-bit lane offset (address VALU removed), on top of the attention edits
# speedup vs baseline: 1.0075x; 1.0075x over previous
; #define PG8_STAGE(bufoff, gbase, voff) do { _Pragma("unroll") for (int _i = 0; _i < 2; ++_i) \
;         __builtin_amdgcn_global_load_lds((const unsigned*)((const char*)(gbase) + (voff)[_i]), (PG8_LAS unsigned*)(lds + (bufoff) + ldsw + _i * 8192), 16, 0, 0); } while (0)
; #define PG8_LDA(dst, b, h) do { _Pragma("unroll") for (int m = 0; m < 4; ++m) _Pragma("unroll") for (int k = 0; k < 2; ++k) dst[m][k] = *(const PG8_LAS bf16x8*)(lds + PG8_SA(b, h) + aoff + m * 2048 + k * 1024); } while (0)
; #define PG8_LDB(dst, b, h) do { _Pragma("unroll") for (int n = 0; n < 2; ++n) _Pragma("unroll") for (int k = 0; k < 2; ++k) dst[n][k] = *(const PG8_LAS bf16x8*)(lds + PG8_SB(b, h) + boff + n * 2048 + k * 1024); } while (0)
; #define PG8_MMA(ai, bj, At, Bt) do { __builtin_amdgcn_s_setprio(1); _Pragma("unroll") for (int m = 0; m < 4; ++m) _Pragma("unroll") for (int n = 0; n < 2; ++n) _Pragma("unroll") for (int k = 0; k < 2; ++k) \
;         acc[ai][bj][m][n] = __builtin_amdgcn_mfma_f32_16x16x32_bf16(Bt[n][k], At[m][k], acc[ai][bj][m][n], 0, 0, 0); __builtin_amdgcn_s_setprio(0); } while (0)
; #define PG8_WAIT_V(n) asm volatile("s_waitcnt vmcnt(" #n ")" ::: "memory")
; #define PG8_WAIT_L(n) asm volatile("s_waitcnt lgkmcnt(" #n ")" ::: "memory")
; template <class Epi, class Sched, bool ALIGN_EPI = false, bool SP2 = false>
; __device__ __forceinline__ void gemm_phase(PG8_LAS unsigned char* lds, const Gemm g, const Sched& S, const Epi& E) {
;     ...
;             const bool last = (t == nt - 2);
;             const char* a1 = cA + (size_t)(t + 1) * kstep;
;             const char* a2 = last ? nA : cA + (size_t)(t + 2) * kstep; const char* b2 = last ? nB : cB + (size_t)(t + 2) * kstep;
;             const char* a3 = a2 + kstep; const char* b3 = b2 + kstep;
;             if (last && has_next) S.a_ready(nxt);
;             if constexpr (SP2) {
;             PG8_LDB(B0, 0, 0); PG8_LDB(B1, 0, 1); PG8_SCHED; PG8_LDA(At, 0, 0); PG8_STAGE(PG8_SA(1, 1), a1 + hstep, voffA);
;             PG8_WAIT_V(8); PG8_WAIT_L(0); PG8_BAR; PG8_MMA(0, 0, At, B0); PG8_MMA(0, 1, At, B1); PG8_BAR; PG8_SCHED;
;             PG8_LDA(At, 0, 1); PG8_STAGE(PG8_SB(0, 0), b2, voffB); PG8_STAGE(PG8_SB(0, 1), b2 + hstep, voffB); PG8_STAGE(PG8_SA(0, 0), a2, voffA);
;             PG8_WAIT_V(8); PG8_WAIT_L(0); PG8_BAR; PG8_MMA(1, 0, At, B0); PG8_MMA(1, 1, At, B1); PG8_BAR; PG8_SCHED;
.LBB0_211:
	ds_read_b128 v[148:151], v158
	ds_read_b128 v[152:155], v158 offset:1024
	ds_read_b128 v[162:165], v158 offset:2048
	ds_read_b128 v[166:169], v158 offset:3072
	ds_read_b128 v[170:173], v159
	ds_read_b128 v[174:177], v159 offset:1024
	ds_read_b128 v[182:185], v159 offset:2048
	ds_read_b128 v[186:189], v159 offset:3072
	s_add_u32 s26, s24, 0xfffc0080
	s_addc_u32 s27, s25, -1
	s_cmp_eq_u32 s75, 12
	s_cselect_b32 s29, s17, s27
	s_cselect_b32 s28, s65, s26
	s_cselect_b32 s27, s15, s74
	s_cselect_b32 s26, s66, s67
	s_add_i32 m0, s35, 0xc000
	ds_read_b128 v[190:193], v160
	ds_read_b128 v[194:197], v160 offset:1024
	ds_read_b128 v[198:201], v160 offset:2048
	ds_read_b128 v[202:205], v160 offset:3072
	ds_read_b128 v[206:209], v160 offset:4096
	ds_read_b128 v[210:213], v160 offset:5120
	ds_read_b128 v[214:217], v160 offset:6144
	ds_read_b128 v[218:221], v160 offset:7168
	global_load_lds_dwordx4 v140, s[24:25]
	s_add_i32 m0, s35, 0xe000
	s_nop 0
	global_load_lds_dwordx4 v142, s[24:25]
	s_waitcnt vmcnt(8)
	s_waitcnt lgkmcnt(0)
	s_barrier
	s_setprio 1
	s_waitcnt lgkmcnt(0)
	v_mfma_f32_16x16x32_bf16 v[126:129], v[148:151], v[190:193], v[126:129]
	v_mfma_f32_16x16x32_bf16 v[122:125], v[162:165], v[190:193], v[122:125]
	v_mfma_f32_16x16x32_bf16 v[118:121], v[148:151], v[198:201], v[118:121]
	v_mfma_f32_16x16x32_bf16 v[114:117], v[162:165], v[198:201], v[114:117]
	v_mfma_f32_16x16x32_bf16 v[110:113], v[148:151], v[206:209], v[110:113]
	v_mfma_f32_16x16x32_bf16 v[106:109], v[162:165], v[206:209], v[106:109]
	v_mfma_f32_16x16x32_bf16 v[102:105], v[148:151], v[214:217], v[102:105]
	v_mfma_f32_16x16x32_bf16 v[98:101], v[162:165], v[214:217], v[98:101]
	v_mfma_f32_16x16x32_bf16 v[126:129], v[152:155], v[194:197], v[126:129]
	v_mfma_f32_16x16x32_bf16 v[122:125], v[166:169], v[194:197], v[122:125]
	v_mfma_f32_16x16x32_bf16 v[118:121], v[152:155], v[202:205], v[118:121]
	v_mfma_f32_16x16x32_bf16 v[114:117], v[166:169], v[202:205], v[114:117]
	v_mfma_f32_16x16x32_bf16 v[110:113], v[152:155], v[210:213], v[110:113]
	v_mfma_f32_16x16x32_bf16 v[106:109], v[166:169], v[210:213], v[106:109]
	v_mfma_f32_16x16x32_bf16 v[102:105], v[152:155], v[218:221], v[102:105]
	v_mfma_f32_16x16x32_bf16 v[98:101], v[166:169], v[218:221], v[98:101]
	s_setprio 0
	s_setprio 1
	v_mfma_f32_16x16x32_bf16 v[70:73], v[170:173], v[190:193], v[70:73]
	v_mfma_f32_16x16x32_bf16 v[62:65], v[182:185], v[190:193], v[62:65]
	v_mfma_f32_16x16x32_bf16 v[54:57], v[170:173], v[198:201], v[54:57]
	v_mfma_f32_16x16x32_bf16 v[50:53], v[182:185], v[198:201], v[50:53]
	v_mfma_f32_16x16x32_bf16 v[46:49], v[170:173], v[206:209], v[46:49]
	v_mfma_f32_16x16x32_bf16 v[42:45], v[182:185], v[206:209], v[42:45]
	v_mfma_f32_16x16x32_bf16 v[38:41], v[170:173], v[214:217], v[38:41]
	v_mfma_f32_16x16x32_bf16 v[34:37], v[182:185], v[214:217], v[34:37]
	v_mfma_f32_16x16x32_bf16 v[70:73], v[174:177], v[194:197], v[70:73]
	v_mfma_f32_16x16x32_bf16 v[62:65], v[186:189], v[194:197], v[62:65]
	v_mfma_f32_16x16x32_bf16 v[54:57], v[174:177], v[202:205], v[54:57]
	v_mfma_f32_16x16x32_bf16 v[50:53], v[186:189], v[202:205], v[50:53]
	v_mfma_f32_16x16x32_bf16 v[46:49], v[174:177], v[210:213], v[46:49]
	v_mfma_f32_16x16x32_bf16 v[42:45], v[186:189], v[210:213], v[42:45]
	v_mfma_f32_16x16x32_bf16 v[38:41], v[174:177], v[218:221], v[38:41]
	v_mfma_f32_16x16x32_bf16 v[34:37], v[186:189], v[218:221], v[34:37]
	s_setprio 0
	s_barrier
	s_add_i32 s76, s47, s30
	s_mov_b32 m0, s76
	ds_read_b128 v[190:193], v160 offset:16384
	ds_read_b128 v[194:197], v160 offset:17408
	ds_read_b128 v[198:201], v160 offset:18432
	ds_read_b128 v[202:205], v160 offset:19456
	ds_read_b128 v[206:209], v160 offset:20480
	ds_read_b128 v[210:213], v160 offset:21504
	ds_read_b128 v[214:217], v160 offset:22528
	ds_read_b128 v[218:221], v160 offset:23552
	global_load_lds_dwordx4 v136, s[26:27]
	s_add_i32 m0, s76, 0x2000
	s_add_u32 s76, s26, 0x40000
	v_lshl_add_u64 v[222:223], s[26:27], 0, v[132:133]
	s_addc_u32 s77, s27, 0
	s_add_i32 s82, s56, s30
	global_load_lds_dwordx4 v132, s[26:27]
	s_mov_b32 m0, s82
	v_lshl_add_u64 v[226:227], s[28:29], 0, v[134:135]
	global_load_lds_dwordx4 v136, s[76:77]
	s_add_i32 m0, s82, 0x2000
	s_nop 0
	global_load_lds_dwordx4 v132, s[76:77]
	v_lshl_add_u64 v[224:225], s[28:29], 0, v[138:139]
	s_mov_b32 m0, s35
	s_nop 0
	global_load_lds_dwordx4 v138, s[28:29]
	s_mov_b32 m0, s36
	s_nop 0
	global_load_lds_dwordx4 v134, s[28:29]
	s_waitcnt vmcnt(8)
	s_waitcnt lgkmcnt(0)
	s_barrier
	s_setprio 1
	s_waitcnt lgkmcnt(0)
	v_mfma_f32_16x16x32_bf16 v[94:97], v[148:151], v[190:193], v[94:97]
	v_mfma_f32_16x16x32_bf16 v[90:93], v[162:165], v[190:193], v[90:93]
	v_mfma_f32_16x16x32_bf16 v[86:89], v[148:151], v[198:201], v[86:89]
	v_mfma_f32_16x16x32_bf16 v[82:85], v[162:165], v[198:201], v[82:85]
	v_mfma_f32_16x16x32_bf16 v[78:81], v[148:151], v[206:209], v[78:81]
	v_mfma_f32_16x16x32_bf16 v[74:77], v[162:165], v[206:209], v[74:77]
	v_mfma_f32_16x16x32_bf16 v[66:69], v[148:151], v[214:217], v[66:69]
	v_mfma_f32_16x16x32_bf16 v[58:61], v[162:165], v[214:217], v[58:61]
	v_mfma_f32_16x16x32_bf16 v[94:97], v[152:155], v[194:197], v[94:97]
	v_mfma_f32_16x16x32_bf16 v[90:93], v[166:169], v[194:197], v[90:93]
	v_mfma_f32_16x16x32_bf16 v[86:89], v[152:155], v[202:205], v[86:89]
	v_mfma_f32_16x16x32_bf16 v[82:85], v[166:169], v[202:205], v[82:85]
	v_mfma_f32_16x16x32_bf16 v[78:81], v[152:155], v[210:213], v[78:81]
	v_mfma_f32_16x16x32_bf16 v[74:77], v[166:169], v[210:213], v[74:77]
	v_mfma_f32_16x16x32_bf16 v[66:69], v[152:155], v[218:221], v[66:69]
	v_mfma_f32_16x16x32_bf16 v[58:61], v[166:169], v[218:221], v[58:61]
	s_setprio 0
	s_setprio 1
	v_mfma_f32_16x16x32_bf16 v[30:33], v[170:173], v[190:193], v[30:33]
	v_mfma_f32_16x16x32_bf16 v[26:29], v[182:185], v[190:193], v[26:29]
	v_mfma_f32_16x16x32_bf16 v[22:25], v[170:173], v[198:201], v[22:25]
	v_mfma_f32_16x16x32_bf16 v[18:21], v[182:185], v[198:201], v[18:21]
	v_mfma_f32_16x16x32_bf16 v[14:17], v[170:173], v[206:209], v[14:17]
	v_mfma_f32_16x16x32_bf16 v[10:13], v[182:185], v[206:209], v[10:13]
	v_mfma_f32_16x16x32_bf16 v[6:9], v[170:173], v[214:217], v[6:9]
	v_mfma_f32_16x16x32_bf16 v[2:5], v[182:185], v[214:217], v[2:5]
	v_mfma_f32_16x16x32_bf16 v[30:33], v[174:177], v[194:197], v[30:33]
	v_mfma_f32_16x16x32_bf16 v[26:29], v[186:189], v[194:197], v[26:29]
	v_mfma_f32_16x16x32_bf16 v[22:25], v[174:177], v[202:205], v[22:25]
	v_mfma_f32_16x16x32_bf16 v[18:21], v[186:189], v[202:205], v[18:21]
	v_mfma_f32_16x16x32_bf16 v[14:17], v[174:177], v[210:213], v[14:17]
	v_mfma_f32_16x16x32_bf16 v[10:13], v[186:189], v[210:213], v[10:13]
	v_mfma_f32_16x16x32_bf16 v[6:9], v[174:177], v[218:221], v[6:9]
	v_mfma_f32_16x16x32_bf16 v[2:5], v[186:189], v[218:221], v[2:5]
	s_setprio 0
	s_barrier
; #define PG8_STAGE(bufoff, gbase, voff) do { _Pragma("unroll") for (int _i = 0; _i < 2; ++_i) \
;         __builtin_amdgcn_global_load_lds((const unsigned*)((const char*)(gbase) + (voff)[_i]), (PG8_LAS unsigned*)(lds + (bufoff) + ldsw + _i * 8192), 16, 0, 0); } while (0)
; #define PG8_LDA(dst, b, h) do { _Pragma("unroll") for (int m = 0; m < 4; ++m) _Pragma("unroll") for (int k = 0; k < 2; ++k) dst[m][k] = *(const PG8_LAS bf16x8*)(lds + PG8_SA(b, h) + aoff + m * 2048 + k * 1024); } while (0)
; #define PG8_LDB(dst, b, h) do { _Pragma("unroll") for (int n = 0; n < 2; ++n) _Pragma("unroll") for (int k = 0; k < 2; ++k) dst[n][k] = *(const PG8_LAS bf16x8*)(lds + PG8_SB(b, h) + boff + n * 2048 + k * 1024); } while (0)
; #define PG8_MMA(ai, bj, At, Bt) do { __builtin_amdgcn_s_setprio(1); _Pragma("unroll") for (int m = 0; m < 4; ++m) _Pragma("unroll") for (int n = 0; n < 2; ++n) _Pragma("unroll") for (int k = 0; k < 2; ++k) \
;         acc[ai][bj][m][n] = __builtin_amdgcn_mfma_f32_16x16x32_bf16(Bt[n][k], At[m][k], acc[ai][bj][m][n], 0, 0, 0); __builtin_amdgcn_s_setprio(0); } while (0)
; #define PG8_WAIT_V(n) asm volatile("s_waitcnt vmcnt(" #n ")" ::: "memory")
; #define PG8_WAIT_L(n) asm volatile("s_waitcnt lgkmcnt(" #n ")" ::: "memory")
; #define PG8_BAR __builtin_amdgcn_s_barrier()
; #define PG8_SCHED __builtin_amdgcn_sched_barrier(0)
; template <class Epi, class Sched, bool ALIGN_EPI = false, bool SP2 = false>
; __device__ __forceinline__ void gemm_phase(PG8_LAS unsigned char* lds, const Gemm g, const Sched& S, const Epi& E) {
;     ...
;             PG8_LDB(B0, 1, 0); PG8_LDB(B1, 1, 1); PG8_SCHED; PG8_LDA(At, 1, 0); PG8_STAGE(PG8_SA(0, 1), a2 + hstep, voffA);
;             PG8_WAIT_V(8); PG8_WAIT_L(0); PG8_BAR; PG8_MMA(0, 0, At, B0); PG8_MMA(0, 1, At, B1); PG8_BAR; PG8_SCHED;
	s_add_i32 s76, 0, 0x18000
	v_add_u32_e32 v161, s76, v156
	s_add_i32 s77, 0, 0x1c000
	ds_read_b128 v[148:151], v161
	ds_read_b128 v[152:155], v161 offset:1024
	ds_read_b128 v[162:165], v161 offset:2048
	ds_read_b128 v[166:169], v161 offset:3072
	v_add_u32_e32 v161, s77, v156
	ds_read_b128 v[170:173], v161
	ds_read_b128 v[174:177], v161 offset:1024
	ds_read_b128 v[182:185], v161 offset:2048
	ds_read_b128 v[186:189], v161 offset:3072
	s_add_u32 s28, s28, 0x40000
	s_addc_u32 s29, s29, 0
	s_mov_b32 m0, s37
	ds_read_b128 v[190:193], v160 offset:32768
	ds_read_b128 v[194:197], v160 offset:33792
	ds_read_b128 v[198:201], v160 offset:34816
	ds_read_b128 v[202:205], v160 offset:35840
	ds_read_b128 v[206:209], v160 offset:36864
	ds_read_b128 v[210:213], v160 offset:37888
	ds_read_b128 v[214:217], v160 offset:38912
	ds_read_b128 v[218:221], v160 offset:39936
	global_load_lds_dwordx4 v138, s[28:29]
	v_lshl_add_u64 v[228:229], s[28:29], 0, v[134:135]
	s_mov_b32 m0, s38
	s_nop 0
	global_load_lds_dwordx4 v134, s[28:29]
	s_waitcnt vmcnt(8)
	s_waitcnt lgkmcnt(0)
	s_barrier
	s_setprio 1
	s_waitcnt lgkmcnt(0)
	v_mfma_f32_16x16x32_bf16 v[126:129], v[148:151], v[190:193], v[126:129]
	v_mfma_f32_16x16x32_bf16 v[122:125], v[162:165], v[190:193], v[122:125]
	v_mfma_f32_16x16x32_bf16 v[118:121], v[148:151], v[198:201], v[118:121]
	v_mfma_f32_16x16x32_bf16 v[114:117], v[162:165], v[198:201], v[114:117]
	v_mfma_f32_16x16x32_bf16 v[110:113], v[148:151], v[206:209], v[110:113]
	v_mfma_f32_16x16x32_bf16 v[106:109], v[162:165], v[206:209], v[106:109]
	v_mfma_f32_16x16x32_bf16 v[102:105], v[148:151], v[214:217], v[102:105]
	v_mfma_f32_16x16x32_bf16 v[98:101], v[162:165], v[214:217], v[98:101]
	v_mfma_f32_16x16x32_bf16 v[126:129], v[152:155], v[194:197], v[126:129]
	v_mfma_f32_16x16x32_bf16 v[122:125], v[166:169], v[194:197], v[122:125]
	v_mfma_f32_16x16x32_bf16 v[118:121], v[152:155], v[202:205], v[118:121]
	v_mfma_f32_16x16x32_bf16 v[114:117], v[166:169], v[202:205], v[114:117]
	v_mfma_f32_16x16x32_bf16 v[110:113], v[152:155], v[210:213], v[110:113]
	v_mfma_f32_16x16x32_bf16 v[106:109], v[166:169], v[210:213], v[106:109]
	v_mfma_f32_16x16x32_bf16 v[102:105], v[152:155], v[218:221], v[102:105]
	v_mfma_f32_16x16x32_bf16 v[98:101], v[166:169], v[218:221], v[98:101]
	s_setprio 0
	s_setprio 1
	v_mfma_f32_16x16x32_bf16 v[70:73], v[170:173], v[190:193], v[70:73]
	v_mfma_f32_16x16x32_bf16 v[62:65], v[182:185], v[190:193], v[62:65]
	v_mfma_f32_16x16x32_bf16 v[54:57], v[170:173], v[198:201], v[54:57]
	v_mfma_f32_16x16x32_bf16 v[50:53], v[182:185], v[198:201], v[50:53]
	v_mfma_f32_16x16x32_bf16 v[46:49], v[170:173], v[206:209], v[46:49]
	v_mfma_f32_16x16x32_bf16 v[42:45], v[182:185], v[206:209], v[42:45]
	v_mfma_f32_16x16x32_bf16 v[38:41], v[170:173], v[214:217], v[38:41]
	v_mfma_f32_16x16x32_bf16 v[34:37], v[182:185], v[214:217], v[34:37]
	v_mfma_f32_16x16x32_bf16 v[70:73], v[174:177], v[194:197], v[70:73]
	v_mfma_f32_16x16x32_bf16 v[62:65], v[186:189], v[194:197], v[62:65]
	v_mfma_f32_16x16x32_bf16 v[54:57], v[174:177], v[202:205], v[54:57]
	v_mfma_f32_16x16x32_bf16 v[50:53], v[186:189], v[202:205], v[50:53]
	v_mfma_f32_16x16x32_bf16 v[46:49], v[174:177], v[210:213], v[46:49]
	v_mfma_f32_16x16x32_bf16 v[42:45], v[186:189], v[210:213], v[42:45]
	v_mfma_f32_16x16x32_bf16 v[38:41], v[174:177], v[218:221], v[38:41]
	v_mfma_f32_16x16x32_bf16 v[34:37], v[186:189], v[218:221], v[34:37]
	s_setprio 0
	s_barrier
; #define PG8_STAGE(bufoff, gbase, voff) do { _Pragma("unroll") for (int _i = 0; _i < 2; ++_i) \
;         __builtin_amdgcn_global_load_lds((const unsigned*)((const char*)(gbase) + (voff)[_i]), (PG8_LAS unsigned*)(lds + (bufoff) + ldsw + _i * 8192), 16, 0, 0); } while (0)
; #define PG8_LDA(dst, b, h) do { _Pragma("unroll") for (int m = 0; m < 4; ++m) _Pragma("unroll") for (int k = 0; k < 2; ++k) dst[m][k] = *(const PG8_LAS bf16x8*)(lds + PG8_SA(b, h) + aoff + m * 2048 + k * 1024); } while (0)
; #define PG8_MMA(ai, bj, At, Bt) do { __builtin_amdgcn_s_setprio(1); _Pragma("unroll") for (int m = 0; m < 4; ++m) _Pragma("unroll") for (int n = 0; n < 2; ++n) _Pragma("unroll") for (int k = 0; k < 2; ++k) \
;         acc[ai][bj][m][n] = __builtin_amdgcn_mfma_f32_16x16x32_bf16(Bt[n][k], At[m][k], acc[ai][bj][m][n], 0, 0, 0); __builtin_amdgcn_s_setprio(0); } while (0)
; #define PG8_WAIT_V(n) asm volatile("s_waitcnt vmcnt(" #n ")" ::: "memory")
; #define PG8_WAIT_L(n) asm volatile("s_waitcnt lgkmcnt(" #n ")" ::: "memory")
; #define PG8_BAR __builtin_amdgcn_s_barrier()
; #define PG8_SCHED __builtin_amdgcn_sched_barrier(0)
; template <class Epi, class Sched, bool ALIGN_EPI = false, bool SP2 = false>
; __device__ __forceinline__ void gemm_phase(PG8_LAS unsigned char* lds, const Gemm g, const Sched& S, const Epi& E) {
;     ...
;         for (int t = 0; t < nt; t += 2) {
;     ...
;             PG8_LDA(At, 1, 1); PG8_STAGE(PG8_SB(1, 0), b3, voffB); PG8_STAGE(PG8_SB(1, 1), b3 + hstep, voffB); PG8_STAGE(PG8_SA(1, 0), a3, voffA);
;             PG8_WAIT_V(8); PG8_WAIT_L(0); PG8_BAR; PG8_MMA(1, 0, At, B0); PG8_MMA(1, 1, At, B1); PG8_BAR; PG8_SCHED;
	s_add_i32 s28, s76, s30
	s_mov_b32 m0, s28
	ds_read_b128 v[190:193], v160 offset:49152
	ds_read_b128 v[194:197], v160 offset:50176
	ds_read_b128 v[198:201], v160 offset:51200
	ds_read_b128 v[202:205], v160 offset:52224
	ds_read_b128 v[206:209], v160 offset:53248
	ds_read_b128 v[210:213], v160 offset:54272
	ds_read_b128 v[214:217], v160 offset:55296
	ds_read_b128 v[218:221], v160 offset:56320
	s_add_u32 s98, s26, s10
	s_addc_u32 s99, s27, s11
	global_load_lds_dwordx4 v136, s[98:99]
	s_add_i32 m0, s28, 0x2000
	s_add_u32 s26, s26, 0x40080
	v_lshl_add_u64 v[178:179], v[222:223], 0, s[10:11]
	s_addc_u32 s27, s27, 0
	s_add_i32 s28, s77, s30
	global_load_lds_dwordx4 v[178:179], off
	s_mov_b32 m0, s28
	s_nop 0
	global_load_lds_dwordx4 v136, s[26:27]
	s_add_i32 m0, s28, 0x2000
	s_nop 0
	global_load_lds_dwordx4 v132, s[26:27]
	v_lshl_add_u64 v[178:179], v[224:225], 0, s[10:11]
	s_mov_b32 m0, s40
	s_nop 0
	global_load_lds_dwordx4 v[178:179], off
	v_lshl_add_u64 v[178:179], v[226:227], 0, s[10:11]
	s_mov_b32 m0, s41
	s_nop 0
	global_load_lds_dwordx4 v[178:179], off
	s_waitcnt vmcnt(8)
	s_waitcnt lgkmcnt(0)
	s_barrier
	s_setprio 1
	s_waitcnt lgkmcnt(0)
	v_mfma_f32_16x16x32_bf16 v[94:97], v[148:151], v[190:193], v[94:97]
	v_mfma_f32_16x16x32_bf16 v[90:93], v[162:165], v[190:193], v[90:93]
	v_mfma_f32_16x16x32_bf16 v[86:89], v[148:151], v[198:201], v[86:89]
	v_mfma_f32_16x16x32_bf16 v[82:85], v[162:165], v[198:201], v[82:85]
	v_mfma_f32_16x16x32_bf16 v[78:81], v[148:151], v[206:209], v[78:81]
	v_mfma_f32_16x16x32_bf16 v[74:77], v[162:165], v[206:209], v[74:77]
	v_mfma_f32_16x16x32_bf16 v[66:69], v[148:151], v[214:217], v[66:69]
	v_mfma_f32_16x16x32_bf16 v[58:61], v[162:165], v[214:217], v[58:61]
	v_mfma_f32_16x16x32_bf16 v[94:97], v[152:155], v[194:197], v[94:97]
	v_mfma_f32_16x16x32_bf16 v[90:93], v[166:169], v[194:197], v[90:93]
	v_mfma_f32_16x16x32_bf16 v[86:89], v[152:155], v[202:205], v[86:89]
	v_mfma_f32_16x16x32_bf16 v[82:85], v[166:169], v[202:205], v[82:85]
	v_mfma_f32_16x16x32_bf16 v[78:81], v[152:155], v[210:213], v[78:81]
	v_mfma_f32_16x16x32_bf16 v[74:77], v[166:169], v[210:213], v[74:77]
	v_mfma_f32_16x16x32_bf16 v[66:69], v[152:155], v[218:221], v[66:69]
	v_mfma_f32_16x16x32_bf16 v[58:61], v[166:169], v[218:221], v[58:61]
	s_setprio 0
	s_setprio 1
	v_mfma_f32_16x16x32_bf16 v[30:33], v[170:173], v[190:193], v[30:33]
	v_mfma_f32_16x16x32_bf16 v[26:29], v[182:185], v[190:193], v[26:29]
	v_mfma_f32_16x16x32_bf16 v[22:25], v[170:173], v[198:201], v[22:25]
	v_mfma_f32_16x16x32_bf16 v[18:21], v[182:185], v[198:201], v[18:21]
	v_mfma_f32_16x16x32_bf16 v[14:17], v[170:173], v[206:209], v[14:17]
	v_mfma_f32_16x16x32_bf16 v[10:13], v[182:185], v[206:209], v[10:13]
	v_mfma_f32_16x16x32_bf16 v[6:9], v[170:173], v[214:217], v[6:9]
	v_mfma_f32_16x16x32_bf16 v[2:5], v[182:185], v[214:217], v[2:5]
	v_mfma_f32_16x16x32_bf16 v[30:33], v[174:177], v[194:197], v[30:33]
	v_mfma_f32_16x16x32_bf16 v[26:29], v[186:189], v[194:197], v[26:29]
	v_mfma_f32_16x16x32_bf16 v[22:25], v[174:177], v[202:205], v[22:25]
	v_mfma_f32_16x16x32_bf16 v[18:21], v[186:189], v[202:205], v[18:21]
	v_mfma_f32_16x16x32_bf16 v[14:17], v[174:177], v[210:213], v[14:17]
	v_mfma_f32_16x16x32_bf16 v[10:13], v[186:189], v[210:213], v[10:13]
	v_mfma_f32_16x16x32_bf16 v[6:9], v[174:177], v[218:221], v[6:9]
	v_mfma_f32_16x16x32_bf16 v[2:5], v[186:189], v[218:221], v[2:5]
	s_setprio 0
	s_barrier
	s_add_i32 s75, s75, 2
	s_add_u32 s24, s24, 0x100
	s_addc_u32 s25, s25, 0
	s_add_u32 s67, s67, 0x100
	s_addc_u32 s74, s74, 0
	s_cmp_gt_u32 s75, 13
	s_cbranch_scc0 .LBB0_211
	s_and_b64 vcc, exec, s[12:13]
	s_cbranch_vccz .LBB0_214
	s_barrier

; #define PG8_STAGE(bufoff, gbase, voff) do { _Pragma("unroll") for (int _i = 0; _i < 2; ++_i) \
;         __builtin_amdgcn_global_load_lds((const unsigned*)((const char*)(gbase) + (voff)[_i]), (PG8_LAS unsigned*)(lds + (bufoff) + ldsw + _i * 8192), 16, 0, 0); } while (0)
; #define PG8_LDA(dst, b, h) do { _Pragma("unroll") for (int m = 0; m < 4; ++m) _Pragma("unroll") for (int k = 0; k < 2; ++k) dst[m][k] = *(const PG8_LAS bf16x8*)(lds + PG8_SA(b, h) + aoff + m * 2048 + k * 1024); } while (0)
; #define PG8_LDB(dst, b, h) do { _Pragma("unroll") for (int n = 0; n < 2; ++n) _Pragma("unroll") for (int k = 0; k < 2; ++k) dst[n][k] = *(const PG8_LAS bf16x8*)(lds + PG8_SB(b, h) + boff + n * 2048 + k * 1024); } while (0)
; #define PG8_MMA(ai, bj, At, Bt) do { __builtin_amdgcn_s_setprio(1); _Pragma("unroll") for (int m = 0; m < 4; ++m) _Pragma("unroll") for (int n = 0; n < 2; ++n) _Pragma("unroll") for (int k = 0; k < 2; ++k) \
;         acc[ai][bj][m][n] = __builtin_amdgcn_mfma_f32_16x16x32_bf16(Bt[n][k], At[m][k], acc[ai][bj][m][n], 0, 0, 0); __builtin_amdgcn_s_setprio(0); } while (0)
; #define PG8_WAIT_V(n) asm volatile("s_waitcnt vmcnt(" #n ")" ::: "memory")
; #define PG8_WAIT_L(n) asm volatile("s_waitcnt lgkmcnt(" #n ")" ::: "memory")
; template <class Epi, class Sched, bool ALIGN_EPI = false, bool SP2 = false>
; __device__ __forceinline__ void gemm_phase(PG8_LAS unsigned char* lds, const Gemm g, const Sched& S, const Epi& E) {
;     ...
;             const bool last = (t == nt - 2);
;             const char* a1 = cA + (size_t)(t + 1) * kstep;
;             const char* a2 = last ? nA : cA + (size_t)(t + 2) * kstep; const char* b2 = last ? nB : cB + (size_t)(t + 2) * kstep;
;             const char* a3 = a2 + kstep; const char* b3 = b2 + kstep;
;             if (last && has_next) S.a_ready(nxt);
;             if constexpr (SP2) {
;             PG8_LDB(B0, 0, 0); PG8_LDB(B1, 0, 1); PG8_SCHED; PG8_LDA(At, 0, 0); PG8_STAGE(PG8_SA(1, 1), a1 + hstep, voffA);
;             PG8_WAIT_V(8); PG8_WAIT_L(0); PG8_BAR; PG8_MMA(0, 0, At, B0); PG8_MMA(0, 1, At, B1); PG8_BAR; PG8_SCHED;
;             PG8_LDA(At, 0, 1); PG8_STAGE(PG8_SB(0, 0), b2, voffB); PG8_STAGE(PG8_SB(0, 1), b2 + hstep, voffB); PG8_STAGE(PG8_SA(0, 0), a2, voffA);
;             PG8_WAIT_V(8); PG8_WAIT_L(0); PG8_BAR; PG8_MMA(1, 0, At, B0); PG8_MMA(1, 1, At, B1); PG8_BAR; PG8_SCHED;
.LBB0_553:
	ds_read_b128 v[156:159], v153
	ds_read_b128 v[160:163], v153 offset:1024
	ds_read_b128 v[164:167], v153 offset:2048
	ds_read_b128 v[168:171], v153 offset:3072
	ds_read_b128 v[172:175], v154
	ds_read_b128 v[176:179], v154 offset:1024
	ds_read_b128 v[182:185], v154 offset:2048
	ds_read_b128 v[186:189], v154 offset:3072
	s_add_u32 s28, s26, 0xfffc0080
	s_addc_u32 s29, s27, -1
	s_cmp_eq_u32 s68, 12
	s_cselect_b32 s31, s19, s29
	s_cselect_b32 s30, s64, s28
	s_cselect_b32 s29, s17, s67
	s_cselect_b32 s28, s65, s66
	s_add_i32 m0, s25, 0xc000
	ds_read_b128 v[190:193], v155
	ds_read_b128 v[194:197], v155 offset:1024
	ds_read_b128 v[198:201], v155 offset:2048
	ds_read_b128 v[202:205], v155 offset:3072
	ds_read_b128 v[206:209], v155 offset:4096
	ds_read_b128 v[210:213], v155 offset:5120
	ds_read_b128 v[214:217], v155 offset:6144
	ds_read_b128 v[218:221], v155 offset:7168
	global_load_lds_dwordx4 v140, s[26:27]
	s_add_i32 m0, s25, 0xe000
	s_nop 0
	global_load_lds_dwordx4 v142, s[26:27]
	s_waitcnt vmcnt(8)
	s_waitcnt lgkmcnt(0)
	s_barrier
	s_setprio 1
	s_waitcnt lgkmcnt(0)
	v_mfma_f32_16x16x32_bf16 v[126:129], v[156:159], v[190:193], v[126:129]
	v_mfma_f32_16x16x32_bf16 v[122:125], v[164:167], v[190:193], v[122:125]
	v_mfma_f32_16x16x32_bf16 v[118:121], v[156:159], v[198:201], v[118:121]
	v_mfma_f32_16x16x32_bf16 v[110:113], v[164:167], v[198:201], v[110:113]
	v_mfma_f32_16x16x32_bf16 v[102:105], v[156:159], v[206:209], v[102:105]
	v_mfma_f32_16x16x32_bf16 v[94:97], v[164:167], v[206:209], v[94:97]
	v_mfma_f32_16x16x32_bf16 v[86:89], v[156:159], v[214:217], v[86:89]
	v_mfma_f32_16x16x32_bf16 v[78:81], v[164:167], v[214:217], v[78:81]
	v_mfma_f32_16x16x32_bf16 v[126:129], v[160:163], v[194:197], v[126:129]
	v_mfma_f32_16x16x32_bf16 v[122:125], v[168:171], v[194:197], v[122:125]
	v_mfma_f32_16x16x32_bf16 v[118:121], v[160:163], v[202:205], v[118:121]
	v_mfma_f32_16x16x32_bf16 v[110:113], v[168:171], v[202:205], v[110:113]
	v_mfma_f32_16x16x32_bf16 v[102:105], v[160:163], v[210:213], v[102:105]
	v_mfma_f32_16x16x32_bf16 v[94:97], v[168:171], v[210:213], v[94:97]
	v_mfma_f32_16x16x32_bf16 v[86:89], v[160:163], v[218:221], v[86:89]
	v_mfma_f32_16x16x32_bf16 v[78:81], v[168:171], v[218:221], v[78:81]
	s_setprio 0
	s_setprio 1
	v_mfma_f32_16x16x32_bf16 v[114:117], v[172:175], v[190:193], v[114:117]
	v_mfma_f32_16x16x32_bf16 v[106:109], v[182:185], v[190:193], v[106:109]
	v_mfma_f32_16x16x32_bf16 v[98:101], v[172:175], v[198:201], v[98:101]
	v_mfma_f32_16x16x32_bf16 v[90:93], v[182:185], v[198:201], v[90:93]
	v_mfma_f32_16x16x32_bf16 v[82:85], v[172:175], v[206:209], v[82:85]
	v_mfma_f32_16x16x32_bf16 v[74:77], v[182:185], v[206:209], v[74:77]
	v_mfma_f32_16x16x32_bf16 v[70:73], v[172:175], v[214:217], v[70:73]
	v_mfma_f32_16x16x32_bf16 v[66:69], v[182:185], v[214:217], v[66:69]
	v_mfma_f32_16x16x32_bf16 v[114:117], v[176:179], v[194:197], v[114:117]
	v_mfma_f32_16x16x32_bf16 v[106:109], v[186:189], v[194:197], v[106:109]
	v_mfma_f32_16x16x32_bf16 v[98:101], v[176:179], v[202:205], v[98:101]
	v_mfma_f32_16x16x32_bf16 v[90:93], v[186:189], v[202:205], v[90:93]
	v_mfma_f32_16x16x32_bf16 v[82:85], v[176:179], v[210:213], v[82:85]
	v_mfma_f32_16x16x32_bf16 v[74:77], v[186:189], v[210:213], v[74:77]
	v_mfma_f32_16x16x32_bf16 v[70:73], v[176:179], v[218:221], v[70:73]
	v_mfma_f32_16x16x32_bf16 v[66:69], v[186:189], v[218:221], v[66:69]
	s_setprio 0
	s_barrier
	s_add_i32 s69, s47, s35
	s_mov_b32 m0, s69
	ds_read_b128 v[190:193], v155 offset:16384
	ds_read_b128 v[194:197], v155 offset:17408
	ds_read_b128 v[198:201], v155 offset:18432
	ds_read_b128 v[202:205], v155 offset:19456
	ds_read_b128 v[206:209], v155 offset:20480
	ds_read_b128 v[210:213], v155 offset:21504
	ds_read_b128 v[214:217], v155 offset:22528
	ds_read_b128 v[218:221], v155 offset:23552
	global_load_lds_dwordx4 v134, s[28:29]
	s_add_i32 m0, s69, 0x2000
	s_add_u32 s70, s28, 0x40000
	v_lshl_add_u64 v[222:223], s[28:29], 0, v[138:139]
	s_addc_u32 s71, s29, 0
	s_add_i32 s69, s58, s35
	global_load_lds_dwordx4 v138, s[28:29]
	s_mov_b32 m0, s69
	v_lshl_add_u64 v[226:227], s[30:31], 0, v[136:137]
	global_load_lds_dwordx4 v134, s[70:71]
	s_add_i32 m0, s69, 0x2000
	s_nop 0
	global_load_lds_dwordx4 v138, s[70:71]
	v_lshl_add_u64 v[224:225], s[30:31], 0, v[132:133]
	s_mov_b32 m0, s25
	s_nop 0
	global_load_lds_dwordx4 v132, s[30:31]
	s_mov_b32 m0, s36
	s_nop 0
	global_load_lds_dwordx4 v136, s[30:31]
	s_waitcnt vmcnt(8)
	s_waitcnt lgkmcnt(0)
	s_barrier
	s_setprio 1
	s_waitcnt lgkmcnt(0)
	v_mfma_f32_16x16x32_bf16 v[62:65], v[156:159], v[190:193], v[62:65]
	v_mfma_f32_16x16x32_bf16 v[58:61], v[164:167], v[190:193], v[58:61]
	v_mfma_f32_16x16x32_bf16 v[54:57], v[156:159], v[198:201], v[54:57]
	v_mfma_f32_16x16x32_bf16 v[46:49], v[164:167], v[198:201], v[46:49]
	v_mfma_f32_16x16x32_bf16 v[38:41], v[156:159], v[206:209], v[38:41]
	v_mfma_f32_16x16x32_bf16 v[30:33], v[164:167], v[206:209], v[30:33]
	v_mfma_f32_16x16x32_bf16 v[22:25], v[156:159], v[214:217], v[22:25]
	v_mfma_f32_16x16x32_bf16 v[14:17], v[164:167], v[214:217], v[14:17]
	v_mfma_f32_16x16x32_bf16 v[62:65], v[160:163], v[194:197], v[62:65]
	v_mfma_f32_16x16x32_bf16 v[58:61], v[168:171], v[194:197], v[58:61]
	v_mfma_f32_16x16x32_bf16 v[54:57], v[160:163], v[202:205], v[54:57]
	v_mfma_f32_16x16x32_bf16 v[46:49], v[168:171], v[202:205], v[46:49]
	v_mfma_f32_16x16x32_bf16 v[38:41], v[160:163], v[210:213], v[38:41]
	v_mfma_f32_16x16x32_bf16 v[30:33], v[168:171], v[210:213], v[30:33]
	v_mfma_f32_16x16x32_bf16 v[22:25], v[160:163], v[218:221], v[22:25]
	v_mfma_f32_16x16x32_bf16 v[14:17], v[168:171], v[218:221], v[14:17]
	s_setprio 0
	s_setprio 1
	v_mfma_f32_16x16x32_bf16 v[50:53], v[172:175], v[190:193], v[50:53]
	v_mfma_f32_16x16x32_bf16 v[42:45], v[182:185], v[190:193], v[42:45]
	v_mfma_f32_16x16x32_bf16 v[34:37], v[172:175], v[198:201], v[34:37]
	v_mfma_f32_16x16x32_bf16 v[26:29], v[182:185], v[198:201], v[26:29]
	v_mfma_f32_16x16x32_bf16 v[18:21], v[172:175], v[206:209], v[18:21]
	v_mfma_f32_16x16x32_bf16 v[10:13], v[182:185], v[206:209], v[10:13]
	v_mfma_f32_16x16x32_bf16 v[6:9], v[172:175], v[214:217], v[6:9]
	v_mfma_f32_16x16x32_bf16 v[2:5], v[182:185], v[214:217], v[2:5]
	v_mfma_f32_16x16x32_bf16 v[50:53], v[176:179], v[194:197], v[50:53]
	v_mfma_f32_16x16x32_bf16 v[42:45], v[186:189], v[194:197], v[42:45]
	v_mfma_f32_16x16x32_bf16 v[34:37], v[176:179], v[202:205], v[34:37]
	v_mfma_f32_16x16x32_bf16 v[26:29], v[186:189], v[202:205], v[26:29]
	v_mfma_f32_16x16x32_bf16 v[18:21], v[176:179], v[210:213], v[18:21]
	v_mfma_f32_16x16x32_bf16 v[10:13], v[186:189], v[210:213], v[10:13]
	v_mfma_f32_16x16x32_bf16 v[6:9], v[176:179], v[218:221], v[6:9]
	v_mfma_f32_16x16x32_bf16 v[2:5], v[186:189], v[218:221], v[2:5]
	s_setprio 0
	s_barrier
; #define PG8_STAGE(bufoff, gbase, voff) do { _Pragma("unroll") for (int _i = 0; _i < 2; ++_i) \
;         __builtin_amdgcn_global_load_lds((const unsigned*)((const char*)(gbase) + (voff)[_i]), (PG8_LAS unsigned*)(lds + (bufoff) + ldsw + _i * 8192), 16, 0, 0); } while (0)
; #define PG8_LDA(dst, b, h) do { _Pragma("unroll") for (int m = 0; m < 4; ++m) _Pragma("unroll") for (int k = 0; k < 2; ++k) dst[m][k] = *(const PG8_LAS bf16x8*)(lds + PG8_SA(b, h) + aoff + m * 2048 + k * 1024); } while (0)
; #define PG8_LDB(dst, b, h) do { _Pragma("unroll") for (int n = 0; n < 2; ++n) _Pragma("unroll") for (int k = 0; k < 2; ++k) dst[n][k] = *(const PG8_LAS bf16x8*)(lds + PG8_SB(b, h) + boff + n * 2048 + k * 1024); } while (0)
; #define PG8_MMA(ai, bj, At, Bt) do { __builtin_amdgcn_s_setprio(1); _Pragma("unroll") for (int m = 0; m < 4; ++m) _Pragma("unroll") for (int n = 0; n < 2; ++n) _Pragma("unroll") for (int k = 0; k < 2; ++k) \
;         acc[ai][bj][m][n] = __builtin_amdgcn_mfma_f32_16x16x32_bf16(Bt[n][k], At[m][k], acc[ai][bj][m][n], 0, 0, 0); __builtin_amdgcn_s_setprio(0); } while (0)
; #define PG8_WAIT_V(n) asm volatile("s_waitcnt vmcnt(" #n ")" ::: "memory")
; #define PG8_WAIT_L(n) asm volatile("s_waitcnt lgkmcnt(" #n ")" ::: "memory")
; #define PG8_BAR __builtin_amdgcn_s_barrier()
; #define PG8_SCHED __builtin_amdgcn_sched_barrier(0)
; template <class Epi, class Sched, bool ALIGN_EPI = false, bool SP2 = false>
; __device__ __forceinline__ void gemm_phase(PG8_LAS unsigned char* lds, const Gemm g, const Sched& S, const Epi& E) {
;     ...
;             PG8_LDB(B0, 1, 0); PG8_LDB(B1, 1, 1); PG8_SCHED; PG8_LDA(At, 1, 0); PG8_STAGE(PG8_SA(0, 1), a2 + hstep, voffA);
;             PG8_WAIT_V(8); PG8_WAIT_L(0); PG8_BAR; PG8_MMA(0, 0, At, B0); PG8_MMA(0, 1, At, B1); PG8_BAR; PG8_SCHED;
	s_add_i32 s69, 0, 0x18000
	s_add_i32 s70, 0, 0x1c000
	v_add_u32_e32 v168, s69, v151
	v_add_u32_e32 v186, s70, v151
	ds_read_b128 v[156:159], v168
	ds_read_b128 v[160:163], v168 offset:1024
	ds_read_b128 v[164:167], v168 offset:2048
	ds_read_b128 v[168:171], v168 offset:3072
	ds_read_b128 v[172:175], v186
	ds_read_b128 v[176:179], v186 offset:1024
	ds_read_b128 v[182:185], v186 offset:2048
	ds_read_b128 v[186:189], v186 offset:3072
	s_add_u32 s30, s30, 0x40000
	s_addc_u32 s31, s31, 0
	s_mov_b32 m0, s37
	ds_read_b128 v[190:193], v155 offset:32768
	ds_read_b128 v[194:197], v155 offset:33792
	ds_read_b128 v[198:201], v155 offset:34816
	ds_read_b128 v[202:205], v155 offset:35840
	ds_read_b128 v[206:209], v155 offset:36864
	ds_read_b128 v[210:213], v155 offset:37888
	ds_read_b128 v[214:217], v155 offset:38912
	ds_read_b128 v[218:221], v155 offset:39936
	global_load_lds_dwordx4 v132, s[30:31]
	v_lshl_add_u64 v[228:229], s[30:31], 0, v[136:137]
	s_mov_b32 m0, s38
	s_nop 0
	global_load_lds_dwordx4 v136, s[30:31]
	s_waitcnt vmcnt(8)
	s_waitcnt lgkmcnt(0)
	s_barrier
	s_setprio 1
	s_waitcnt lgkmcnt(0)
	v_mfma_f32_16x16x32_bf16 v[126:129], v[156:159], v[190:193], v[126:129]
	v_mfma_f32_16x16x32_bf16 v[122:125], v[164:167], v[190:193], v[122:125]
	v_mfma_f32_16x16x32_bf16 v[118:121], v[156:159], v[198:201], v[118:121]
	v_mfma_f32_16x16x32_bf16 v[110:113], v[164:167], v[198:201], v[110:113]
	v_mfma_f32_16x16x32_bf16 v[102:105], v[156:159], v[206:209], v[102:105]
	v_mfma_f32_16x16x32_bf16 v[94:97], v[164:167], v[206:209], v[94:97]
	v_mfma_f32_16x16x32_bf16 v[86:89], v[156:159], v[214:217], v[86:89]
	v_mfma_f32_16x16x32_bf16 v[78:81], v[164:167], v[214:217], v[78:81]
	v_mfma_f32_16x16x32_bf16 v[126:129], v[160:163], v[194:197], v[126:129]
	v_mfma_f32_16x16x32_bf16 v[122:125], v[168:171], v[194:197], v[122:125]
	v_mfma_f32_16x16x32_bf16 v[118:121], v[160:163], v[202:205], v[118:121]
	v_mfma_f32_16x16x32_bf16 v[110:113], v[168:171], v[202:205], v[110:113]
	v_mfma_f32_16x16x32_bf16 v[102:105], v[160:163], v[210:213], v[102:105]
	v_mfma_f32_16x16x32_bf16 v[94:97], v[168:171], v[210:213], v[94:97]
	v_mfma_f32_16x16x32_bf16 v[86:89], v[160:163], v[218:221], v[86:89]
	v_mfma_f32_16x16x32_bf16 v[78:81], v[168:171], v[218:221], v[78:81]
	s_setprio 0
	s_setprio 1
	v_mfma_f32_16x16x32_bf16 v[114:117], v[172:175], v[190:193], v[114:117]
	v_mfma_f32_16x16x32_bf16 v[106:109], v[182:185], v[190:193], v[106:109]
	v_mfma_f32_16x16x32_bf16 v[98:101], v[172:175], v[198:201], v[98:101]
	v_mfma_f32_16x16x32_bf16 v[90:93], v[182:185], v[198:201], v[90:93]
	v_mfma_f32_16x16x32_bf16 v[82:85], v[172:175], v[206:209], v[82:85]
	v_mfma_f32_16x16x32_bf16 v[74:77], v[182:185], v[206:209], v[74:77]
	v_mfma_f32_16x16x32_bf16 v[70:73], v[172:175], v[214:217], v[70:73]
	v_mfma_f32_16x16x32_bf16 v[66:69], v[182:185], v[214:217], v[66:69]
	v_mfma_f32_16x16x32_bf16 v[114:117], v[176:179], v[194:197], v[114:117]
	v_mfma_f32_16x16x32_bf16 v[106:109], v[186:189], v[194:197], v[106:109]
	v_mfma_f32_16x16x32_bf16 v[98:101], v[176:179], v[202:205], v[98:101]
	v_mfma_f32_16x16x32_bf16 v[90:93], v[186:189], v[202:205], v[90:93]
	v_mfma_f32_16x16x32_bf16 v[82:85], v[176:179], v[210:213], v[82:85]
	v_mfma_f32_16x16x32_bf16 v[74:77], v[186:189], v[210:213], v[74:77]
	v_mfma_f32_16x16x32_bf16 v[70:73], v[176:179], v[218:221], v[70:73]
	v_mfma_f32_16x16x32_bf16 v[66:69], v[186:189], v[218:221], v[66:69]
	s_setprio 0
	s_barrier
; #define PG8_STAGE(bufoff, gbase, voff) do { _Pragma("unroll") for (int _i = 0; _i < 2; ++_i) \
;         __builtin_amdgcn_global_load_lds((const unsigned*)((const char*)(gbase) + (voff)[_i]), (PG8_LAS unsigned*)(lds + (bufoff) + ldsw + _i * 8192), 16, 0, 0); } while (0)
; #define PG8_LDA(dst, b, h) do { _Pragma("unroll") for (int m = 0; m < 4; ++m) _Pragma("unroll") for (int k = 0; k < 2; ++k) dst[m][k] = *(const PG8_LAS bf16x8*)(lds + PG8_SA(b, h) + aoff + m * 2048 + k * 1024); } while (0)
; #define PG8_MMA(ai, bj, At, Bt) do { __builtin_amdgcn_s_setprio(1); _Pragma("unroll") for (int m = 0; m < 4; ++m) _Pragma("unroll") for (int n = 0; n < 2; ++n) _Pragma("unroll") for (int k = 0; k < 2; ++k) \
;         acc[ai][bj][m][n] = __builtin_amdgcn_mfma_f32_16x16x32_bf16(Bt[n][k], At[m][k], acc[ai][bj][m][n], 0, 0, 0); __builtin_amdgcn_s_setprio(0); } while (0)
; #define PG8_WAIT_V(n) asm volatile("s_waitcnt vmcnt(" #n ")" ::: "memory")
; #define PG8_WAIT_L(n) asm volatile("s_waitcnt lgkmcnt(" #n ")" ::: "memory")
; #define PG8_BAR __builtin_amdgcn_s_barrier()
; #define PG8_SCHED __builtin_amdgcn_sched_barrier(0)
; template <class Epi, class Sched, bool ALIGN_EPI = false, bool SP2 = false>
; __device__ __forceinline__ void gemm_phase(PG8_LAS unsigned char* lds, const Gemm g, const Sched& S, const Epi& E) {
;     ...
;         for (int t = 0; t < nt; t += 2) {
;     ...
;             PG8_LDA(At, 1, 1); PG8_STAGE(PG8_SB(1, 0), b3, voffB); PG8_STAGE(PG8_SB(1, 1), b3 + hstep, voffB); PG8_STAGE(PG8_SA(1, 0), a3, voffA);
;             PG8_WAIT_V(8); PG8_WAIT_L(0); PG8_BAR; PG8_MMA(1, 0, At, B0); PG8_MMA(1, 1, At, B1); PG8_BAR; PG8_SCHED;
	s_add_i32 s30, s69, s35
	s_mov_b32 m0, s30
	ds_read_b128 v[190:193], v155 offset:49152
	ds_read_b128 v[194:197], v155 offset:50176
	ds_read_b128 v[198:201], v155 offset:51200
	ds_read_b128 v[202:205], v155 offset:52224
	ds_read_b128 v[206:209], v155 offset:53248
	ds_read_b128 v[210:213], v155 offset:54272
	ds_read_b128 v[214:217], v155 offset:55296
	ds_read_b128 v[218:221], v155 offset:56320
	s_add_u32 s98, s28, s8
	s_addc_u32 s99, s29, s9
	global_load_lds_dwordx4 v134, s[98:99]
	s_add_i32 m0, s30, 0x2000
	s_add_u32 s28, s28, 0x40080
	v_lshl_add_u64 v[148:149], v[222:223], 0, s[8:9]
	s_addc_u32 s29, s29, 0
	s_add_i32 s30, s70, s35
	global_load_lds_dwordx4 v[148:149], off
	s_mov_b32 m0, s30
	s_nop 0
	global_load_lds_dwordx4 v134, s[28:29]
	s_add_i32 m0, s30, 0x2000
	s_nop 0
	global_load_lds_dwordx4 v138, s[28:29]
	v_lshl_add_u64 v[148:149], v[224:225], 0, s[8:9]
	s_mov_b32 m0, s40
	s_nop 0
	global_load_lds_dwordx4 v[148:149], off
	v_lshl_add_u64 v[148:149], v[226:227], 0, s[8:9]
	s_mov_b32 m0, s41
	s_nop 0
	global_load_lds_dwordx4 v[148:149], off
	s_waitcnt vmcnt(8)
	s_waitcnt lgkmcnt(0)
	s_barrier
	s_setprio 1
	s_waitcnt lgkmcnt(0)
	v_mfma_f32_16x16x32_bf16 v[62:65], v[156:159], v[190:193], v[62:65]
	v_mfma_f32_16x16x32_bf16 v[58:61], v[164:167], v[190:193], v[58:61]
	v_mfma_f32_16x16x32_bf16 v[54:57], v[156:159], v[198:201], v[54:57]
	v_mfma_f32_16x16x32_bf16 v[46:49], v[164:167], v[198:201], v[46:49]
	v_mfma_f32_16x16x32_bf16 v[38:41], v[156:159], v[206:209], v[38:41]
	v_mfma_f32_16x16x32_bf16 v[30:33], v[164:167], v[206:209], v[30:33]
	v_mfma_f32_16x16x32_bf16 v[22:25], v[156:159], v[214:217], v[22:25]
	v_mfma_f32_16x16x32_bf16 v[14:17], v[164:167], v[214:217], v[14:17]
	v_mfma_f32_16x16x32_bf16 v[62:65], v[160:163], v[194:197], v[62:65]
	v_mfma_f32_16x16x32_bf16 v[58:61], v[168:171], v[194:197], v[58:61]
	v_mfma_f32_16x16x32_bf16 v[54:57], v[160:163], v[202:205], v[54:57]
	v_mfma_f32_16x16x32_bf16 v[46:49], v[168:171], v[202:205], v[46:49]
	v_mfma_f32_16x16x32_bf16 v[38:41], v[160:163], v[210:213], v[38:41]
	v_mfma_f32_16x16x32_bf16 v[30:33], v[168:171], v[210:213], v[30:33]
	v_mfma_f32_16x16x32_bf16 v[22:25], v[160:163], v[218:221], v[22:25]
	v_mfma_f32_16x16x32_bf16 v[14:17], v[168:171], v[218:221], v[14:17]
	s_setprio 0
	s_setprio 1
	v_mfma_f32_16x16x32_bf16 v[50:53], v[172:175], v[190:193], v[50:53]
	v_mfma_f32_16x16x32_bf16 v[42:45], v[182:185], v[190:193], v[42:45]
	v_mfma_f32_16x16x32_bf16 v[34:37], v[172:175], v[198:201], v[34:37]
	v_mfma_f32_16x16x32_bf16 v[26:29], v[182:185], v[198:201], v[26:29]
	v_mfma_f32_16x16x32_bf16 v[18:21], v[172:175], v[206:209], v[18:21]
	v_mfma_f32_16x16x32_bf16 v[10:13], v[182:185], v[206:209], v[10:13]
	v_mfma_f32_16x16x32_bf16 v[6:9], v[172:175], v[214:217], v[6:9]
	v_mfma_f32_16x16x32_bf16 v[2:5], v[182:185], v[214:217], v[2:5]
	v_mfma_f32_16x16x32_bf16 v[50:53], v[176:179], v[194:197], v[50:53]
	v_mfma_f32_16x16x32_bf16 v[42:45], v[186:189], v[194:197], v[42:45]
	v_mfma_f32_16x16x32_bf16 v[34:37], v[176:179], v[202:205], v[34:37]
	v_mfma_f32_16x16x32_bf16 v[26:29], v[186:189], v[202:205], v[26:29]
	v_mfma_f32_16x16x32_bf16 v[18:21], v[176:179], v[210:213], v[18:21]
	v_mfma_f32_16x16x32_bf16 v[10:13], v[186:189], v[210:213], v[10:13]
	v_mfma_f32_16x16x32_bf16 v[6:9], v[176:179], v[218:221], v[6:9]
	v_mfma_f32_16x16x32_bf16 v[2:5], v[186:189], v[218:221], v[2:5]
	s_setprio 0
	s_barrier
	s_add_i32 s68, s68, 2
	s_add_u32 s26, s26, 0x100
	s_addc_u32 s27, s27, 0
	s_add_u32 s66, s66, 0x100
	s_addc_u32 s67, s67, 0
	s_cmp_gt_u32 s68, 13
	s_cbranch_scc0 .LBB0_553
	s_and_b64 vcc, exec, s[10:11]
	s_cbranch_vccz .LBB0_556
	s_barrier

; #define PG8_STAGE(bufoff, gbase, voff) do { _Pragma("unroll") for (int _i = 0; _i < 2; ++_i) \
;         __builtin_amdgcn_global_load_lds((const unsigned*)((const char*)(gbase) + (voff)[_i]), (PG8_LAS unsigned*)(lds + (bufoff) + ldsw + _i * 8192), 16, 0, 0); } while (0)
; #define PG8_LDA(dst, b, h) do { _Pragma("unroll") for (int m = 0; m < 4; ++m) _Pragma("unroll") for (int k = 0; k < 2; ++k) dst[m][k] = *(const PG8_LAS bf16x8*)(lds + PG8_SA(b, h) + aoff + m * 2048 + k * 1024); } while (0)
; #define PG8_LDB(dst, b, h) do { _Pragma("unroll") for (int n = 0; n < 2; ++n) _Pragma("unroll") for (int k = 0; k < 2; ++k) dst[n][k] = *(const PG8_LAS bf16x8*)(lds + PG8_SB(b, h) + boff + n * 2048 + k * 1024); } while (0)
; #define PG8_MMA(ai, bj, At, Bt) do { __builtin_amdgcn_s_setprio(1); _Pragma("unroll") for (int m = 0; m < 4; ++m) _Pragma("unroll") for (int n = 0; n < 2; ++n) _Pragma("unroll") for (int k = 0; k < 2; ++k) \
;         acc[ai][bj][m][n] = __builtin_amdgcn_mfma_f32_16x16x32_bf16(Bt[n][k], At[m][k], acc[ai][bj][m][n], 0, 0, 0); __builtin_amdgcn_s_setprio(0); } while (0)
; #define PG8_WAIT_V(n) asm volatile("s_waitcnt vmcnt(" #n ")" ::: "memory")
; #define PG8_WAIT_L(n) asm volatile("s_waitcnt lgkmcnt(" #n ")" ::: "memory")
; template <class Epi, class Sched, bool ALIGN_EPI = false, bool SP2 = false>
; __device__ __forceinline__ void gemm_phase(PG8_LAS unsigned char* lds, const Gemm g, const Sched& S, const Epi& E) {
;     ...
;             const bool last = (t == nt - 2);
;             const char* a1 = cA + (size_t)(t + 1) * kstep;
;             const char* a2 = last ? nA : cA + (size_t)(t + 2) * kstep; const char* b2 = last ? nB : cB + (size_t)(t + 2) * kstep;
;             const char* a3 = a2 + kstep; const char* b3 = b2 + kstep;
;             if (last && has_next) S.a_ready(nxt);
;             if constexpr (SP2) {
;             PG8_LDB(B0, 0, 0); PG8_LDB(B1, 0, 1); PG8_SCHED; PG8_LDA(At, 0, 0); PG8_STAGE(PG8_SA(1, 1), a1 + hstep, voffA);
;             PG8_WAIT_V(8); PG8_WAIT_L(0); PG8_BAR; PG8_MMA(0, 0, At, B0); PG8_MMA(0, 1, At, B1); PG8_BAR; PG8_SCHED;
;             PG8_LDA(At, 0, 1); PG8_STAGE(PG8_SB(0, 0), b2, voffB); PG8_STAGE(PG8_SB(0, 1), b2 + hstep, voffB); PG8_STAGE(PG8_SA(0, 0), a2, voffA);
;             PG8_WAIT_V(8); PG8_WAIT_L(0); PG8_BAR; PG8_MMA(1, 0, At, B0); PG8_MMA(1, 1, At, B1); PG8_BAR; PG8_SCHED;
.LBB0_696:
	ds_read_b128 v[152:155], v146
	ds_read_b128 v[156:159], v146 offset:1024
	ds_read_b128 v[160:163], v146 offset:2048
	ds_read_b128 v[164:167], v146 offset:3072
	ds_read_b128 v[168:171], v147
	ds_read_b128 v[172:175], v147 offset:1024
	ds_read_b128 v[176:179], v147 offset:2048
	ds_read_b128 v[182:185], v147 offset:3072
	s_add_u32 s16, s14, 0xe79c0080
	s_addc_u32 s17, s15, -1
	s_cmp_lg_u32 s28, 12
	s_cselect_b32 s16, s16, 0
	s_cselect_b32 s17, s17, 0
	s_add_u32 s18, s10, s16
	s_addc_u32 s19, s11, s17
	s_add_u32 s16, s8, s16
	s_addc_u32 s17, s9, s17
	s_mov_b32 m0, s29
	v_lshl_add_u64 v[218:219], v[140:141], 0, s[14:15]
	ds_read_b128 v[186:189], v148
	ds_read_b128 v[190:193], v148 offset:1024
	ds_read_b128 v[194:197], v148 offset:2048
	ds_read_b128 v[198:201], v148 offset:3072
	ds_read_b128 v[202:205], v148 offset:4096
	ds_read_b128 v[206:209], v148 offset:5120
	ds_read_b128 v[210:213], v148 offset:6144
	ds_read_b128 v[214:217], v148 offset:7168
	global_load_lds_dwordx4 v[218:219], off
	v_lshl_add_u64 v[218:219], v[142:143], 0, s[14:15]
	s_mov_b32 m0, s30
	s_nop 0
	global_load_lds_dwordx4 v[218:219], off
	s_waitcnt vmcnt(8)
	s_waitcnt lgkmcnt(0)
	s_barrier
	s_setprio 1
	s_waitcnt lgkmcnt(0)
	v_mfma_f32_16x16x32_bf16 v[126:129], v[152:155], v[186:189], v[126:129]
	v_mfma_f32_16x16x32_bf16 v[122:125], v[160:163], v[186:189], v[122:125]
	v_mfma_f32_16x16x32_bf16 v[118:121], v[152:155], v[194:197], v[118:121]
	v_mfma_f32_16x16x32_bf16 v[110:113], v[160:163], v[194:197], v[110:113]
	v_mfma_f32_16x16x32_bf16 v[102:105], v[152:155], v[202:205], v[102:105]
	v_mfma_f32_16x16x32_bf16 v[94:97], v[160:163], v[202:205], v[94:97]
	v_mfma_f32_16x16x32_bf16 v[86:89], v[152:155], v[210:213], v[86:89]
	v_mfma_f32_16x16x32_bf16 v[78:81], v[160:163], v[210:213], v[78:81]
	v_mfma_f32_16x16x32_bf16 v[126:129], v[156:159], v[190:193], v[126:129]
	v_mfma_f32_16x16x32_bf16 v[122:125], v[164:167], v[190:193], v[122:125]
	v_mfma_f32_16x16x32_bf16 v[118:121], v[156:159], v[198:201], v[118:121]
	v_mfma_f32_16x16x32_bf16 v[110:113], v[164:167], v[198:201], v[110:113]
	v_mfma_f32_16x16x32_bf16 v[102:105], v[156:159], v[206:209], v[102:105]
	v_mfma_f32_16x16x32_bf16 v[94:97], v[164:167], v[206:209], v[94:97]
	v_mfma_f32_16x16x32_bf16 v[86:89], v[156:159], v[214:217], v[86:89]
	v_mfma_f32_16x16x32_bf16 v[78:81], v[164:167], v[214:217], v[78:81]
	s_setprio 0
	s_setprio 1
	v_mfma_f32_16x16x32_bf16 v[114:117], v[168:171], v[186:189], v[114:117]
	v_mfma_f32_16x16x32_bf16 v[106:109], v[176:179], v[186:189], v[106:109]
	v_mfma_f32_16x16x32_bf16 v[98:101], v[168:171], v[194:197], v[98:101]
	v_mfma_f32_16x16x32_bf16 v[90:93], v[176:179], v[194:197], v[90:93]
	v_mfma_f32_16x16x32_bf16 v[82:85], v[168:171], v[202:205], v[82:85]
	v_mfma_f32_16x16x32_bf16 v[74:77], v[176:179], v[202:205], v[74:77]
	v_mfma_f32_16x16x32_bf16 v[70:73], v[168:171], v[210:213], v[70:73]
	v_mfma_f32_16x16x32_bf16 v[66:69], v[176:179], v[210:213], v[66:69]
	v_mfma_f32_16x16x32_bf16 v[114:117], v[172:175], v[190:193], v[114:117]
	v_mfma_f32_16x16x32_bf16 v[106:109], v[182:185], v[190:193], v[106:109]
	v_mfma_f32_16x16x32_bf16 v[98:101], v[172:175], v[198:201], v[98:101]
	v_mfma_f32_16x16x32_bf16 v[90:93], v[182:185], v[198:201], v[90:93]
	v_mfma_f32_16x16x32_bf16 v[82:85], v[172:175], v[206:209], v[82:85]
	v_mfma_f32_16x16x32_bf16 v[74:77], v[182:185], v[206:209], v[74:77]
	v_mfma_f32_16x16x32_bf16 v[70:73], v[172:175], v[214:217], v[70:73]
	v_mfma_f32_16x16x32_bf16 v[66:69], v[182:185], v[214:217], v[66:69]
	s_setprio 0
	s_barrier
	s_mov_b32 m0, s31
	v_lshl_add_u64 v[218:219], s[16:17], 0, v[136:137]
	s_add_u32 s42, s16, 0x40000
	ds_read_b128 v[186:189], v148 offset:16384
	ds_read_b128 v[190:193], v148 offset:17408
	ds_read_b128 v[194:197], v148 offset:18432
	ds_read_b128 v[198:201], v148 offset:19456
	ds_read_b128 v[202:205], v148 offset:20480
	ds_read_b128 v[206:209], v148 offset:21504
	ds_read_b128 v[210:213], v148 offset:22528
	ds_read_b128 v[214:217], v148 offset:23552
	global_load_lds_dwordx4 v136, s[16:17]
	v_lshl_add_u64 v[220:221], s[16:17], 0, v[132:133]
	s_mov_b32 m0, s34
	s_addc_u32 s43, s17, 0
	global_load_lds_dwordx4 v132, s[16:17]
	s_mov_b32 m0, s35
	v_lshl_add_u64 v[224:225], s[18:19], 0, v[134:135]
	global_load_lds_dwordx4 v136, s[42:43]
	s_mov_b32 m0, s36
	s_nop 0
	global_load_lds_dwordx4 v132, s[42:43]
	v_lshl_add_u64 v[222:223], s[18:19], 0, v[138:139]
	s_mov_b32 m0, s5
	s_nop 0
	global_load_lds_dwordx4 v138, s[18:19]
	s_mov_b32 m0, s22
	s_nop 0
	global_load_lds_dwordx4 v134, s[18:19]
	s_waitcnt vmcnt(8)
	s_waitcnt lgkmcnt(0)
	s_barrier
; #define PG8_STAGE(bufoff, gbase, voff) do { _Pragma("unroll") for (int _i = 0; _i < 2; ++_i) \
;         __builtin_amdgcn_global_load_lds((const unsigned*)((const char*)(gbase) + (voff)[_i]), (PG8_LAS unsigned*)(lds + (bufoff) + ldsw + _i * 8192), 16, 0, 0); } while (0)
; #define PG8_LDA(dst, b, h) do { _Pragma("unroll") for (int m = 0; m < 4; ++m) _Pragma("unroll") for (int k = 0; k < 2; ++k) dst[m][k] = *(const PG8_LAS bf16x8*)(lds + PG8_SA(b, h) + aoff + m * 2048 + k * 1024); } while (0)
; #define PG8_LDB(dst, b, h) do { _Pragma("unroll") for (int n = 0; n < 2; ++n) _Pragma("unroll") for (int k = 0; k < 2; ++k) dst[n][k] = *(const PG8_LAS bf16x8*)(lds + PG8_SB(b, h) + boff + n * 2048 + k * 1024); } while (0)
; #define PG8_MMA(ai, bj, At, Bt) do { __builtin_amdgcn_s_setprio(1); _Pragma("unroll") for (int m = 0; m < 4; ++m) _Pragma("unroll") for (int n = 0; n < 2; ++n) _Pragma("unroll") for (int k = 0; k < 2; ++k) \
;         acc[ai][bj][m][n] = __builtin_amdgcn_mfma_f32_16x16x32_bf16(Bt[n][k], At[m][k], acc[ai][bj][m][n], 0, 0, 0); __builtin_amdgcn_s_setprio(0); } while (0)
; #define PG8_WAIT_V(n) asm volatile("s_waitcnt vmcnt(" #n ")" ::: "memory")
; #define PG8_WAIT_L(n) asm volatile("s_waitcnt lgkmcnt(" #n ")" ::: "memory")
; #define PG8_BAR __builtin_amdgcn_s_barrier()
; #define PG8_SCHED __builtin_amdgcn_sched_barrier(0)
; template <class Epi, class Sched, bool ALIGN_EPI = false, bool SP2 = false>
; __device__ __forceinline__ void gemm_phase(PG8_LAS unsigned char* lds, const Gemm g, const Sched& S, const Epi& E) {
;     ...
;             PG8_WAIT_V(8); PG8_WAIT_L(0); PG8_BAR; PG8_MMA(1, 0, At, B0); PG8_MMA(1, 1, At, B1); PG8_BAR; PG8_SCHED;
;             PG8_LDB(B0, 1, 0); PG8_LDB(B1, 1, 1); PG8_SCHED; PG8_LDA(At, 1, 0); PG8_STAGE(PG8_SA(0, 1), a2 + hstep, voffA);
;             PG8_WAIT_V(8); PG8_WAIT_L(0); PG8_BAR; PG8_MMA(0, 0, At, B0); PG8_MMA(0, 1, At, B1); PG8_BAR; PG8_SCHED;
	s_setprio 1
	s_waitcnt lgkmcnt(0)
	v_mfma_f32_16x16x32_bf16 v[62:65], v[152:155], v[186:189], v[62:65]
	v_mfma_f32_16x16x32_bf16 v[58:61], v[160:163], v[186:189], v[58:61]
	v_mfma_f32_16x16x32_bf16 v[54:57], v[152:155], v[194:197], v[54:57]
	v_mfma_f32_16x16x32_bf16 v[46:49], v[160:163], v[194:197], v[46:49]
	v_mfma_f32_16x16x32_bf16 v[38:41], v[152:155], v[202:205], v[38:41]
	v_mfma_f32_16x16x32_bf16 v[30:33], v[160:163], v[202:205], v[30:33]
	v_mfma_f32_16x16x32_bf16 v[22:25], v[152:155], v[210:213], v[22:25]
	v_mfma_f32_16x16x32_bf16 v[14:17], v[160:163], v[210:213], v[14:17]
	v_mfma_f32_16x16x32_bf16 v[62:65], v[156:159], v[190:193], v[62:65]
	v_mfma_f32_16x16x32_bf16 v[58:61], v[164:167], v[190:193], v[58:61]
	v_mfma_f32_16x16x32_bf16 v[54:57], v[156:159], v[198:201], v[54:57]
	v_mfma_f32_16x16x32_bf16 v[46:49], v[164:167], v[198:201], v[46:49]
	v_mfma_f32_16x16x32_bf16 v[38:41], v[156:159], v[206:209], v[38:41]
	v_mfma_f32_16x16x32_bf16 v[30:33], v[164:167], v[206:209], v[30:33]
	v_mfma_f32_16x16x32_bf16 v[22:25], v[156:159], v[214:217], v[22:25]
	v_mfma_f32_16x16x32_bf16 v[14:17], v[164:167], v[214:217], v[14:17]
	s_setprio 0
	s_setprio 1
	v_mfma_f32_16x16x32_bf16 v[50:53], v[168:171], v[186:189], v[50:53]
	v_mfma_f32_16x16x32_bf16 v[42:45], v[176:179], v[186:189], v[42:45]
	v_mfma_f32_16x16x32_bf16 v[34:37], v[168:171], v[194:197], v[34:37]
	v_mfma_f32_16x16x32_bf16 v[26:29], v[176:179], v[194:197], v[26:29]
	v_mfma_f32_16x16x32_bf16 v[18:21], v[168:171], v[202:205], v[18:21]
	v_mfma_f32_16x16x32_bf16 v[10:13], v[176:179], v[202:205], v[10:13]
	v_mfma_f32_16x16x32_bf16 v[6:9], v[168:171], v[210:213], v[6:9]
	v_mfma_f32_16x16x32_bf16 v[2:5], v[176:179], v[210:213], v[2:5]
	v_mfma_f32_16x16x32_bf16 v[50:53], v[172:175], v[190:193], v[50:53]
	v_mfma_f32_16x16x32_bf16 v[42:45], v[182:185], v[190:193], v[42:45]
	v_mfma_f32_16x16x32_bf16 v[34:37], v[172:175], v[198:201], v[34:37]
	v_mfma_f32_16x16x32_bf16 v[26:29], v[182:185], v[198:201], v[26:29]
	v_mfma_f32_16x16x32_bf16 v[18:21], v[172:175], v[206:209], v[18:21]
	v_mfma_f32_16x16x32_bf16 v[10:13], v[182:185], v[206:209], v[10:13]
	v_mfma_f32_16x16x32_bf16 v[6:9], v[172:175], v[214:217], v[6:9]
	v_mfma_f32_16x16x32_bf16 v[2:5], v[182:185], v[214:217], v[2:5]
	s_setprio 0
	s_barrier
	ds_read_b128 v[152:155], v149
	ds_read_b128 v[156:159], v149 offset:1024
	ds_read_b128 v[160:163], v149 offset:2048
	ds_read_b128 v[164:167], v149 offset:3072
	ds_read_b128 v[168:171], v150
	ds_read_b128 v[172:175], v150 offset:1024
	ds_read_b128 v[176:179], v150 offset:2048
	ds_read_b128 v[182:185], v150 offset:3072
	s_add_u32 s18, s18, 0x40000
	s_addc_u32 s19, s19, 0
	s_mov_b32 m0, s23
	ds_read_b128 v[186:189], v148 offset:32768
	ds_read_b128 v[190:193], v148 offset:33792
	ds_read_b128 v[194:197], v148 offset:34816
	ds_read_b128 v[198:201], v148 offset:35840
	ds_read_b128 v[202:205], v148 offset:36864
	ds_read_b128 v[206:209], v148 offset:37888
	ds_read_b128 v[210:213], v148 offset:38912
	ds_read_b128 v[214:217], v148 offset:39936
	global_load_lds_dwordx4 v138, s[18:19]
	v_lshl_add_u64 v[226:227], s[18:19], 0, v[134:135]
	s_mov_b32 m0, s24
	s_nop 0
	global_load_lds_dwordx4 v134, s[18:19]
	s_waitcnt vmcnt(8)
	s_waitcnt lgkmcnt(0)
	s_barrier
	s_setprio 1
	s_waitcnt lgkmcnt(0)
	v_mfma_f32_16x16x32_bf16 v[126:129], v[152:155], v[186:189], v[126:129]
	v_mfma_f32_16x16x32_bf16 v[122:125], v[160:163], v[186:189], v[122:125]
	v_mfma_f32_16x16x32_bf16 v[118:121], v[152:155], v[194:197], v[118:121]
	v_mfma_f32_16x16x32_bf16 v[110:113], v[160:163], v[194:197], v[110:113]
	v_mfma_f32_16x16x32_bf16 v[102:105], v[152:155], v[202:205], v[102:105]
	v_mfma_f32_16x16x32_bf16 v[94:97], v[160:163], v[202:205], v[94:97]
	v_mfma_f32_16x16x32_bf16 v[86:89], v[152:155], v[210:213], v[86:89]
	v_mfma_f32_16x16x32_bf16 v[78:81], v[160:163], v[210:213], v[78:81]
	v_mfma_f32_16x16x32_bf16 v[126:129], v[156:159], v[190:193], v[126:129]
	v_mfma_f32_16x16x32_bf16 v[122:125], v[164:167], v[190:193], v[122:125]
	v_mfma_f32_16x16x32_bf16 v[118:121], v[156:159], v[198:201], v[118:121]
	v_mfma_f32_16x16x32_bf16 v[110:113], v[164:167], v[198:201], v[110:113]
	v_mfma_f32_16x16x32_bf16 v[102:105], v[156:159], v[206:209], v[102:105]
	v_mfma_f32_16x16x32_bf16 v[94:97], v[164:167], v[206:209], v[94:97]
	v_mfma_f32_16x16x32_bf16 v[86:89], v[156:159], v[214:217], v[86:89]
	v_mfma_f32_16x16x32_bf16 v[78:81], v[164:167], v[214:217], v[78:81]
	s_setprio 0
	s_setprio 1
	v_mfma_f32_16x16x32_bf16 v[114:117], v[168:171], v[186:189], v[114:117]
	v_mfma_f32_16x16x32_bf16 v[106:109], v[176:179], v[186:189], v[106:109]
	v_mfma_f32_16x16x32_bf16 v[98:101], v[168:171], v[194:197], v[98:101]
	v_mfma_f32_16x16x32_bf16 v[90:93], v[176:179], v[194:197], v[90:93]
	v_mfma_f32_16x16x32_bf16 v[82:85], v[168:171], v[202:205], v[82:85]
	v_mfma_f32_16x16x32_bf16 v[74:77], v[176:179], v[202:205], v[74:77]
	v_mfma_f32_16x16x32_bf16 v[70:73], v[168:171], v[210:213], v[70:73]
	v_mfma_f32_16x16x32_bf16 v[66:69], v[176:179], v[210:213], v[66:69]
	v_mfma_f32_16x16x32_bf16 v[114:117], v[172:175], v[190:193], v[114:117]
	v_mfma_f32_16x16x32_bf16 v[106:109], v[182:185], v[190:193], v[106:109]
	v_mfma_f32_16x16x32_bf16 v[98:101], v[172:175], v[198:201], v[98:101]
	v_mfma_f32_16x16x32_bf16 v[90:93], v[182:185], v[198:201], v[90:93]
	v_mfma_f32_16x16x32_bf16 v[82:85], v[172:175], v[206:209], v[82:85]
	v_mfma_f32_16x16x32_bf16 v[74:77], v[182:185], v[206:209], v[74:77]
	v_mfma_f32_16x16x32_bf16 v[70:73], v[172:175], v[214:217], v[70:73]
	v_mfma_f32_16x16x32_bf16 v[66:69], v[182:185], v[214:217], v[66:69]
	s_setprio 0
	s_barrier
; #define PG8_STAGE(bufoff, gbase, voff) do { _Pragma("unroll") for (int _i = 0; _i < 2; ++_i) \
;         __builtin_amdgcn_global_load_lds((const unsigned*)((const char*)(gbase) + (voff)[_i]), (PG8_LAS unsigned*)(lds + (bufoff) + ldsw + _i * 8192), 16, 0, 0); } while (0)
; #define PG8_LDA(dst, b, h) do { _Pragma("unroll") for (int m = 0; m < 4; ++m) _Pragma("unroll") for (int k = 0; k < 2; ++k) dst[m][k] = *(const PG8_LAS bf16x8*)(lds + PG8_SA(b, h) + aoff + m * 2048 + k * 1024); } while (0)
; #define PG8_MMA(ai, bj, At, Bt) do { __builtin_amdgcn_s_setprio(1); _Pragma("unroll") for (int m = 0; m < 4; ++m) _Pragma("unroll") for (int n = 0; n < 2; ++n) _Pragma("unroll") for (int k = 0; k < 2; ++k) \
;         acc[ai][bj][m][n] = __builtin_amdgcn_mfma_f32_16x16x32_bf16(Bt[n][k], At[m][k], acc[ai][bj][m][n], 0, 0, 0); __builtin_amdgcn_s_setprio(0); } while (0)
; #define PG8_WAIT_V(n) asm volatile("s_waitcnt vmcnt(" #n ")" ::: "memory")
; #define PG8_WAIT_L(n) asm volatile("s_waitcnt lgkmcnt(" #n ")" ::: "memory")
; #define PG8_BAR __builtin_amdgcn_s_barrier()
; #define PG8_SCHED __builtin_amdgcn_sched_barrier(0)
; template <class Epi, class Sched, bool ALIGN_EPI = false, bool SP2 = false>
; __device__ __forceinline__ void gemm_phase(PG8_LAS unsigned char* lds, const Gemm g, const Sched& S, const Epi& E) {
;     ...
;             PG8_LDA(At, 1, 1); PG8_STAGE(PG8_SB(1, 0), b3, voffB); PG8_STAGE(PG8_SB(1, 1), b3 + hstep, voffB); PG8_STAGE(PG8_SA(1, 0), a3, voffA);
;             PG8_WAIT_V(8); PG8_WAIT_L(0); PG8_BAR; PG8_MMA(1, 0, At, B0); PG8_MMA(1, 1, At, B1); PG8_BAR; PG8_SCHED;
	s_mov_b32 m0, s37
	v_lshl_add_u64 v[218:219], v[218:219], 0, s[12:13]
	s_add_u32 s16, s16, 0x40080
	ds_read_b128 v[186:189], v148 offset:49152
	ds_read_b128 v[190:193], v148 offset:50176
	ds_read_b128 v[194:197], v148 offset:51200
	ds_read_b128 v[198:201], v148 offset:52224
	ds_read_b128 v[202:205], v148 offset:53248
	ds_read_b128 v[206:209], v148 offset:54272
	ds_read_b128 v[210:213], v148 offset:55296
	ds_read_b128 v[214:217], v148 offset:56320
	global_load_lds_dwordx4 v[218:219], off
	v_lshl_add_u64 v[218:219], v[220:221], 0, s[12:13]
	s_mov_b32 m0, s38
	s_addc_u32 s17, s17, 0
	global_load_lds_dwordx4 v[218:219], off
	s_mov_b32 m0, s39
	s_nop 0
	global_load_lds_dwordx4 v136, s[16:17]
	s_mov_b32 m0, s40
	s_nop 0
	global_load_lds_dwordx4 v132, s[16:17]
	v_lshl_add_u64 v[218:219], v[222:223], 0, s[12:13]
	s_mov_b32 m0, s26
	s_nop 0
	global_load_lds_dwordx4 v[218:219], off
	v_lshl_add_u64 v[218:219], v[224:225], 0, s[12:13]
	s_mov_b32 m0, s27
	s_nop 0
	global_load_lds_dwordx4 v[218:219], off
	s_waitcnt vmcnt(8)
	s_waitcnt lgkmcnt(0)
	s_barrier
	s_setprio 1
	s_waitcnt lgkmcnt(0)
	v_mfma_f32_16x16x32_bf16 v[62:65], v[152:155], v[186:189], v[62:65]
	v_mfma_f32_16x16x32_bf16 v[58:61], v[160:163], v[186:189], v[58:61]
	v_mfma_f32_16x16x32_bf16 v[54:57], v[152:155], v[194:197], v[54:57]
	v_mfma_f32_16x16x32_bf16 v[46:49], v[160:163], v[194:197], v[46:49]
	v_mfma_f32_16x16x32_bf16 v[38:41], v[152:155], v[202:205], v[38:41]
	v_mfma_f32_16x16x32_bf16 v[30:33], v[160:163], v[202:205], v[30:33]
	v_mfma_f32_16x16x32_bf16 v[22:25], v[152:155], v[210:213], v[22:25]
	v_mfma_f32_16x16x32_bf16 v[14:17], v[160:163], v[210:213], v[14:17]
	v_mfma_f32_16x16x32_bf16 v[62:65], v[156:159], v[190:193], v[62:65]
	v_mfma_f32_16x16x32_bf16 v[58:61], v[164:167], v[190:193], v[58:61]
	v_mfma_f32_16x16x32_bf16 v[54:57], v[156:159], v[198:201], v[54:57]
	v_mfma_f32_16x16x32_bf16 v[46:49], v[164:167], v[198:201], v[46:49]
	v_mfma_f32_16x16x32_bf16 v[38:41], v[156:159], v[206:209], v[38:41]
	v_mfma_f32_16x16x32_bf16 v[30:33], v[164:167], v[206:209], v[30:33]
	v_mfma_f32_16x16x32_bf16 v[22:25], v[156:159], v[214:217], v[22:25]
	v_mfma_f32_16x16x32_bf16 v[14:17], v[164:167], v[214:217], v[14:17]
	s_setprio 0
	s_setprio 1
	v_mfma_f32_16x16x32_bf16 v[50:53], v[168:171], v[186:189], v[50:53]
	v_mfma_f32_16x16x32_bf16 v[42:45], v[176:179], v[186:189], v[42:45]
	v_mfma_f32_16x16x32_bf16 v[34:37], v[168:171], v[194:197], v[34:37]
	v_mfma_f32_16x16x32_bf16 v[26:29], v[176:179], v[194:197], v[26:29]
	v_mfma_f32_16x16x32_bf16 v[18:21], v[168:171], v[202:205], v[18:21]
	v_mfma_f32_16x16x32_bf16 v[10:13], v[176:179], v[202:205], v[10:13]
	v_mfma_f32_16x16x32_bf16 v[6:9], v[168:171], v[210:213], v[6:9]
	v_mfma_f32_16x16x32_bf16 v[2:5], v[176:179], v[210:213], v[2:5]
	v_mfma_f32_16x16x32_bf16 v[50:53], v[172:175], v[190:193], v[50:53]
	v_mfma_f32_16x16x32_bf16 v[42:45], v[182:185], v[190:193], v[42:45]
	v_mfma_f32_16x16x32_bf16 v[34:37], v[172:175], v[198:201], v[34:37]
	v_mfma_f32_16x16x32_bf16 v[26:29], v[182:185], v[198:201], v[26:29]
	v_mfma_f32_16x16x32_bf16 v[18:21], v[172:175], v[206:209], v[18:21]
	v_mfma_f32_16x16x32_bf16 v[10:13], v[182:185], v[206:209], v[10:13]
	v_mfma_f32_16x16x32_bf16 v[6:9], v[172:175], v[214:217], v[6:9]
	v_mfma_f32_16x16x32_bf16 v[2:5], v[182:185], v[214:217], v[2:5]
	s_setprio 0
	s_barrier
	s_add_i32 s28, s28, 2
	s_add_u32 s14, s14, 0x100
	s_addc_u32 s15, s15, 0
	s_cmp_gt_u32 s28, 13
	s_cbranch_scc0 .LBB0_696
	s_cmpk_lt_u32 s21, 0x100
	s_cbranch_scc0 .LBB0_699
	s_barrier

; #define PG8_STAGE(bufoff, gbase, voff) do { _Pragma("unroll") for (int _i = 0; _i < 2; ++_i) \
;         __builtin_amdgcn_global_load_lds((const unsigned*)((const char*)(gbase) + (voff)[_i]), (PG8_LAS unsigned*)(lds + (bufoff) + ldsw + _i * 8192), 16, 0, 0); } while (0)
; #define PG8_LDA(dst, b, h) do { _Pragma("unroll") for (int m = 0; m < 4; ++m) _Pragma("unroll") for (int k = 0; k < 2; ++k) dst[m][k] = *(const PG8_LAS bf16x8*)(lds + PG8_SA(b, h) + aoff + m * 2048 + k * 1024); } while (0)
; #define PG8_LDB(dst, b, h) do { _Pragma("unroll") for (int n = 0; n < 2; ++n) _Pragma("unroll") for (int k = 0; k < 2; ++k) dst[n][k] = *(const PG8_LAS bf16x8*)(lds + PG8_SB(b, h) + boff + n * 2048 + k * 1024); } while (0)
; #define PG8_MMA(ai, bj, At, Bt) do { __builtin_amdgcn_s_setprio(1); _Pragma("unroll") for (int m = 0; m < 4; ++m) _Pragma("unroll") for (int n = 0; n < 2; ++n) _Pragma("unroll") for (int k = 0; k < 2; ++k) \
;         acc[ai][bj][m][n] = __builtin_amdgcn_mfma_f32_16x16x32_bf16(Bt[n][k], At[m][k], acc[ai][bj][m][n], 0, 0, 0); __builtin_amdgcn_s_setprio(0); } while (0)
; #define PG8_WAIT_V(n) asm volatile("s_waitcnt vmcnt(" #n ")" ::: "memory")
; #define PG8_WAIT_L(n) asm volatile("s_waitcnt lgkmcnt(" #n ")" ::: "memory")
; template <class Epi, class Sched, bool ALIGN_EPI = false, bool SP2 = false>
; __device__ __forceinline__ void gemm_phase(PG8_LAS unsigned char* lds, const Gemm g, const Sched& S, const Epi& E) {
;     ...
;             const bool last = (t == nt - 2);
;             const char* a1 = cA + (size_t)(t + 1) * kstep;
;             const char* a2 = last ? nA : cA + (size_t)(t + 2) * kstep; const char* b2 = last ? nB : cB + (size_t)(t + 2) * kstep;
;             const char* a3 = a2 + kstep; const char* b3 = b2 + kstep;
;             if (last && has_next) S.a_ready(nxt);
;             if constexpr (SP2) {
;             PG8_LDB(B0, 0, 0); PG8_LDB(B1, 0, 1); PG8_SCHED; PG8_LDA(At, 0, 0); PG8_STAGE(PG8_SA(1, 1), a1 + hstep, voffA);
;             PG8_WAIT_V(8); PG8_WAIT_L(0); PG8_BAR; PG8_MMA(0, 0, At, B0); PG8_MMA(0, 1, At, B1); PG8_BAR; PG8_SCHED;
;             PG8_LDA(At, 0, 1); PG8_STAGE(PG8_SB(0, 0), b2, voffB); PG8_STAGE(PG8_SB(0, 1), b2 + hstep, voffB); PG8_STAGE(PG8_SA(0, 0), a2, voffA);
;             PG8_WAIT_V(8); PG8_WAIT_L(0); PG8_BAR; PG8_MMA(1, 0, At, B0); PG8_MMA(1, 1, At, B1); PG8_BAR; PG8_SCHED;
.LBB0_890:
	ds_read_b128 v[148:151], v155
	ds_read_b128 v[158:161], v155 offset:1024
	ds_read_b128 v[162:165], v155 offset:2048
	ds_read_b128 v[166:169], v155 offset:3072
	ds_read_b128 v[170:173], v156
	ds_read_b128 v[174:177], v156 offset:1024
	ds_read_b128 v[182:185], v156 offset:2048
	ds_read_b128 v[186:189], v156 offset:3072
	s_add_u32 s26, s24, 0xfffc0080
	s_addc_u32 s27, s25, -1
	s_cmp_eq_u32 s62, 12
	s_cselect_b32 s29, s17, s27
	s_cselect_b32 s28, s52, s26
	s_cselect_b32 s27, s15, s59
	s_cselect_b32 s26, s53, s58
	s_add_i32 m0, s23, 0xc000
	ds_read_b128 v[190:193], v157
	ds_read_b128 v[194:197], v157 offset:1024
	ds_read_b128 v[198:201], v157 offset:2048
	ds_read_b128 v[202:205], v157 offset:3072
	ds_read_b128 v[206:209], v157 offset:4096
	ds_read_b128 v[210:213], v157 offset:5120
	ds_read_b128 v[214:217], v157 offset:6144
	ds_read_b128 v[218:221], v157 offset:7168
	global_load_lds_dwordx4 v140, s[24:25]
	s_add_i32 m0, s23, 0xe000
	s_nop 0
	global_load_lds_dwordx4 v142, s[24:25]
	s_waitcnt vmcnt(8)
	s_waitcnt lgkmcnt(0)
	s_barrier
	s_setprio 1
	s_waitcnt lgkmcnt(0)
	v_mfma_f32_16x16x32_bf16 v[126:129], v[148:151], v[190:193], v[126:129]
	v_mfma_f32_16x16x32_bf16 v[122:125], v[162:165], v[190:193], v[122:125]
	v_mfma_f32_16x16x32_bf16 v[110:113], v[148:151], v[198:201], v[110:113]
	v_mfma_f32_16x16x32_bf16 v[106:109], v[162:165], v[198:201], v[106:109]
	v_mfma_f32_16x16x32_bf16 v[94:97], v[148:151], v[206:209], v[94:97]
	v_mfma_f32_16x16x32_bf16 v[90:93], v[162:165], v[206:209], v[90:93]
	v_mfma_f32_16x16x32_bf16 v[78:81], v[148:151], v[214:217], v[78:81]
	v_mfma_f32_16x16x32_bf16 v[74:77], v[162:165], v[214:217], v[74:77]
	v_mfma_f32_16x16x32_bf16 v[126:129], v[158:161], v[194:197], v[126:129]
	v_mfma_f32_16x16x32_bf16 v[122:125], v[166:169], v[194:197], v[122:125]
	v_mfma_f32_16x16x32_bf16 v[110:113], v[158:161], v[202:205], v[110:113]
	v_mfma_f32_16x16x32_bf16 v[106:109], v[166:169], v[202:205], v[106:109]
	v_mfma_f32_16x16x32_bf16 v[94:97], v[158:161], v[210:213], v[94:97]
	v_mfma_f32_16x16x32_bf16 v[90:93], v[166:169], v[210:213], v[90:93]
	v_mfma_f32_16x16x32_bf16 v[78:81], v[158:161], v[218:221], v[78:81]
	v_mfma_f32_16x16x32_bf16 v[74:77], v[166:169], v[218:221], v[74:77]
	s_setprio 0
	s_setprio 1
	v_mfma_f32_16x16x32_bf16 v[118:121], v[170:173], v[190:193], v[118:121]
	v_mfma_f32_16x16x32_bf16 v[114:117], v[182:185], v[190:193], v[114:117]
	v_mfma_f32_16x16x32_bf16 v[102:105], v[170:173], v[198:201], v[102:105]
	v_mfma_f32_16x16x32_bf16 v[98:101], v[182:185], v[198:201], v[98:101]
	v_mfma_f32_16x16x32_bf16 v[86:89], v[170:173], v[206:209], v[86:89]
	v_mfma_f32_16x16x32_bf16 v[82:85], v[182:185], v[206:209], v[82:85]
	v_mfma_f32_16x16x32_bf16 v[70:73], v[170:173], v[214:217], v[70:73]
	v_mfma_f32_16x16x32_bf16 v[66:69], v[182:185], v[214:217], v[66:69]
	v_mfma_f32_16x16x32_bf16 v[118:121], v[174:177], v[194:197], v[118:121]
	v_mfma_f32_16x16x32_bf16 v[114:117], v[186:189], v[194:197], v[114:117]
	v_mfma_f32_16x16x32_bf16 v[102:105], v[174:177], v[202:205], v[102:105]
	v_mfma_f32_16x16x32_bf16 v[98:101], v[186:189], v[202:205], v[98:101]
	v_mfma_f32_16x16x32_bf16 v[86:89], v[174:177], v[210:213], v[86:89]
	v_mfma_f32_16x16x32_bf16 v[82:85], v[186:189], v[210:213], v[82:85]
	v_mfma_f32_16x16x32_bf16 v[70:73], v[174:177], v[218:221], v[70:73]
	v_mfma_f32_16x16x32_bf16 v[66:69], v[186:189], v[218:221], v[66:69]
	s_setprio 0
	s_barrier
	s_add_i32 s63, s43, s30
	s_mov_b32 m0, s63
	ds_read_b128 v[190:193], v157 offset:16384
	ds_read_b128 v[194:197], v157 offset:17408
	ds_read_b128 v[198:201], v157 offset:18432
	ds_read_b128 v[202:205], v157 offset:19456
	ds_read_b128 v[206:209], v157 offset:20480
	ds_read_b128 v[210:213], v157 offset:21504
	ds_read_b128 v[214:217], v157 offset:22528
	ds_read_b128 v[218:221], v157 offset:23552
	global_load_lds_dwordx4 v136, s[26:27]
	s_add_i32 m0, s63, 0x2000
	s_add_u32 s64, s26, 0x40000
	v_lshl_add_u64 v[222:223], s[26:27], 0, v[132:133]
	s_addc_u32 s65, s27, 0
	s_add_i32 s63, s47, s30
	global_load_lds_dwordx4 v132, s[26:27]
	s_mov_b32 m0, s63
	v_lshl_add_u64 v[226:227], s[28:29], 0, v[134:135]
	global_load_lds_dwordx4 v136, s[64:65]
	s_add_i32 m0, s63, 0x2000
	s_nop 0
	global_load_lds_dwordx4 v132, s[64:65]
	v_lshl_add_u64 v[224:225], s[28:29], 0, v[138:139]
	s_mov_b32 m0, s23
	s_nop 0
	global_load_lds_dwordx4 v138, s[28:29]
	s_mov_b32 m0, s35
	s_nop 0
	global_load_lds_dwordx4 v134, s[28:29]
	s_waitcnt vmcnt(8)
	s_waitcnt lgkmcnt(0)
	s_barrier
	s_setprio 1
	s_waitcnt lgkmcnt(0)
	v_mfma_f32_16x16x32_bf16 v[62:65], v[148:151], v[190:193], v[62:65]
	v_mfma_f32_16x16x32_bf16 v[58:61], v[162:165], v[190:193], v[58:61]
	v_mfma_f32_16x16x32_bf16 v[46:49], v[148:151], v[198:201], v[46:49]
	v_mfma_f32_16x16x32_bf16 v[42:45], v[162:165], v[198:201], v[42:45]
	v_mfma_f32_16x16x32_bf16 v[30:33], v[148:151], v[206:209], v[30:33]
	v_mfma_f32_16x16x32_bf16 v[26:29], v[162:165], v[206:209], v[26:29]
	v_mfma_f32_16x16x32_bf16 v[14:17], v[148:151], v[214:217], v[14:17]
	v_mfma_f32_16x16x32_bf16 v[10:13], v[162:165], v[214:217], v[10:13]
	v_mfma_f32_16x16x32_bf16 v[62:65], v[158:161], v[194:197], v[62:65]
	v_mfma_f32_16x16x32_bf16 v[58:61], v[166:169], v[194:197], v[58:61]
	v_mfma_f32_16x16x32_bf16 v[46:49], v[158:161], v[202:205], v[46:49]
	v_mfma_f32_16x16x32_bf16 v[42:45], v[166:169], v[202:205], v[42:45]
	v_mfma_f32_16x16x32_bf16 v[30:33], v[158:161], v[210:213], v[30:33]
	v_mfma_f32_16x16x32_bf16 v[26:29], v[166:169], v[210:213], v[26:29]
	v_mfma_f32_16x16x32_bf16 v[14:17], v[158:161], v[218:221], v[14:17]
	v_mfma_f32_16x16x32_bf16 v[10:13], v[166:169], v[218:221], v[10:13]
	s_setprio 0
	s_setprio 1
	v_mfma_f32_16x16x32_bf16 v[54:57], v[170:173], v[190:193], v[54:57]
	v_mfma_f32_16x16x32_bf16 v[50:53], v[182:185], v[190:193], v[50:53]
	v_mfma_f32_16x16x32_bf16 v[38:41], v[170:173], v[198:201], v[38:41]
	v_mfma_f32_16x16x32_bf16 v[34:37], v[182:185], v[198:201], v[34:37]
	v_mfma_f32_16x16x32_bf16 v[22:25], v[170:173], v[206:209], v[22:25]
	v_mfma_f32_16x16x32_bf16 v[18:21], v[182:185], v[206:209], v[18:21]
	v_mfma_f32_16x16x32_bf16 v[6:9], v[170:173], v[214:217], v[6:9]
	v_mfma_f32_16x16x32_bf16 v[2:5], v[182:185], v[214:217], v[2:5]
	v_mfma_f32_16x16x32_bf16 v[54:57], v[174:177], v[194:197], v[54:57]
	v_mfma_f32_16x16x32_bf16 v[50:53], v[186:189], v[194:197], v[50:53]
	v_mfma_f32_16x16x32_bf16 v[38:41], v[174:177], v[202:205], v[38:41]
	v_mfma_f32_16x16x32_bf16 v[34:37], v[186:189], v[202:205], v[34:37]
	v_mfma_f32_16x16x32_bf16 v[22:25], v[174:177], v[210:213], v[22:25]
	v_mfma_f32_16x16x32_bf16 v[18:21], v[186:189], v[210:213], v[18:21]
	v_mfma_f32_16x16x32_bf16 v[6:9], v[174:177], v[218:221], v[6:9]
	v_mfma_f32_16x16x32_bf16 v[2:5], v[186:189], v[218:221], v[2:5]
	s_setprio 0
	s_barrier
; #define PG8_STAGE(bufoff, gbase, voff) do { _Pragma("unroll") for (int _i = 0; _i < 2; ++_i) \
;         __builtin_amdgcn_global_load_lds((const unsigned*)((const char*)(gbase) + (voff)[_i]), (PG8_LAS unsigned*)(lds + (bufoff) + ldsw + _i * 8192), 16, 0, 0); } while (0)
; #define PG8_LDA(dst, b, h) do { _Pragma("unroll") for (int m = 0; m < 4; ++m) _Pragma("unroll") for (int k = 0; k < 2; ++k) dst[m][k] = *(const PG8_LAS bf16x8*)(lds + PG8_SA(b, h) + aoff + m * 2048 + k * 1024); } while (0)
; #define PG8_LDB(dst, b, h) do { _Pragma("unroll") for (int n = 0; n < 2; ++n) _Pragma("unroll") for (int k = 0; k < 2; ++k) dst[n][k] = *(const PG8_LAS bf16x8*)(lds + PG8_SB(b, h) + boff + n * 2048 + k * 1024); } while (0)
; #define PG8_MMA(ai, bj, At, Bt) do { __builtin_amdgcn_s_setprio(1); _Pragma("unroll") for (int m = 0; m < 4; ++m) _Pragma("unroll") for (int n = 0; n < 2; ++n) _Pragma("unroll") for (int k = 0; k < 2; ++k) \
;         acc[ai][bj][m][n] = __builtin_amdgcn_mfma_f32_16x16x32_bf16(Bt[n][k], At[m][k], acc[ai][bj][m][n], 0, 0, 0); __builtin_amdgcn_s_setprio(0); } while (0)
; #define PG8_WAIT_V(n) asm volatile("s_waitcnt vmcnt(" #n ")" ::: "memory")
; #define PG8_WAIT_L(n) asm volatile("s_waitcnt lgkmcnt(" #n ")" ::: "memory")
; #define PG8_BAR __builtin_amdgcn_s_barrier()
; #define PG8_SCHED __builtin_amdgcn_sched_barrier(0)
; template <class Epi, class Sched, bool ALIGN_EPI = false, bool SP2 = false>
; __device__ __forceinline__ void gemm_phase(PG8_LAS unsigned char* lds, const Gemm g, const Sched& S, const Epi& E) {
;     ...
;             PG8_LDB(B0, 1, 0); PG8_LDB(B1, 1, 1); PG8_SCHED; PG8_LDA(At, 1, 0); PG8_STAGE(PG8_SA(0, 1), a2 + hstep, voffA);
;             PG8_WAIT_V(8); PG8_WAIT_L(0); PG8_BAR; PG8_MMA(0, 0, At, B0); PG8_MMA(0, 1, At, B1); PG8_BAR; PG8_SCHED;
	s_add_i32 s63, 0, 0x18000
	s_add_i32 s64, 0, 0x1c000
	v_add_u32_e32 v166, s63, v153
	v_add_u32_e32 v186, s64, v153
	ds_read_b128 v[148:151], v166
	ds_read_b128 v[158:161], v166 offset:1024
	ds_read_b128 v[162:165], v166 offset:2048
	ds_read_b128 v[166:169], v166 offset:3072
	ds_read_b128 v[170:173], v186
	ds_read_b128 v[174:177], v186 offset:1024
	ds_read_b128 v[182:185], v186 offset:2048
	ds_read_b128 v[186:189], v186 offset:3072
	s_add_u32 s28, s28, 0x40000
	s_addc_u32 s29, s29, 0
	s_mov_b32 m0, s36
	ds_read_b128 v[190:193], v157 offset:32768
	ds_read_b128 v[194:197], v157 offset:33792
	ds_read_b128 v[198:201], v157 offset:34816
	ds_read_b128 v[202:205], v157 offset:35840
	ds_read_b128 v[206:209], v157 offset:36864
	ds_read_b128 v[210:213], v157 offset:37888
	ds_read_b128 v[214:217], v157 offset:38912
	ds_read_b128 v[218:221], v157 offset:39936
	global_load_lds_dwordx4 v138, s[28:29]
	v_lshl_add_u64 v[228:229], s[28:29], 0, v[134:135]
	s_mov_b32 m0, s37
	s_nop 0
	global_load_lds_dwordx4 v134, s[28:29]
	s_waitcnt vmcnt(8)
	s_waitcnt lgkmcnt(0)
	s_barrier
	s_setprio 1
	s_waitcnt lgkmcnt(0)
	v_mfma_f32_16x16x32_bf16 v[126:129], v[148:151], v[190:193], v[126:129]
	v_mfma_f32_16x16x32_bf16 v[122:125], v[162:165], v[190:193], v[122:125]
	v_mfma_f32_16x16x32_bf16 v[110:113], v[148:151], v[198:201], v[110:113]
	v_mfma_f32_16x16x32_bf16 v[106:109], v[162:165], v[198:201], v[106:109]
	v_mfma_f32_16x16x32_bf16 v[94:97], v[148:151], v[206:209], v[94:97]
	v_mfma_f32_16x16x32_bf16 v[90:93], v[162:165], v[206:209], v[90:93]
	v_mfma_f32_16x16x32_bf16 v[78:81], v[148:151], v[214:217], v[78:81]
	v_mfma_f32_16x16x32_bf16 v[74:77], v[162:165], v[214:217], v[74:77]
	v_mfma_f32_16x16x32_bf16 v[126:129], v[158:161], v[194:197], v[126:129]
	v_mfma_f32_16x16x32_bf16 v[122:125], v[166:169], v[194:197], v[122:125]
	v_mfma_f32_16x16x32_bf16 v[110:113], v[158:161], v[202:205], v[110:113]
	v_mfma_f32_16x16x32_bf16 v[106:109], v[166:169], v[202:205], v[106:109]
	v_mfma_f32_16x16x32_bf16 v[94:97], v[158:161], v[210:213], v[94:97]
	v_mfma_f32_16x16x32_bf16 v[90:93], v[166:169], v[210:213], v[90:93]
	v_mfma_f32_16x16x32_bf16 v[78:81], v[158:161], v[218:221], v[78:81]
	v_mfma_f32_16x16x32_bf16 v[74:77], v[166:169], v[218:221], v[74:77]
	s_setprio 0
	s_setprio 1
	v_mfma_f32_16x16x32_bf16 v[118:121], v[170:173], v[190:193], v[118:121]
	v_mfma_f32_16x16x32_bf16 v[114:117], v[182:185], v[190:193], v[114:117]
	v_mfma_f32_16x16x32_bf16 v[102:105], v[170:173], v[198:201], v[102:105]
	v_mfma_f32_16x16x32_bf16 v[98:101], v[182:185], v[198:201], v[98:101]
	v_mfma_f32_16x16x32_bf16 v[86:89], v[170:173], v[206:209], v[86:89]
	v_mfma_f32_16x16x32_bf16 v[82:85], v[182:185], v[206:209], v[82:85]
	v_mfma_f32_16x16x32_bf16 v[70:73], v[170:173], v[214:217], v[70:73]
	v_mfma_f32_16x16x32_bf16 v[66:69], v[182:185], v[214:217], v[66:69]
	v_mfma_f32_16x16x32_bf16 v[118:121], v[174:177], v[194:197], v[118:121]
	v_mfma_f32_16x16x32_bf16 v[114:117], v[186:189], v[194:197], v[114:117]
	v_mfma_f32_16x16x32_bf16 v[102:105], v[174:177], v[202:205], v[102:105]
	v_mfma_f32_16x16x32_bf16 v[98:101], v[186:189], v[202:205], v[98:101]
	v_mfma_f32_16x16x32_bf16 v[86:89], v[174:177], v[210:213], v[86:89]
	v_mfma_f32_16x16x32_bf16 v[82:85], v[186:189], v[210:213], v[82:85]
	v_mfma_f32_16x16x32_bf16 v[70:73], v[174:177], v[218:221], v[70:73]
	v_mfma_f32_16x16x32_bf16 v[66:69], v[186:189], v[218:221], v[66:69]
	s_setprio 0
	s_barrier
; #define PG8_STAGE(bufoff, gbase, voff) do { _Pragma("unroll") for (int _i = 0; _i < 2; ++_i) \
;         __builtin_amdgcn_global_load_lds((const unsigned*)((const char*)(gbase) + (voff)[_i]), (PG8_LAS unsigned*)(lds + (bufoff) + ldsw + _i * 8192), 16, 0, 0); } while (0)
; #define PG8_LDA(dst, b, h) do { _Pragma("unroll") for (int m = 0; m < 4; ++m) _Pragma("unroll") for (int k = 0; k < 2; ++k) dst[m][k] = *(const PG8_LAS bf16x8*)(lds + PG8_SA(b, h) + aoff + m * 2048 + k * 1024); } while (0)
; #define PG8_MMA(ai, bj, At, Bt) do { __builtin_amdgcn_s_setprio(1); _Pragma("unroll") for (int m = 0; m < 4; ++m) _Pragma("unroll") for (int n = 0; n < 2; ++n) _Pragma("unroll") for (int k = 0; k < 2; ++k) \
;         acc[ai][bj][m][n] = __builtin_amdgcn_mfma_f32_16x16x32_bf16(Bt[n][k], At[m][k], acc[ai][bj][m][n], 0, 0, 0); __builtin_amdgcn_s_setprio(0); } while (0)
; #define PG8_WAIT_V(n) asm volatile("s_waitcnt vmcnt(" #n ")" ::: "memory")
; #define PG8_WAIT_L(n) asm volatile("s_waitcnt lgkmcnt(" #n ")" ::: "memory")
; #define PG8_BAR __builtin_amdgcn_s_barrier()
; #define PG8_SCHED __builtin_amdgcn_sched_barrier(0)
; template <class Epi, class Sched, bool ALIGN_EPI = false, bool SP2 = false>
; __device__ __forceinline__ void gemm_phase(PG8_LAS unsigned char* lds, const Gemm g, const Sched& S, const Epi& E) {
;     ...
;         for (int t = 0; t < nt; t += 2) {
;     ...
;             PG8_LDA(At, 1, 1); PG8_STAGE(PG8_SB(1, 0), b3, voffB); PG8_STAGE(PG8_SB(1, 1), b3 + hstep, voffB); PG8_STAGE(PG8_SA(1, 0), a3, voffA);
;             PG8_WAIT_V(8); PG8_WAIT_L(0); PG8_BAR; PG8_MMA(1, 0, At, B0); PG8_MMA(1, 1, At, B1); PG8_BAR; PG8_SCHED;
	s_add_i32 s28, s63, s30
	s_mov_b32 m0, s28
	ds_read_b128 v[190:193], v157 offset:49152
	ds_read_b128 v[194:197], v157 offset:50176
	ds_read_b128 v[198:201], v157 offset:51200
	ds_read_b128 v[202:205], v157 offset:52224
	ds_read_b128 v[206:209], v157 offset:53248
	ds_read_b128 v[210:213], v157 offset:54272
	ds_read_b128 v[214:217], v157 offset:55296
	ds_read_b128 v[218:221], v157 offset:56320
	s_add_u32 s98, s26, s10
	s_addc_u32 s99, s27, s11
	global_load_lds_dwordx4 v136, s[98:99]
	s_add_i32 m0, s28, 0x2000
	s_add_u32 s26, s26, 0x40080
	v_lshl_add_u64 v[178:179], v[222:223], 0, s[10:11]
	s_addc_u32 s27, s27, 0
	s_add_i32 s28, s64, s30
	global_load_lds_dwordx4 v[178:179], off
	s_mov_b32 m0, s28
	s_nop 0
	global_load_lds_dwordx4 v136, s[26:27]
	s_add_i32 m0, s28, 0x2000
	s_nop 0
	global_load_lds_dwordx4 v132, s[26:27]
	v_lshl_add_u64 v[178:179], v[224:225], 0, s[10:11]
	s_mov_b32 m0, s39
	s_nop 0
	global_load_lds_dwordx4 v[178:179], off
	v_lshl_add_u64 v[178:179], v[226:227], 0, s[10:11]
	s_mov_b32 m0, s40
	s_nop 0
	global_load_lds_dwordx4 v[178:179], off
	s_waitcnt vmcnt(8)
	s_waitcnt lgkmcnt(0)
	s_barrier
	s_setprio 1
	s_waitcnt lgkmcnt(0)
	v_mfma_f32_16x16x32_bf16 v[62:65], v[148:151], v[190:193], v[62:65]
	v_mfma_f32_16x16x32_bf16 v[58:61], v[162:165], v[190:193], v[58:61]
	v_mfma_f32_16x16x32_bf16 v[46:49], v[148:151], v[198:201], v[46:49]
	v_mfma_f32_16x16x32_bf16 v[42:45], v[162:165], v[198:201], v[42:45]
	v_mfma_f32_16x16x32_bf16 v[30:33], v[148:151], v[206:209], v[30:33]
	v_mfma_f32_16x16x32_bf16 v[26:29], v[162:165], v[206:209], v[26:29]
	v_mfma_f32_16x16x32_bf16 v[14:17], v[148:151], v[214:217], v[14:17]
	v_mfma_f32_16x16x32_bf16 v[10:13], v[162:165], v[214:217], v[10:13]
	v_mfma_f32_16x16x32_bf16 v[62:65], v[158:161], v[194:197], v[62:65]
	v_mfma_f32_16x16x32_bf16 v[58:61], v[166:169], v[194:197], v[58:61]
	v_mfma_f32_16x16x32_bf16 v[46:49], v[158:161], v[202:205], v[46:49]
	v_mfma_f32_16x16x32_bf16 v[42:45], v[166:169], v[202:205], v[42:45]
	v_mfma_f32_16x16x32_bf16 v[30:33], v[158:161], v[210:213], v[30:33]
	v_mfma_f32_16x16x32_bf16 v[26:29], v[166:169], v[210:213], v[26:29]
	v_mfma_f32_16x16x32_bf16 v[14:17], v[158:161], v[218:221], v[14:17]
	v_mfma_f32_16x16x32_bf16 v[10:13], v[166:169], v[218:221], v[10:13]
	s_setprio 0
	s_setprio 1
	v_mfma_f32_16x16x32_bf16 v[54:57], v[170:173], v[190:193], v[54:57]
	v_mfma_f32_16x16x32_bf16 v[50:53], v[182:185], v[190:193], v[50:53]
	v_mfma_f32_16x16x32_bf16 v[38:41], v[170:173], v[198:201], v[38:41]
	v_mfma_f32_16x16x32_bf16 v[34:37], v[182:185], v[198:201], v[34:37]
	v_mfma_f32_16x16x32_bf16 v[22:25], v[170:173], v[206:209], v[22:25]
	v_mfma_f32_16x16x32_bf16 v[18:21], v[182:185], v[206:209], v[18:21]
	v_mfma_f32_16x16x32_bf16 v[6:9], v[170:173], v[214:217], v[6:9]
	v_mfma_f32_16x16x32_bf16 v[2:5], v[182:185], v[214:217], v[2:5]
	v_mfma_f32_16x16x32_bf16 v[54:57], v[174:177], v[194:197], v[54:57]
	v_mfma_f32_16x16x32_bf16 v[50:53], v[186:189], v[194:197], v[50:53]
	v_mfma_f32_16x16x32_bf16 v[38:41], v[174:177], v[202:205], v[38:41]
	v_mfma_f32_16x16x32_bf16 v[34:37], v[186:189], v[202:205], v[34:37]
	v_mfma_f32_16x16x32_bf16 v[22:25], v[174:177], v[210:213], v[22:25]
	v_mfma_f32_16x16x32_bf16 v[18:21], v[186:189], v[210:213], v[18:21]
	v_mfma_f32_16x16x32_bf16 v[6:9], v[174:177], v[218:221], v[6:9]
	v_mfma_f32_16x16x32_bf16 v[2:5], v[186:189], v[218:221], v[2:5]
	s_setprio 0
	s_barrier
	s_add_i32 s62, s62, 2
	s_add_u32 s24, s24, 0x100
	s_addc_u32 s25, s25, 0
	s_add_u32 s58, s58, 0x100
	s_addc_u32 s59, s59, 0
	s_cmp_gt_u32 s62, 13
	s_cbranch_scc0 .LBB0_890
	s_and_b64 vcc, exec, s[12:13]
	s_cbranch_vccz .LBB0_893
	s_barrier

; #define PG8_STAGE(bufoff, gbase, voff) do { _Pragma("unroll") for (int _i = 0; _i < 2; ++_i) \
;         __builtin_amdgcn_global_load_lds((const unsigned*)((const char*)(gbase) + (voff)[_i]), (PG8_LAS unsigned*)(lds + (bufoff) + ldsw + _i * 8192), 16, 0, 0); } while (0)
; #define PG8_LDA(dst, b, h) do { _Pragma("unroll") for (int m = 0; m < 4; ++m) _Pragma("unroll") for (int k = 0; k < 2; ++k) dst[m][k] = *(const PG8_LAS bf16x8*)(lds + PG8_SA(b, h) + aoff + m * 2048 + k * 1024); } while (0)
; #define PG8_LDB(dst, b, h) do { _Pragma("unroll") for (int n = 0; n < 2; ++n) _Pragma("unroll") for (int k = 0; k < 2; ++k) dst[n][k] = *(const PG8_LAS bf16x8*)(lds + PG8_SB(b, h) + boff + n * 2048 + k * 1024); } while (0)
; #define PG8_MMA(ai, bj, At, Bt) do { __builtin_amdgcn_s_setprio(1); _Pragma("unroll") for (int m = 0; m < 4; ++m) _Pragma("unroll") for (int n = 0; n < 2; ++n) _Pragma("unroll") for (int k = 0; k < 2; ++k) \
;         acc[ai][bj][m][n] = __builtin_amdgcn_mfma_f32_16x16x32_bf16(Bt[n][k], At[m][k], acc[ai][bj][m][n], 0, 0, 0); __builtin_amdgcn_s_setprio(0); } while (0)
; #define PG8_WAIT_V(n) asm volatile("s_waitcnt vmcnt(" #n ")" ::: "memory")
; #define PG8_WAIT_L(n) asm volatile("s_waitcnt lgkmcnt(" #n ")" ::: "memory")
; template <class Epi, class Sched, bool ALIGN_EPI = false, bool SP2 = false>
; __device__ __forceinline__ void gemm_phase(PG8_LAS unsigned char* lds, const Gemm g, const Sched& S, const Epi& E) {
;     ...
;             const bool last = (t == nt - 2);
;             const char* a1 = cA + (size_t)(t + 1) * kstep;
;             const char* a2 = last ? nA : cA + (size_t)(t + 2) * kstep; const char* b2 = last ? nB : cB + (size_t)(t + 2) * kstep;
;             const char* a3 = a2 + kstep; const char* b3 = b2 + kstep;
;             if (last && has_next) S.a_ready(nxt);
;             if constexpr (SP2) {
;             PG8_LDB(B0, 0, 0); PG8_LDB(B1, 0, 1); PG8_SCHED; PG8_LDA(At, 0, 0); PG8_STAGE(PG8_SA(1, 1), a1 + hstep, voffA);
;             PG8_WAIT_V(8); PG8_WAIT_L(0); PG8_BAR; PG8_MMA(0, 0, At, B0); PG8_MMA(0, 1, At, B1); PG8_BAR; PG8_SCHED;
;             PG8_LDA(At, 0, 1); PG8_STAGE(PG8_SB(0, 0), b2, voffB); PG8_STAGE(PG8_SB(0, 1), b2 + hstep, voffB); PG8_STAGE(PG8_SA(0, 0), a2, voffA);
;             PG8_WAIT_V(8); PG8_WAIT_L(0); PG8_BAR; PG8_MMA(1, 0, At, B0); PG8_MMA(1, 1, At, B1); PG8_BAR; PG8_SCHED;
.LBB0_973:
	ds_read_b128 v[156:159], v153
	ds_read_b128 v[160:163], v153 offset:1024
	ds_read_b128 v[164:167], v153 offset:2048
	ds_read_b128 v[168:171], v153 offset:3072
	ds_read_b128 v[172:175], v154
	ds_read_b128 v[176:179], v154 offset:1024
	ds_read_b128 v[182:185], v154 offset:2048
	ds_read_b128 v[186:189], v154 offset:3072
	s_add_u32 s28, s26, 0xfff50080
	s_addc_u32 s29, s27, -1
	s_cmp_eq_u32 s68, 40
	s_cselect_b32 s31, s5, s29
	s_cselect_b32 s30, s4, s28
	s_cselect_b32 s29, s25, s67
	s_cselect_b32 s28, s24, s66
	s_add_i32 m0, s36, 0xc000
	ds_read_b128 v[190:193], v155
	ds_read_b128 v[194:197], v155 offset:1024
	ds_read_b128 v[198:201], v155 offset:2048
	ds_read_b128 v[202:205], v155 offset:3072
	ds_read_b128 v[206:209], v155 offset:4096
	ds_read_b128 v[210:213], v155 offset:5120
	ds_read_b128 v[214:217], v155 offset:6144
	ds_read_b128 v[218:221], v155 offset:7168
	global_load_lds_dwordx4 v140, s[26:27]
	s_add_i32 m0, s36, 0xe000
	s_nop 0
	global_load_lds_dwordx4 v142, s[26:27]
	s_waitcnt vmcnt(8)
	s_waitcnt lgkmcnt(0)
	s_barrier
	s_setprio 1
	s_waitcnt lgkmcnt(0)
	v_mfma_f32_16x16x32_bf16 v[126:129], v[156:159], v[190:193], v[126:129]
	v_mfma_f32_16x16x32_bf16 v[122:125], v[164:167], v[190:193], v[122:125]
	v_mfma_f32_16x16x32_bf16 v[118:121], v[156:159], v[198:201], v[118:121]
	v_mfma_f32_16x16x32_bf16 v[110:113], v[164:167], v[198:201], v[110:113]
	v_mfma_f32_16x16x32_bf16 v[102:105], v[156:159], v[206:209], v[102:105]
	v_mfma_f32_16x16x32_bf16 v[94:97], v[164:167], v[206:209], v[94:97]
	v_mfma_f32_16x16x32_bf16 v[86:89], v[156:159], v[214:217], v[86:89]
	v_mfma_f32_16x16x32_bf16 v[78:81], v[164:167], v[214:217], v[78:81]
	v_mfma_f32_16x16x32_bf16 v[126:129], v[160:163], v[194:197], v[126:129]
	v_mfma_f32_16x16x32_bf16 v[122:125], v[168:171], v[194:197], v[122:125]
	v_mfma_f32_16x16x32_bf16 v[118:121], v[160:163], v[202:205], v[118:121]
	v_mfma_f32_16x16x32_bf16 v[110:113], v[168:171], v[202:205], v[110:113]
	v_mfma_f32_16x16x32_bf16 v[102:105], v[160:163], v[210:213], v[102:105]
	v_mfma_f32_16x16x32_bf16 v[94:97], v[168:171], v[210:213], v[94:97]
	v_mfma_f32_16x16x32_bf16 v[86:89], v[160:163], v[218:221], v[86:89]
	v_mfma_f32_16x16x32_bf16 v[78:81], v[168:171], v[218:221], v[78:81]
	s_setprio 0
	s_setprio 1
	v_mfma_f32_16x16x32_bf16 v[114:117], v[172:175], v[190:193], v[114:117]
	v_mfma_f32_16x16x32_bf16 v[106:109], v[182:185], v[190:193], v[106:109]
	v_mfma_f32_16x16x32_bf16 v[98:101], v[172:175], v[198:201], v[98:101]
	v_mfma_f32_16x16x32_bf16 v[90:93], v[182:185], v[198:201], v[90:93]
	v_mfma_f32_16x16x32_bf16 v[82:85], v[172:175], v[206:209], v[82:85]
	v_mfma_f32_16x16x32_bf16 v[74:77], v[182:185], v[206:209], v[74:77]
	v_mfma_f32_16x16x32_bf16 v[70:73], v[172:175], v[214:217], v[70:73]
	v_mfma_f32_16x16x32_bf16 v[66:69], v[182:185], v[214:217], v[66:69]
	v_mfma_f32_16x16x32_bf16 v[114:117], v[176:179], v[194:197], v[114:117]
	v_mfma_f32_16x16x32_bf16 v[106:109], v[186:189], v[194:197], v[106:109]
	v_mfma_f32_16x16x32_bf16 v[98:101], v[176:179], v[202:205], v[98:101]
	v_mfma_f32_16x16x32_bf16 v[90:93], v[186:189], v[202:205], v[90:93]
	v_mfma_f32_16x16x32_bf16 v[82:85], v[176:179], v[210:213], v[82:85]
	v_mfma_f32_16x16x32_bf16 v[74:77], v[186:189], v[210:213], v[74:77]
	v_mfma_f32_16x16x32_bf16 v[70:73], v[176:179], v[218:221], v[70:73]
	v_mfma_f32_16x16x32_bf16 v[66:69], v[186:189], v[218:221], v[66:69]
	s_setprio 0
	s_barrier
	s_add_i32 s69, s48, s35
	s_mov_b32 m0, s69
	ds_read_b128 v[190:193], v155 offset:16384
	ds_read_b128 v[194:197], v155 offset:17408
	ds_read_b128 v[198:201], v155 offset:18432
	ds_read_b128 v[202:205], v155 offset:19456
	ds_read_b128 v[206:209], v155 offset:20480
	ds_read_b128 v[210:213], v155 offset:21504
	ds_read_b128 v[214:217], v155 offset:22528
	ds_read_b128 v[218:221], v155 offset:23552
	global_load_lds_dwordx4 v134, s[28:29]
	s_add_i32 m0, s69, 0x2000
	s_add_u32 s70, s28, 0xb0000
	v_lshl_add_u64 v[222:223], s[28:29], 0, v[138:139]
	s_addc_u32 s71, s29, 0
	s_add_i32 s69, s49, s35
	global_load_lds_dwordx4 v138, s[28:29]
	s_mov_b32 m0, s69
	v_lshl_add_u64 v[226:227], s[30:31], 0, v[136:137]
	global_load_lds_dwordx4 v134, s[70:71]
	s_add_i32 m0, s69, 0x2000
	s_nop 0
	global_load_lds_dwordx4 v138, s[70:71]
	v_lshl_add_u64 v[224:225], s[30:31], 0, v[132:133]
	s_mov_b32 m0, s36
	s_nop 0
	global_load_lds_dwordx4 v132, s[30:31]
	s_mov_b32 m0, s37
	s_nop 0
	global_load_lds_dwordx4 v136, s[30:31]
	s_waitcnt vmcnt(8)
	s_waitcnt lgkmcnt(0)
	s_barrier
	s_setprio 1
	s_waitcnt lgkmcnt(0)
	v_mfma_f32_16x16x32_bf16 v[62:65], v[156:159], v[190:193], v[62:65]
	v_mfma_f32_16x16x32_bf16 v[58:61], v[164:167], v[190:193], v[58:61]
	v_mfma_f32_16x16x32_bf16 v[54:57], v[156:159], v[198:201], v[54:57]
	v_mfma_f32_16x16x32_bf16 v[46:49], v[164:167], v[198:201], v[46:49]
	v_mfma_f32_16x16x32_bf16 v[38:41], v[156:159], v[206:209], v[38:41]
	v_mfma_f32_16x16x32_bf16 v[30:33], v[164:167], v[206:209], v[30:33]
	v_mfma_f32_16x16x32_bf16 v[22:25], v[156:159], v[214:217], v[22:25]
	v_mfma_f32_16x16x32_bf16 v[14:17], v[164:167], v[214:217], v[14:17]
	v_mfma_f32_16x16x32_bf16 v[62:65], v[160:163], v[194:197], v[62:65]
	v_mfma_f32_16x16x32_bf16 v[58:61], v[168:171], v[194:197], v[58:61]
	v_mfma_f32_16x16x32_bf16 v[54:57], v[160:163], v[202:205], v[54:57]
	v_mfma_f32_16x16x32_bf16 v[46:49], v[168:171], v[202:205], v[46:49]
	v_mfma_f32_16x16x32_bf16 v[38:41], v[160:163], v[210:213], v[38:41]
	v_mfma_f32_16x16x32_bf16 v[30:33], v[168:171], v[210:213], v[30:33]
	v_mfma_f32_16x16x32_bf16 v[22:25], v[160:163], v[218:221], v[22:25]
	v_mfma_f32_16x16x32_bf16 v[14:17], v[168:171], v[218:221], v[14:17]
	s_setprio 0
	s_setprio 1
	v_mfma_f32_16x16x32_bf16 v[50:53], v[172:175], v[190:193], v[50:53]
	v_mfma_f32_16x16x32_bf16 v[42:45], v[182:185], v[190:193], v[42:45]
	v_mfma_f32_16x16x32_bf16 v[34:37], v[172:175], v[198:201], v[34:37]
	v_mfma_f32_16x16x32_bf16 v[26:29], v[182:185], v[198:201], v[26:29]
	v_mfma_f32_16x16x32_bf16 v[18:21], v[172:175], v[206:209], v[18:21]
	v_mfma_f32_16x16x32_bf16 v[10:13], v[182:185], v[206:209], v[10:13]
	v_mfma_f32_16x16x32_bf16 v[6:9], v[172:175], v[214:217], v[6:9]
	v_mfma_f32_16x16x32_bf16 v[2:5], v[182:185], v[214:217], v[2:5]
	v_mfma_f32_16x16x32_bf16 v[50:53], v[176:179], v[194:197], v[50:53]
	v_mfma_f32_16x16x32_bf16 v[42:45], v[186:189], v[194:197], v[42:45]
	v_mfma_f32_16x16x32_bf16 v[34:37], v[176:179], v[202:205], v[34:37]
	v_mfma_f32_16x16x32_bf16 v[26:29], v[186:189], v[202:205], v[26:29]
	v_mfma_f32_16x16x32_bf16 v[18:21], v[176:179], v[210:213], v[18:21]
	v_mfma_f32_16x16x32_bf16 v[10:13], v[186:189], v[210:213], v[10:13]
	v_mfma_f32_16x16x32_bf16 v[6:9], v[176:179], v[218:221], v[6:9]
	v_mfma_f32_16x16x32_bf16 v[2:5], v[186:189], v[218:221], v[2:5]
	s_setprio 0
	s_barrier
; #define PG8_STAGE(bufoff, gbase, voff) do { _Pragma("unroll") for (int _i = 0; _i < 2; ++_i) \
;         __builtin_amdgcn_global_load_lds((const unsigned*)((const char*)(gbase) + (voff)[_i]), (PG8_LAS unsigned*)(lds + (bufoff) + ldsw + _i * 8192), 16, 0, 0); } while (0)
; #define PG8_LDA(dst, b, h) do { _Pragma("unroll") for (int m = 0; m < 4; ++m) _Pragma("unroll") for (int k = 0; k < 2; ++k) dst[m][k] = *(const PG8_LAS bf16x8*)(lds + PG8_SA(b, h) + aoff + m * 2048 + k * 1024); } while (0)
; #define PG8_LDB(dst, b, h) do { _Pragma("unroll") for (int n = 0; n < 2; ++n) _Pragma("unroll") for (int k = 0; k < 2; ++k) dst[n][k] = *(const PG8_LAS bf16x8*)(lds + PG8_SB(b, h) + boff + n * 2048 + k * 1024); } while (0)
; #define PG8_MMA(ai, bj, At, Bt) do { __builtin_amdgcn_s_setprio(1); _Pragma("unroll") for (int m = 0; m < 4; ++m) _Pragma("unroll") for (int n = 0; n < 2; ++n) _Pragma("unroll") for (int k = 0; k < 2; ++k) \
;         acc[ai][bj][m][n] = __builtin_amdgcn_mfma_f32_16x16x32_bf16(Bt[n][k], At[m][k], acc[ai][bj][m][n], 0, 0, 0); __builtin_amdgcn_s_setprio(0); } while (0)
; #define PG8_WAIT_V(n) asm volatile("s_waitcnt vmcnt(" #n ")" ::: "memory")
; #define PG8_WAIT_L(n) asm volatile("s_waitcnt lgkmcnt(" #n ")" ::: "memory")
; #define PG8_BAR __builtin_amdgcn_s_barrier()
; #define PG8_SCHED __builtin_amdgcn_sched_barrier(0)
; template <class Epi, class Sched, bool ALIGN_EPI = false, bool SP2 = false>
; __device__ __forceinline__ void gemm_phase(PG8_LAS unsigned char* lds, const Gemm g, const Sched& S, const Epi& E) {
;     ...
;             PG8_LDB(B0, 1, 0); PG8_LDB(B1, 1, 1); PG8_SCHED; PG8_LDA(At, 1, 0); PG8_STAGE(PG8_SA(0, 1), a2 + hstep, voffA);
;             PG8_WAIT_V(8); PG8_WAIT_L(0); PG8_BAR; PG8_MMA(0, 0, At, B0); PG8_MMA(0, 1, At, B1); PG8_BAR; PG8_SCHED;
	s_add_i32 s69, 0, 0x18000
	s_add_i32 s70, 0, 0x1c000
	v_add_u32_e32 v168, s69, v151
	v_add_u32_e32 v186, s70, v151
	ds_read_b128 v[156:159], v168
	ds_read_b128 v[160:163], v168 offset:1024
	ds_read_b128 v[164:167], v168 offset:2048
	ds_read_b128 v[168:171], v168 offset:3072
	ds_read_b128 v[172:175], v186
	ds_read_b128 v[176:179], v186 offset:1024
	ds_read_b128 v[182:185], v186 offset:2048
	ds_read_b128 v[186:189], v186 offset:3072
	s_add_u32 s30, s30, 0xb0000
	s_addc_u32 s31, s31, 0
	s_mov_b32 m0, s38
	ds_read_b128 v[190:193], v155 offset:32768
	ds_read_b128 v[194:197], v155 offset:33792
	ds_read_b128 v[198:201], v155 offset:34816
	ds_read_b128 v[202:205], v155 offset:35840
	ds_read_b128 v[206:209], v155 offset:36864
	ds_read_b128 v[210:213], v155 offset:37888
	ds_read_b128 v[214:217], v155 offset:38912
	ds_read_b128 v[218:221], v155 offset:39936
	global_load_lds_dwordx4 v132, s[30:31]
	v_lshl_add_u64 v[228:229], s[30:31], 0, v[136:137]
	s_mov_b32 m0, s39
	s_nop 0
	global_load_lds_dwordx4 v136, s[30:31]
	s_waitcnt vmcnt(8)
	s_waitcnt lgkmcnt(0)
	s_barrier
	s_setprio 1
	s_waitcnt lgkmcnt(0)
	v_mfma_f32_16x16x32_bf16 v[126:129], v[156:159], v[190:193], v[126:129]
	v_mfma_f32_16x16x32_bf16 v[122:125], v[164:167], v[190:193], v[122:125]
	v_mfma_f32_16x16x32_bf16 v[118:121], v[156:159], v[198:201], v[118:121]
	v_mfma_f32_16x16x32_bf16 v[110:113], v[164:167], v[198:201], v[110:113]
	v_mfma_f32_16x16x32_bf16 v[102:105], v[156:159], v[206:209], v[102:105]
	v_mfma_f32_16x16x32_bf16 v[94:97], v[164:167], v[206:209], v[94:97]
	v_mfma_f32_16x16x32_bf16 v[86:89], v[156:159], v[214:217], v[86:89]
	v_mfma_f32_16x16x32_bf16 v[78:81], v[164:167], v[214:217], v[78:81]
	v_mfma_f32_16x16x32_bf16 v[126:129], v[160:163], v[194:197], v[126:129]
	v_mfma_f32_16x16x32_bf16 v[122:125], v[168:171], v[194:197], v[122:125]
	v_mfma_f32_16x16x32_bf16 v[118:121], v[160:163], v[202:205], v[118:121]
	v_mfma_f32_16x16x32_bf16 v[110:113], v[168:171], v[202:205], v[110:113]
	v_mfma_f32_16x16x32_bf16 v[102:105], v[160:163], v[210:213], v[102:105]
	v_mfma_f32_16x16x32_bf16 v[94:97], v[168:171], v[210:213], v[94:97]
	v_mfma_f32_16x16x32_bf16 v[86:89], v[160:163], v[218:221], v[86:89]
	v_mfma_f32_16x16x32_bf16 v[78:81], v[168:171], v[218:221], v[78:81]
	s_setprio 0
	s_setprio 1
	v_mfma_f32_16x16x32_bf16 v[114:117], v[172:175], v[190:193], v[114:117]
	v_mfma_f32_16x16x32_bf16 v[106:109], v[182:185], v[190:193], v[106:109]
	v_mfma_f32_16x16x32_bf16 v[98:101], v[172:175], v[198:201], v[98:101]
	v_mfma_f32_16x16x32_bf16 v[90:93], v[182:185], v[198:201], v[90:93]
	v_mfma_f32_16x16x32_bf16 v[82:85], v[172:175], v[206:209], v[82:85]
	v_mfma_f32_16x16x32_bf16 v[74:77], v[182:185], v[206:209], v[74:77]
	v_mfma_f32_16x16x32_bf16 v[70:73], v[172:175], v[214:217], v[70:73]
	v_mfma_f32_16x16x32_bf16 v[66:69], v[182:185], v[214:217], v[66:69]
	v_mfma_f32_16x16x32_bf16 v[114:117], v[176:179], v[194:197], v[114:117]
	v_mfma_f32_16x16x32_bf16 v[106:109], v[186:189], v[194:197], v[106:109]
	v_mfma_f32_16x16x32_bf16 v[98:101], v[176:179], v[202:205], v[98:101]
	v_mfma_f32_16x16x32_bf16 v[90:93], v[186:189], v[202:205], v[90:93]
	v_mfma_f32_16x16x32_bf16 v[82:85], v[176:179], v[210:213], v[82:85]
	v_mfma_f32_16x16x32_bf16 v[74:77], v[186:189], v[210:213], v[74:77]
	v_mfma_f32_16x16x32_bf16 v[70:73], v[176:179], v[218:221], v[70:73]
	v_mfma_f32_16x16x32_bf16 v[66:69], v[186:189], v[218:221], v[66:69]
	s_setprio 0
	s_barrier
; #define PG8_STAGE(bufoff, gbase, voff) do { _Pragma("unroll") for (int _i = 0; _i < 2; ++_i) \
;         __builtin_amdgcn_global_load_lds((const unsigned*)((const char*)(gbase) + (voff)[_i]), (PG8_LAS unsigned*)(lds + (bufoff) + ldsw + _i * 8192), 16, 0, 0); } while (0)
; #define PG8_LDA(dst, b, h) do { _Pragma("unroll") for (int m = 0; m < 4; ++m) _Pragma("unroll") for (int k = 0; k < 2; ++k) dst[m][k] = *(const PG8_LAS bf16x8*)(lds + PG8_SA(b, h) + aoff + m * 2048 + k * 1024); } while (0)
; #define PG8_MMA(ai, bj, At, Bt) do { __builtin_amdgcn_s_setprio(1); _Pragma("unroll") for (int m = 0; m < 4; ++m) _Pragma("unroll") for (int n = 0; n < 2; ++n) _Pragma("unroll") for (int k = 0; k < 2; ++k) \
;         acc[ai][bj][m][n] = __builtin_amdgcn_mfma_f32_16x16x32_bf16(Bt[n][k], At[m][k], acc[ai][bj][m][n], 0, 0, 0); __builtin_amdgcn_s_setprio(0); } while (0)
; #define PG8_WAIT_V(n) asm volatile("s_waitcnt vmcnt(" #n ")" ::: "memory")
; #define PG8_WAIT_L(n) asm volatile("s_waitcnt lgkmcnt(" #n ")" ::: "memory")
; #define PG8_BAR __builtin_amdgcn_s_barrier()
; #define PG8_SCHED __builtin_amdgcn_sched_barrier(0)
; template <class Epi, class Sched, bool ALIGN_EPI = false, bool SP2 = false>
; __device__ __forceinline__ void gemm_phase(PG8_LAS unsigned char* lds, const Gemm g, const Sched& S, const Epi& E) {
;     ...
;         for (int t = 0; t < nt; t += 2) {
;     ...
;             PG8_LDA(At, 1, 1); PG8_STAGE(PG8_SB(1, 0), b3, voffB); PG8_STAGE(PG8_SB(1, 1), b3 + hstep, voffB); PG8_STAGE(PG8_SA(1, 0), a3, voffA);
;             PG8_WAIT_V(8); PG8_WAIT_L(0); PG8_BAR; PG8_MMA(1, 0, At, B0); PG8_MMA(1, 1, At, B1); PG8_BAR; PG8_SCHED;
	s_add_i32 s30, s69, s35
	s_mov_b32 m0, s30
	ds_read_b128 v[190:193], v155 offset:49152
	ds_read_b128 v[194:197], v155 offset:50176
	ds_read_b128 v[198:201], v155 offset:51200
	ds_read_b128 v[202:205], v155 offset:52224
	ds_read_b128 v[206:209], v155 offset:53248
	ds_read_b128 v[210:213], v155 offset:54272
	ds_read_b128 v[214:217], v155 offset:55296
	ds_read_b128 v[218:221], v155 offset:56320
	s_add_u32 s98, s28, s12
	s_addc_u32 s99, s29, s13
	global_load_lds_dwordx4 v134, s[98:99]
	s_add_i32 m0, s30, 0x2000
	s_add_u32 s28, s28, 0xb0080
	v_lshl_add_u64 v[148:149], v[222:223], 0, s[12:13]
	s_addc_u32 s29, s29, 0
	s_add_i32 s30, s70, s35
	global_load_lds_dwordx4 v[148:149], off
	s_mov_b32 m0, s30
	s_nop 0
	global_load_lds_dwordx4 v134, s[28:29]
	s_add_i32 m0, s30, 0x2000
	s_nop 0
	global_load_lds_dwordx4 v138, s[28:29]
	v_lshl_add_u64 v[148:149], v[224:225], 0, s[12:13]
	s_mov_b32 m0, s41
	s_nop 0
	global_load_lds_dwordx4 v[148:149], off
	v_lshl_add_u64 v[148:149], v[226:227], 0, s[12:13]
	s_mov_b32 m0, s42
	s_nop 0
	global_load_lds_dwordx4 v[148:149], off
	s_waitcnt vmcnt(8)
	s_waitcnt lgkmcnt(0)
	s_barrier
	s_setprio 1
	s_waitcnt lgkmcnt(0)
	v_mfma_f32_16x16x32_bf16 v[62:65], v[156:159], v[190:193], v[62:65]
	v_mfma_f32_16x16x32_bf16 v[58:61], v[164:167], v[190:193], v[58:61]
	v_mfma_f32_16x16x32_bf16 v[54:57], v[156:159], v[198:201], v[54:57]
	v_mfma_f32_16x16x32_bf16 v[46:49], v[164:167], v[198:201], v[46:49]
	v_mfma_f32_16x16x32_bf16 v[38:41], v[156:159], v[206:209], v[38:41]
	v_mfma_f32_16x16x32_bf16 v[30:33], v[164:167], v[206:209], v[30:33]
	v_mfma_f32_16x16x32_bf16 v[22:25], v[156:159], v[214:217], v[22:25]
	v_mfma_f32_16x16x32_bf16 v[14:17], v[164:167], v[214:217], v[14:17]
	v_mfma_f32_16x16x32_bf16 v[62:65], v[160:163], v[194:197], v[62:65]
	v_mfma_f32_16x16x32_bf16 v[58:61], v[168:171], v[194:197], v[58:61]
	v_mfma_f32_16x16x32_bf16 v[54:57], v[160:163], v[202:205], v[54:57]
	v_mfma_f32_16x16x32_bf16 v[46:49], v[168:171], v[202:205], v[46:49]
	v_mfma_f32_16x16x32_bf16 v[38:41], v[160:163], v[210:213], v[38:41]
	v_mfma_f32_16x16x32_bf16 v[30:33], v[168:171], v[210:213], v[30:33]
	v_mfma_f32_16x16x32_bf16 v[22:25], v[160:163], v[218:221], v[22:25]
	v_mfma_f32_16x16x32_bf16 v[14:17], v[168:171], v[218:221], v[14:17]
	s_setprio 0
	s_setprio 1
	v_mfma_f32_16x16x32_bf16 v[50:53], v[172:175], v[190:193], v[50:53]
	v_mfma_f32_16x16x32_bf16 v[42:45], v[182:185], v[190:193], v[42:45]
	v_mfma_f32_16x16x32_bf16 v[34:37], v[172:175], v[198:201], v[34:37]
	v_mfma_f32_16x16x32_bf16 v[26:29], v[182:185], v[198:201], v[26:29]
	v_mfma_f32_16x16x32_bf16 v[18:21], v[172:175], v[206:209], v[18:21]
	v_mfma_f32_16x16x32_bf16 v[10:13], v[182:185], v[206:209], v[10:13]
	v_mfma_f32_16x16x32_bf16 v[6:9], v[172:175], v[214:217], v[6:9]
	v_mfma_f32_16x16x32_bf16 v[2:5], v[182:185], v[214:217], v[2:5]
	v_mfma_f32_16x16x32_bf16 v[50:53], v[176:179], v[194:197], v[50:53]
	v_mfma_f32_16x16x32_bf16 v[42:45], v[186:189], v[194:197], v[42:45]
	v_mfma_f32_16x16x32_bf16 v[34:37], v[176:179], v[202:205], v[34:37]
	v_mfma_f32_16x16x32_bf16 v[26:29], v[186:189], v[202:205], v[26:29]
	v_mfma_f32_16x16x32_bf16 v[18:21], v[176:179], v[210:213], v[18:21]
	v_mfma_f32_16x16x32_bf16 v[10:13], v[186:189], v[210:213], v[10:13]
	v_mfma_f32_16x16x32_bf16 v[6:9], v[176:179], v[218:221], v[6:9]
	v_mfma_f32_16x16x32_bf16 v[2:5], v[186:189], v[218:221], v[2:5]
	s_setprio 0
	s_barrier
	s_add_i32 s68, s68, 2
	s_add_u32 s26, s26, 0x100
	s_addc_u32 s27, s27, 0
	s_add_u32 s66, s66, 0x100
	s_addc_u32 s67, s67, 0
	s_cmp_gt_u32 s68, 41
	s_cbranch_scc0 .LBB0_973
	s_and_b64 vcc, exec, s[14:15]
	s_cbranch_vccz .LBB0_976
	s_barrier

; #define PG8_STAGE(bufoff, gbase, voff) do { _Pragma("unroll") for (int _i = 0; _i < 2; ++_i) \
;         __builtin_amdgcn_global_load_lds((const unsigned*)((const char*)(gbase) + (voff)[_i]), (PG8_LAS unsigned*)(lds + (bufoff) + ldsw + _i * 8192), 16, 0, 0); } while (0)
; #define PG8_LDA(dst, b, h) do { _Pragma("unroll") for (int m = 0; m < 4; ++m) _Pragma("unroll") for (int k = 0; k < 2; ++k) dst[m][k] = *(const PG8_LAS bf16x8*)(lds + PG8_SA(b, h) + aoff + m * 2048 + k * 1024); } while (0)
; #define PG8_LDB(dst, b, h) do { _Pragma("unroll") for (int n = 0; n < 2; ++n) _Pragma("unroll") for (int k = 0; k < 2; ++k) dst[n][k] = *(const PG8_LAS bf16x8*)(lds + PG8_SB(b, h) + boff + n * 2048 + k * 1024); } while (0)
; #define PG8_MMA(ai, bj, At, Bt) do { __builtin_amdgcn_s_setprio(1); _Pragma("unroll") for (int m = 0; m < 4; ++m) _Pragma("unroll") for (int n = 0; n < 2; ++n) _Pragma("unroll") for (int k = 0; k < 2; ++k) \
;         acc[ai][bj][m][n] = __builtin_amdgcn_mfma_f32_16x16x32_bf16(Bt[n][k], At[m][k], acc[ai][bj][m][n], 0, 0, 0); __builtin_amdgcn_s_setprio(0); } while (0)
; #define PG8_WAIT_V(n) asm volatile("s_waitcnt vmcnt(" #n ")" ::: "memory")
; #define PG8_WAIT_L(n) asm volatile("s_waitcnt lgkmcnt(" #n ")" ::: "memory")
; template <class Epi, class Sched, bool ALIGN_EPI = false, bool SP2 = false>
; __device__ __forceinline__ void gemm_phase(PG8_LAS unsigned char* lds, const Gemm g, const Sched& S, const Epi& E) {
;     ...
;             const bool last = (t == nt - 2);
;             const char* a1 = cA + (size_t)(t + 1) * kstep;
;             const char* a2 = last ? nA : cA + (size_t)(t + 2) * kstep; const char* b2 = last ? nB : cB + (size_t)(t + 2) * kstep;
;             const char* a3 = a2 + kstep; const char* b3 = b2 + kstep;
;             if (last && has_next) S.a_ready(nxt);
;             if constexpr (SP2) {
;             PG8_LDB(B0, 0, 0); PG8_LDB(B1, 0, 1); PG8_SCHED; PG8_LDA(At, 0, 0); PG8_STAGE(PG8_SA(1, 1), a1 + hstep, voffA);
;             PG8_WAIT_V(8); PG8_WAIT_L(0); PG8_BAR; PG8_MMA(0, 0, At, B0); PG8_MMA(0, 1, At, B1); PG8_BAR; PG8_SCHED;
;             PG8_LDA(At, 0, 1); PG8_STAGE(PG8_SB(0, 0), b2, voffB); PG8_STAGE(PG8_SB(0, 1), b2 + hstep, voffB); PG8_STAGE(PG8_SA(0, 0), a2, voffA);
;             PG8_WAIT_V(8); PG8_WAIT_L(0); PG8_BAR; PG8_MMA(1, 0, At, B0); PG8_MMA(1, 1, At, B1); PG8_BAR; PG8_SCHED;
.LBB0_1116:
	ds_read_b128 v[152:155], v146
	ds_read_b128 v[156:159], v146 offset:1024
	ds_read_b128 v[160:163], v146 offset:2048
	ds_read_b128 v[164:167], v146 offset:3072
	ds_read_b128 v[168:171], v147
	ds_read_b128 v[172:175], v147 offset:1024
	ds_read_b128 v[176:179], v147 offset:2048
	ds_read_b128 v[182:185], v147 offset:3072
	s_add_u32 s14, s12, 0xf3f50080
	s_addc_u32 s15, s13, -1
	s_cmp_lg_u32 s28, 40
	s_cselect_b32 s14, s14, 0
	s_cselect_b32 s15, s15, 0
	s_add_u32 s16, s8, s14
	s_addc_u32 s17, s9, s15
	s_add_u32 s14, s4, s14
	s_addc_u32 s15, s5, s15
	s_mov_b32 m0, s29
	v_lshl_add_u64 v[218:219], v[140:141], 0, s[12:13]
	ds_read_b128 v[186:189], v148
	ds_read_b128 v[190:193], v148 offset:1024
	ds_read_b128 v[194:197], v148 offset:2048
	ds_read_b128 v[198:201], v148 offset:3072
	ds_read_b128 v[202:205], v148 offset:4096
	ds_read_b128 v[206:209], v148 offset:5120
	ds_read_b128 v[210:213], v148 offset:6144
	ds_read_b128 v[214:217], v148 offset:7168
	global_load_lds_dwordx4 v[218:219], off
	v_lshl_add_u64 v[218:219], v[142:143], 0, s[12:13]
	s_mov_b32 m0, s30
	s_nop 0
	global_load_lds_dwordx4 v[218:219], off
	s_waitcnt vmcnt(8)
	s_waitcnt lgkmcnt(0)
	s_barrier
	s_setprio 1
	s_waitcnt lgkmcnt(0)
	v_mfma_f32_16x16x32_bf16 v[126:129], v[152:155], v[186:189], v[126:129]
	v_mfma_f32_16x16x32_bf16 v[122:125], v[160:163], v[186:189], v[122:125]
	v_mfma_f32_16x16x32_bf16 v[118:121], v[152:155], v[194:197], v[118:121]
	v_mfma_f32_16x16x32_bf16 v[110:113], v[160:163], v[194:197], v[110:113]
	v_mfma_f32_16x16x32_bf16 v[102:105], v[152:155], v[202:205], v[102:105]
	v_mfma_f32_16x16x32_bf16 v[94:97], v[160:163], v[202:205], v[94:97]
	v_mfma_f32_16x16x32_bf16 v[86:89], v[152:155], v[210:213], v[86:89]
	v_mfma_f32_16x16x32_bf16 v[78:81], v[160:163], v[210:213], v[78:81]
	v_mfma_f32_16x16x32_bf16 v[126:129], v[156:159], v[190:193], v[126:129]
	v_mfma_f32_16x16x32_bf16 v[122:125], v[164:167], v[190:193], v[122:125]
	v_mfma_f32_16x16x32_bf16 v[118:121], v[156:159], v[198:201], v[118:121]
	v_mfma_f32_16x16x32_bf16 v[110:113], v[164:167], v[198:201], v[110:113]
	v_mfma_f32_16x16x32_bf16 v[102:105], v[156:159], v[206:209], v[102:105]
	v_mfma_f32_16x16x32_bf16 v[94:97], v[164:167], v[206:209], v[94:97]
	v_mfma_f32_16x16x32_bf16 v[86:89], v[156:159], v[214:217], v[86:89]
	v_mfma_f32_16x16x32_bf16 v[78:81], v[164:167], v[214:217], v[78:81]
	s_setprio 0
	s_setprio 1
	v_mfma_f32_16x16x32_bf16 v[114:117], v[168:171], v[186:189], v[114:117]
	v_mfma_f32_16x16x32_bf16 v[106:109], v[176:179], v[186:189], v[106:109]
	v_mfma_f32_16x16x32_bf16 v[98:101], v[168:171], v[194:197], v[98:101]
	v_mfma_f32_16x16x32_bf16 v[90:93], v[176:179], v[194:197], v[90:93]
	v_mfma_f32_16x16x32_bf16 v[82:85], v[168:171], v[202:205], v[82:85]
	v_mfma_f32_16x16x32_bf16 v[74:77], v[176:179], v[202:205], v[74:77]
	v_mfma_f32_16x16x32_bf16 v[70:73], v[168:171], v[210:213], v[70:73]
	v_mfma_f32_16x16x32_bf16 v[66:69], v[176:179], v[210:213], v[66:69]
	v_mfma_f32_16x16x32_bf16 v[114:117], v[172:175], v[190:193], v[114:117]
	v_mfma_f32_16x16x32_bf16 v[106:109], v[182:185], v[190:193], v[106:109]
	v_mfma_f32_16x16x32_bf16 v[98:101], v[172:175], v[198:201], v[98:101]
	v_mfma_f32_16x16x32_bf16 v[90:93], v[182:185], v[198:201], v[90:93]
	v_mfma_f32_16x16x32_bf16 v[82:85], v[172:175], v[206:209], v[82:85]
	v_mfma_f32_16x16x32_bf16 v[74:77], v[182:185], v[206:209], v[74:77]
	v_mfma_f32_16x16x32_bf16 v[70:73], v[172:175], v[214:217], v[70:73]
	v_mfma_f32_16x16x32_bf16 v[66:69], v[182:185], v[214:217], v[66:69]
	s_setprio 0
	s_barrier
	s_mov_b32 m0, s31
	v_lshl_add_u64 v[218:219], s[14:15], 0, v[136:137]
	s_add_u32 s42, s14, 0xb0000
	ds_read_b128 v[186:189], v148 offset:16384
	ds_read_b128 v[190:193], v148 offset:17408
	ds_read_b128 v[194:197], v148 offset:18432
	ds_read_b128 v[198:201], v148 offset:19456
	ds_read_b128 v[202:205], v148 offset:20480
	ds_read_b128 v[206:209], v148 offset:21504
	ds_read_b128 v[210:213], v148 offset:22528
	ds_read_b128 v[214:217], v148 offset:23552
	global_load_lds_dwordx4 v136, s[14:15]
	v_lshl_add_u64 v[220:221], s[14:15], 0, v[132:133]
	s_mov_b32 m0, s34
	s_addc_u32 s43, s15, 0
	global_load_lds_dwordx4 v132, s[14:15]
	s_mov_b32 m0, s35
	v_lshl_add_u64 v[224:225], s[16:17], 0, v[134:135]
	global_load_lds_dwordx4 v136, s[42:43]
	s_mov_b32 m0, s36
	s_nop 0
	global_load_lds_dwordx4 v132, s[42:43]
	v_lshl_add_u64 v[222:223], s[16:17], 0, v[138:139]
	s_mov_b32 m0, s21
	s_nop 0
	global_load_lds_dwordx4 v138, s[16:17]
	s_mov_b32 m0, s22
	s_nop 0
	global_load_lds_dwordx4 v134, s[16:17]
	s_waitcnt vmcnt(8)
	s_waitcnt lgkmcnt(0)
	s_barrier
; #define PG8_STAGE(bufoff, gbase, voff) do { _Pragma("unroll") for (int _i = 0; _i < 2; ++_i) \
;         __builtin_amdgcn_global_load_lds((const unsigned*)((const char*)(gbase) + (voff)[_i]), (PG8_LAS unsigned*)(lds + (bufoff) + ldsw + _i * 8192), 16, 0, 0); } while (0)
; #define PG8_LDA(dst, b, h) do { _Pragma("unroll") for (int m = 0; m < 4; ++m) _Pragma("unroll") for (int k = 0; k < 2; ++k) dst[m][k] = *(const PG8_LAS bf16x8*)(lds + PG8_SA(b, h) + aoff + m * 2048 + k * 1024); } while (0)
; #define PG8_LDB(dst, b, h) do { _Pragma("unroll") for (int n = 0; n < 2; ++n) _Pragma("unroll") for (int k = 0; k < 2; ++k) dst[n][k] = *(const PG8_LAS bf16x8*)(lds + PG8_SB(b, h) + boff + n * 2048 + k * 1024); } while (0)
; #define PG8_MMA(ai, bj, At, Bt) do { __builtin_amdgcn_s_setprio(1); _Pragma("unroll") for (int m = 0; m < 4; ++m) _Pragma("unroll") for (int n = 0; n < 2; ++n) _Pragma("unroll") for (int k = 0; k < 2; ++k) \
;         acc[ai][bj][m][n] = __builtin_amdgcn_mfma_f32_16x16x32_bf16(Bt[n][k], At[m][k], acc[ai][bj][m][n], 0, 0, 0); __builtin_amdgcn_s_setprio(0); } while (0)
; #define PG8_WAIT_V(n) asm volatile("s_waitcnt vmcnt(" #n ")" ::: "memory")
; #define PG8_WAIT_L(n) asm volatile("s_waitcnt lgkmcnt(" #n ")" ::: "memory")
; #define PG8_BAR __builtin_amdgcn_s_barrier()
; #define PG8_SCHED __builtin_amdgcn_sched_barrier(0)
; template <class Epi, class Sched, bool ALIGN_EPI = false, bool SP2 = false>
; __device__ __forceinline__ void gemm_phase(PG8_LAS unsigned char* lds, const Gemm g, const Sched& S, const Epi& E) {
;     ...
;             PG8_WAIT_V(8); PG8_WAIT_L(0); PG8_BAR; PG8_MMA(1, 0, At, B0); PG8_MMA(1, 1, At, B1); PG8_BAR; PG8_SCHED;
;             PG8_LDB(B0, 1, 0); PG8_LDB(B1, 1, 1); PG8_SCHED; PG8_LDA(At, 1, 0); PG8_STAGE(PG8_SA(0, 1), a2 + hstep, voffA);
;             PG8_WAIT_V(8); PG8_WAIT_L(0); PG8_BAR; PG8_MMA(0, 0, At, B0); PG8_MMA(0, 1, At, B1); PG8_BAR; PG8_SCHED;
	s_setprio 1
	s_waitcnt lgkmcnt(0)
	v_mfma_f32_16x16x32_bf16 v[62:65], v[152:155], v[186:189], v[62:65]
	v_mfma_f32_16x16x32_bf16 v[58:61], v[160:163], v[186:189], v[58:61]
	v_mfma_f32_16x16x32_bf16 v[54:57], v[152:155], v[194:197], v[54:57]
	v_mfma_f32_16x16x32_bf16 v[46:49], v[160:163], v[194:197], v[46:49]
	v_mfma_f32_16x16x32_bf16 v[38:41], v[152:155], v[202:205], v[38:41]
	v_mfma_f32_16x16x32_bf16 v[30:33], v[160:163], v[202:205], v[30:33]
	v_mfma_f32_16x16x32_bf16 v[22:25], v[152:155], v[210:213], v[22:25]
	v_mfma_f32_16x16x32_bf16 v[14:17], v[160:163], v[210:213], v[14:17]
	v_mfma_f32_16x16x32_bf16 v[62:65], v[156:159], v[190:193], v[62:65]
	v_mfma_f32_16x16x32_bf16 v[58:61], v[164:167], v[190:193], v[58:61]
	v_mfma_f32_16x16x32_bf16 v[54:57], v[156:159], v[198:201], v[54:57]
	v_mfma_f32_16x16x32_bf16 v[46:49], v[164:167], v[198:201], v[46:49]
	v_mfma_f32_16x16x32_bf16 v[38:41], v[156:159], v[206:209], v[38:41]
	v_mfma_f32_16x16x32_bf16 v[30:33], v[164:167], v[206:209], v[30:33]
	v_mfma_f32_16x16x32_bf16 v[22:25], v[156:159], v[214:217], v[22:25]
	v_mfma_f32_16x16x32_bf16 v[14:17], v[164:167], v[214:217], v[14:17]
	s_setprio 0
	s_setprio 1
	v_mfma_f32_16x16x32_bf16 v[50:53], v[168:171], v[186:189], v[50:53]
	v_mfma_f32_16x16x32_bf16 v[42:45], v[176:179], v[186:189], v[42:45]
	v_mfma_f32_16x16x32_bf16 v[34:37], v[168:171], v[194:197], v[34:37]
	v_mfma_f32_16x16x32_bf16 v[26:29], v[176:179], v[194:197], v[26:29]
	v_mfma_f32_16x16x32_bf16 v[18:21], v[168:171], v[202:205], v[18:21]
	v_mfma_f32_16x16x32_bf16 v[10:13], v[176:179], v[202:205], v[10:13]
	v_mfma_f32_16x16x32_bf16 v[6:9], v[168:171], v[210:213], v[6:9]
	v_mfma_f32_16x16x32_bf16 v[2:5], v[176:179], v[210:213], v[2:5]
	v_mfma_f32_16x16x32_bf16 v[50:53], v[172:175], v[190:193], v[50:53]
	v_mfma_f32_16x16x32_bf16 v[42:45], v[182:185], v[190:193], v[42:45]
	v_mfma_f32_16x16x32_bf16 v[34:37], v[172:175], v[198:201], v[34:37]
	v_mfma_f32_16x16x32_bf16 v[26:29], v[182:185], v[198:201], v[26:29]
	v_mfma_f32_16x16x32_bf16 v[18:21], v[172:175], v[206:209], v[18:21]
	v_mfma_f32_16x16x32_bf16 v[10:13], v[182:185], v[206:209], v[10:13]
	v_mfma_f32_16x16x32_bf16 v[6:9], v[172:175], v[214:217], v[6:9]
	v_mfma_f32_16x16x32_bf16 v[2:5], v[182:185], v[214:217], v[2:5]
	s_setprio 0
	s_barrier
	ds_read_b128 v[152:155], v149
	ds_read_b128 v[156:159], v149 offset:1024
	ds_read_b128 v[160:163], v149 offset:2048
	ds_read_b128 v[164:167], v149 offset:3072
	ds_read_b128 v[168:171], v150
	ds_read_b128 v[172:175], v150 offset:1024
	ds_read_b128 v[176:179], v150 offset:2048
	ds_read_b128 v[182:185], v150 offset:3072
	s_add_u32 s16, s16, 0xb0000
	s_addc_u32 s17, s17, 0
	s_mov_b32 m0, s23
	ds_read_b128 v[186:189], v148 offset:32768
	ds_read_b128 v[190:193], v148 offset:33792
	ds_read_b128 v[194:197], v148 offset:34816
	ds_read_b128 v[198:201], v148 offset:35840
	ds_read_b128 v[202:205], v148 offset:36864
	ds_read_b128 v[206:209], v148 offset:37888
	ds_read_b128 v[210:213], v148 offset:38912
	ds_read_b128 v[214:217], v148 offset:39936
	global_load_lds_dwordx4 v138, s[16:17]
	v_lshl_add_u64 v[226:227], s[16:17], 0, v[134:135]
	s_mov_b32 m0, s24
	s_nop 0
	global_load_lds_dwordx4 v134, s[16:17]
	s_waitcnt vmcnt(8)
	s_waitcnt lgkmcnt(0)
	s_barrier
	s_setprio 1
	s_waitcnt lgkmcnt(0)
	v_mfma_f32_16x16x32_bf16 v[126:129], v[152:155], v[186:189], v[126:129]
	v_mfma_f32_16x16x32_bf16 v[122:125], v[160:163], v[186:189], v[122:125]
	v_mfma_f32_16x16x32_bf16 v[118:121], v[152:155], v[194:197], v[118:121]
	v_mfma_f32_16x16x32_bf16 v[110:113], v[160:163], v[194:197], v[110:113]
	v_mfma_f32_16x16x32_bf16 v[102:105], v[152:155], v[202:205], v[102:105]
	v_mfma_f32_16x16x32_bf16 v[94:97], v[160:163], v[202:205], v[94:97]
	v_mfma_f32_16x16x32_bf16 v[86:89], v[152:155], v[210:213], v[86:89]
	v_mfma_f32_16x16x32_bf16 v[78:81], v[160:163], v[210:213], v[78:81]
	v_mfma_f32_16x16x32_bf16 v[126:129], v[156:159], v[190:193], v[126:129]
	v_mfma_f32_16x16x32_bf16 v[122:125], v[164:167], v[190:193], v[122:125]
	v_mfma_f32_16x16x32_bf16 v[118:121], v[156:159], v[198:201], v[118:121]
	v_mfma_f32_16x16x32_bf16 v[110:113], v[164:167], v[198:201], v[110:113]
	v_mfma_f32_16x16x32_bf16 v[102:105], v[156:159], v[206:209], v[102:105]
	v_mfma_f32_16x16x32_bf16 v[94:97], v[164:167], v[206:209], v[94:97]
	v_mfma_f32_16x16x32_bf16 v[86:89], v[156:159], v[214:217], v[86:89]
	v_mfma_f32_16x16x32_bf16 v[78:81], v[164:167], v[214:217], v[78:81]
	s_setprio 0
	s_setprio 1
	v_mfma_f32_16x16x32_bf16 v[114:117], v[168:171], v[186:189], v[114:117]
	v_mfma_f32_16x16x32_bf16 v[106:109], v[176:179], v[186:189], v[106:109]
	v_mfma_f32_16x16x32_bf16 v[98:101], v[168:171], v[194:197], v[98:101]
	v_mfma_f32_16x16x32_bf16 v[90:93], v[176:179], v[194:197], v[90:93]
	v_mfma_f32_16x16x32_bf16 v[82:85], v[168:171], v[202:205], v[82:85]
	v_mfma_f32_16x16x32_bf16 v[74:77], v[176:179], v[202:205], v[74:77]
	v_mfma_f32_16x16x32_bf16 v[70:73], v[168:171], v[210:213], v[70:73]
	v_mfma_f32_16x16x32_bf16 v[66:69], v[176:179], v[210:213], v[66:69]
	v_mfma_f32_16x16x32_bf16 v[114:117], v[172:175], v[190:193], v[114:117]
	v_mfma_f32_16x16x32_bf16 v[106:109], v[182:185], v[190:193], v[106:109]
	v_mfma_f32_16x16x32_bf16 v[98:101], v[172:175], v[198:201], v[98:101]
	v_mfma_f32_16x16x32_bf16 v[90:93], v[182:185], v[198:201], v[90:93]
	v_mfma_f32_16x16x32_bf16 v[82:85], v[172:175], v[206:209], v[82:85]
	v_mfma_f32_16x16x32_bf16 v[74:77], v[182:185], v[206:209], v[74:77]
	v_mfma_f32_16x16x32_bf16 v[70:73], v[172:175], v[214:217], v[70:73]
	v_mfma_f32_16x16x32_bf16 v[66:69], v[182:185], v[214:217], v[66:69]
	s_setprio 0
	s_barrier
; #define PG8_STAGE(bufoff, gbase, voff) do { _Pragma("unroll") for (int _i = 0; _i < 2; ++_i) \
;         __builtin_amdgcn_global_load_lds((const unsigned*)((const char*)(gbase) + (voff)[_i]), (PG8_LAS unsigned*)(lds + (bufoff) + ldsw + _i * 8192), 16, 0, 0); } while (0)
; #define PG8_LDA(dst, b, h) do { _Pragma("unroll") for (int m = 0; m < 4; ++m) _Pragma("unroll") for (int k = 0; k < 2; ++k) dst[m][k] = *(const PG8_LAS bf16x8*)(lds + PG8_SA(b, h) + aoff + m * 2048 + k * 1024); } while (0)
; #define PG8_MMA(ai, bj, At, Bt) do { __builtin_amdgcn_s_setprio(1); _Pragma("unroll") for (int m = 0; m < 4; ++m) _Pragma("unroll") for (int n = 0; n < 2; ++n) _Pragma("unroll") for (int k = 0; k < 2; ++k) \
;         acc[ai][bj][m][n] = __builtin_amdgcn_mfma_f32_16x16x32_bf16(Bt[n][k], At[m][k], acc[ai][bj][m][n], 0, 0, 0); __builtin_amdgcn_s_setprio(0); } while (0)
; #define PG8_WAIT_V(n) asm volatile("s_waitcnt vmcnt(" #n ")" ::: "memory")
; #define PG8_WAIT_L(n) asm volatile("s_waitcnt lgkmcnt(" #n ")" ::: "memory")
; #define PG8_BAR __builtin_amdgcn_s_barrier()
; #define PG8_SCHED __builtin_amdgcn_sched_barrier(0)
; template <class Epi, class Sched, bool ALIGN_EPI = false, bool SP2 = false>
; __device__ __forceinline__ void gemm_phase(PG8_LAS unsigned char* lds, const Gemm g, const Sched& S, const Epi& E) {
;     ...
;             PG8_LDA(At, 1, 1); PG8_STAGE(PG8_SB(1, 0), b3, voffB); PG8_STAGE(PG8_SB(1, 1), b3 + hstep, voffB); PG8_STAGE(PG8_SA(1, 0), a3, voffA);
;             PG8_WAIT_V(8); PG8_WAIT_L(0); PG8_BAR; PG8_MMA(1, 0, At, B0); PG8_MMA(1, 1, At, B1); PG8_BAR; PG8_SCHED;
	s_mov_b32 m0, s37
	v_lshl_add_u64 v[218:219], v[218:219], 0, s[10:11]
	s_add_u32 s14, s14, 0xb0080
	ds_read_b128 v[186:189], v148 offset:49152
	ds_read_b128 v[190:193], v148 offset:50176
	ds_read_b128 v[194:197], v148 offset:51200
	ds_read_b128 v[198:201], v148 offset:52224
	ds_read_b128 v[202:205], v148 offset:53248
	ds_read_b128 v[206:209], v148 offset:54272
	ds_read_b128 v[210:213], v148 offset:55296
	ds_read_b128 v[214:217], v148 offset:56320
	global_load_lds_dwordx4 v[218:219], off
	v_lshl_add_u64 v[218:219], v[220:221], 0, s[10:11]
	s_mov_b32 m0, s38
	s_addc_u32 s15, s15, 0
	global_load_lds_dwordx4 v[218:219], off
	s_mov_b32 m0, s39
	s_nop 0
	global_load_lds_dwordx4 v136, s[14:15]
	s_mov_b32 m0, s40
	s_nop 0
	global_load_lds_dwordx4 v132, s[14:15]
	v_lshl_add_u64 v[218:219], v[222:223], 0, s[10:11]
	s_mov_b32 m0, s26
	s_nop 0
	global_load_lds_dwordx4 v[218:219], off
	v_lshl_add_u64 v[218:219], v[224:225], 0, s[10:11]
	s_mov_b32 m0, s27
	s_nop 0
	global_load_lds_dwordx4 v[218:219], off
	s_waitcnt vmcnt(8)
	s_waitcnt lgkmcnt(0)
	s_barrier
	s_setprio 1
	s_waitcnt lgkmcnt(0)
	v_mfma_f32_16x16x32_bf16 v[62:65], v[152:155], v[186:189], v[62:65]
	v_mfma_f32_16x16x32_bf16 v[58:61], v[160:163], v[186:189], v[58:61]
	v_mfma_f32_16x16x32_bf16 v[54:57], v[152:155], v[194:197], v[54:57]
	v_mfma_f32_16x16x32_bf16 v[46:49], v[160:163], v[194:197], v[46:49]
	v_mfma_f32_16x16x32_bf16 v[38:41], v[152:155], v[202:205], v[38:41]
	v_mfma_f32_16x16x32_bf16 v[30:33], v[160:163], v[202:205], v[30:33]
	v_mfma_f32_16x16x32_bf16 v[22:25], v[152:155], v[210:213], v[22:25]
	v_mfma_f32_16x16x32_bf16 v[14:17], v[160:163], v[210:213], v[14:17]
	v_mfma_f32_16x16x32_bf16 v[62:65], v[156:159], v[190:193], v[62:65]
	v_mfma_f32_16x16x32_bf16 v[58:61], v[164:167], v[190:193], v[58:61]
	v_mfma_f32_16x16x32_bf16 v[54:57], v[156:159], v[198:201], v[54:57]
	v_mfma_f32_16x16x32_bf16 v[46:49], v[164:167], v[198:201], v[46:49]
	v_mfma_f32_16x16x32_bf16 v[38:41], v[156:159], v[206:209], v[38:41]
	v_mfma_f32_16x16x32_bf16 v[30:33], v[164:167], v[206:209], v[30:33]
	v_mfma_f32_16x16x32_bf16 v[22:25], v[156:159], v[214:217], v[22:25]
	v_mfma_f32_16x16x32_bf16 v[14:17], v[164:167], v[214:217], v[14:17]
	s_setprio 0
	s_setprio 1
	v_mfma_f32_16x16x32_bf16 v[50:53], v[168:171], v[186:189], v[50:53]
	v_mfma_f32_16x16x32_bf16 v[42:45], v[176:179], v[186:189], v[42:45]
	v_mfma_f32_16x16x32_bf16 v[34:37], v[168:171], v[194:197], v[34:37]
	v_mfma_f32_16x16x32_bf16 v[26:29], v[176:179], v[194:197], v[26:29]
	v_mfma_f32_16x16x32_bf16 v[18:21], v[168:171], v[202:205], v[18:21]
	v_mfma_f32_16x16x32_bf16 v[10:13], v[176:179], v[202:205], v[10:13]
	v_mfma_f32_16x16x32_bf16 v[6:9], v[168:171], v[210:213], v[6:9]
	v_mfma_f32_16x16x32_bf16 v[2:5], v[176:179], v[210:213], v[2:5]
	v_mfma_f32_16x16x32_bf16 v[50:53], v[172:175], v[190:193], v[50:53]
	v_mfma_f32_16x16x32_bf16 v[42:45], v[182:185], v[190:193], v[42:45]
	v_mfma_f32_16x16x32_bf16 v[34:37], v[172:175], v[198:201], v[34:37]
	v_mfma_f32_16x16x32_bf16 v[26:29], v[182:185], v[198:201], v[26:29]
	v_mfma_f32_16x16x32_bf16 v[18:21], v[172:175], v[206:209], v[18:21]
	v_mfma_f32_16x16x32_bf16 v[10:13], v[182:185], v[206:209], v[10:13]
	v_mfma_f32_16x16x32_bf16 v[6:9], v[172:175], v[214:217], v[6:9]
	v_mfma_f32_16x16x32_bf16 v[2:5], v[182:185], v[214:217], v[2:5]
	s_setprio 0
	s_barrier
	s_add_i32 s28, s28, 2
	s_add_u32 s12, s12, 0x100
	s_addc_u32 s13, s13, 0
	s_cmp_gt_u32 s28, 41
	s_cbranch_scc0 .LBB0_1116
	s_cmpk_lt_u32 s19, 0x100
	s_cbranch_scc0 .LBB0_1119
	s_barrier

; #define PG8_STAGE(bufoff, gbase, voff) do { _Pragma("unroll") for (int _i = 0; _i < 2; ++_i) \
;         __builtin_amdgcn_global_load_lds((const unsigned*)((const char*)(gbase) + (voff)[_i]), (PG8_LAS unsigned*)(lds + (bufoff) + ldsw + _i * 8192), 16, 0, 0); } while (0)
; #define PG8_LDA(dst, b, h) do { _Pragma("unroll") for (int m = 0; m < 4; ++m) _Pragma("unroll") for (int k = 0; k < 2; ++k) dst[m][k] = *(const PG8_LAS bf16x8*)(lds + PG8_SA(b, h) + aoff + m * 2048 + k * 1024); } while (0)
; #define PG8_LDB(dst, b, h) do { _Pragma("unroll") for (int n = 0; n < 2; ++n) _Pragma("unroll") for (int k = 0; k < 2; ++k) dst[n][k] = *(const PG8_LAS bf16x8*)(lds + PG8_SB(b, h) + boff + n * 2048 + k * 1024); } while (0)
; #define PG8_MMA(ai, bj, At, Bt) do { __builtin_amdgcn_s_setprio(1); _Pragma("unroll") for (int m = 0; m < 4; ++m) _Pragma("unroll") for (int n = 0; n < 2; ++n) _Pragma("unroll") for (int k = 0; k < 2; ++k) \
;         acc[ai][bj][m][n] = __builtin_amdgcn_mfma_f32_16x16x32_bf16(Bt[n][k], At[m][k], acc[ai][bj][m][n], 0, 0, 0); __builtin_amdgcn_s_setprio(0); } while (0)
; #define PG8_WAIT_V(n) asm volatile("s_waitcnt vmcnt(" #n ")" ::: "memory")
; #define PG8_WAIT_L(n) asm volatile("s_waitcnt lgkmcnt(" #n ")" ::: "memory")
; template <class Epi, class Sched, bool ALIGN_EPI = false, bool SP2 = false>
; __device__ __forceinline__ void gemm_phase(PG8_LAS unsigned char* lds, const Gemm g, const Sched& S, const Epi& E) {
;     ...
;             const bool last = (t == nt - 2);
;             const char* a1 = cA + (size_t)(t + 1) * kstep;
;             const char* a2 = last ? nA : cA + (size_t)(t + 2) * kstep; const char* b2 = last ? nB : cB + (size_t)(t + 2) * kstep;
;             const char* a3 = a2 + kstep; const char* b3 = b2 + kstep;
;             if (last && has_next) S.a_ready(nxt);
;             if constexpr (SP2) {
;             PG8_LDB(B0, 0, 0); PG8_LDB(B1, 0, 1); PG8_SCHED; PG8_LDA(At, 0, 0); PG8_STAGE(PG8_SA(1, 1), a1 + hstep, voffA);
;             PG8_WAIT_V(8); PG8_WAIT_L(0); PG8_BAR; PG8_MMA(0, 0, At, B0); PG8_MMA(0, 1, At, B1); PG8_BAR; PG8_SCHED;
;             PG8_LDA(At, 0, 1); PG8_STAGE(PG8_SB(0, 0), b2, voffB); PG8_STAGE(PG8_SB(0, 1), b2 + hstep, voffB); PG8_STAGE(PG8_SA(0, 0), a2, voffA);
;             PG8_WAIT_V(8); PG8_WAIT_L(0); PG8_BAR; PG8_MMA(1, 0, At, B0); PG8_MMA(1, 1, At, B1); PG8_BAR; PG8_SCHED;
.LBB0_1310:
	ds_read_b128 v[148:151], v155
	ds_read_b128 v[158:161], v155 offset:1024
	ds_read_b128 v[162:165], v155 offset:2048
	ds_read_b128 v[166:169], v155 offset:3072
	ds_read_b128 v[170:173], v156
	ds_read_b128 v[174:177], v156 offset:1024
	ds_read_b128 v[182:185], v156 offset:2048
	ds_read_b128 v[186:189], v156 offset:3072
	s_add_u32 s26, s24, 0xfffc0080
	s_addc_u32 s27, s25, -1
	s_cmp_eq_u32 s62, 12
	s_cselect_b32 s29, s17, s27
	s_cselect_b32 s28, s52, s26
	s_cselect_b32 s27, s15, s59
	s_cselect_b32 s26, s53, s58
	s_add_i32 m0, s23, 0xc000
	ds_read_b128 v[190:193], v157
	ds_read_b128 v[194:197], v157 offset:1024
	ds_read_b128 v[198:201], v157 offset:2048
	ds_read_b128 v[202:205], v157 offset:3072
	ds_read_b128 v[206:209], v157 offset:4096
	ds_read_b128 v[210:213], v157 offset:5120
	ds_read_b128 v[214:217], v157 offset:6144
	ds_read_b128 v[218:221], v157 offset:7168
	global_load_lds_dwordx4 v140, s[24:25]
	s_add_i32 m0, s23, 0xe000
	s_nop 0
	global_load_lds_dwordx4 v142, s[24:25]
	s_waitcnt vmcnt(8)
	s_waitcnt lgkmcnt(0)
	s_barrier
	s_setprio 1
	s_waitcnt lgkmcnt(0)
	v_mfma_f32_16x16x32_bf16 v[126:129], v[148:151], v[190:193], v[126:129]
	v_mfma_f32_16x16x32_bf16 v[122:125], v[162:165], v[190:193], v[122:125]
	v_mfma_f32_16x16x32_bf16 v[118:121], v[148:151], v[198:201], v[118:121]
	v_mfma_f32_16x16x32_bf16 v[110:113], v[162:165], v[198:201], v[110:113]
	v_mfma_f32_16x16x32_bf16 v[102:105], v[148:151], v[206:209], v[102:105]
	v_mfma_f32_16x16x32_bf16 v[94:97], v[162:165], v[206:209], v[94:97]
	v_mfma_f32_16x16x32_bf16 v[86:89], v[148:151], v[214:217], v[86:89]
	v_mfma_f32_16x16x32_bf16 v[78:81], v[162:165], v[214:217], v[78:81]
	v_mfma_f32_16x16x32_bf16 v[126:129], v[158:161], v[194:197], v[126:129]
	v_mfma_f32_16x16x32_bf16 v[122:125], v[166:169], v[194:197], v[122:125]
	v_mfma_f32_16x16x32_bf16 v[118:121], v[158:161], v[202:205], v[118:121]
	v_mfma_f32_16x16x32_bf16 v[110:113], v[166:169], v[202:205], v[110:113]
	v_mfma_f32_16x16x32_bf16 v[102:105], v[158:161], v[210:213], v[102:105]
	v_mfma_f32_16x16x32_bf16 v[94:97], v[166:169], v[210:213], v[94:97]
	v_mfma_f32_16x16x32_bf16 v[86:89], v[158:161], v[218:221], v[86:89]
	v_mfma_f32_16x16x32_bf16 v[78:81], v[166:169], v[218:221], v[78:81]
	s_setprio 0
	s_setprio 1
	v_mfma_f32_16x16x32_bf16 v[114:117], v[170:173], v[190:193], v[114:117]
	v_mfma_f32_16x16x32_bf16 v[106:109], v[182:185], v[190:193], v[106:109]
	v_mfma_f32_16x16x32_bf16 v[98:101], v[170:173], v[198:201], v[98:101]
	v_mfma_f32_16x16x32_bf16 v[90:93], v[182:185], v[198:201], v[90:93]
	v_mfma_f32_16x16x32_bf16 v[82:85], v[170:173], v[206:209], v[82:85]
	v_mfma_f32_16x16x32_bf16 v[74:77], v[182:185], v[206:209], v[74:77]
	v_mfma_f32_16x16x32_bf16 v[70:73], v[170:173], v[214:217], v[70:73]
	v_mfma_f32_16x16x32_bf16 v[66:69], v[182:185], v[214:217], v[66:69]
	v_mfma_f32_16x16x32_bf16 v[114:117], v[174:177], v[194:197], v[114:117]
	v_mfma_f32_16x16x32_bf16 v[106:109], v[186:189], v[194:197], v[106:109]
	v_mfma_f32_16x16x32_bf16 v[98:101], v[174:177], v[202:205], v[98:101]
	v_mfma_f32_16x16x32_bf16 v[90:93], v[186:189], v[202:205], v[90:93]
	v_mfma_f32_16x16x32_bf16 v[82:85], v[174:177], v[210:213], v[82:85]
	v_mfma_f32_16x16x32_bf16 v[74:77], v[186:189], v[210:213], v[74:77]
	v_mfma_f32_16x16x32_bf16 v[70:73], v[174:177], v[218:221], v[70:73]
	v_mfma_f32_16x16x32_bf16 v[66:69], v[186:189], v[218:221], v[66:69]
	s_setprio 0
	s_barrier
	s_add_i32 s63, s43, s30
	s_mov_b32 m0, s63
	ds_read_b128 v[190:193], v157 offset:16384
	ds_read_b128 v[194:197], v157 offset:17408
	ds_read_b128 v[198:201], v157 offset:18432
	ds_read_b128 v[202:205], v157 offset:19456
	ds_read_b128 v[206:209], v157 offset:20480
	ds_read_b128 v[210:213], v157 offset:21504
	ds_read_b128 v[214:217], v157 offset:22528
	ds_read_b128 v[218:221], v157 offset:23552
	global_load_lds_dwordx4 v136, s[26:27]
	s_add_i32 m0, s63, 0x2000
	s_add_u32 s64, s26, 0x40000
	v_lshl_add_u64 v[222:223], s[26:27], 0, v[132:133]
	s_addc_u32 s65, s27, 0
	s_add_i32 s63, s47, s30
	global_load_lds_dwordx4 v132, s[26:27]
	s_mov_b32 m0, s63
	v_lshl_add_u64 v[226:227], s[28:29], 0, v[134:135]
	global_load_lds_dwordx4 v136, s[64:65]
	s_add_i32 m0, s63, 0x2000
	s_nop 0
	global_load_lds_dwordx4 v132, s[64:65]
	v_lshl_add_u64 v[224:225], s[28:29], 0, v[138:139]
	s_mov_b32 m0, s23
	s_nop 0
	global_load_lds_dwordx4 v138, s[28:29]
	s_mov_b32 m0, s35
	s_nop 0
	global_load_lds_dwordx4 v134, s[28:29]
	s_waitcnt vmcnt(8)
	s_waitcnt lgkmcnt(0)
	s_barrier
	s_setprio 1
	s_waitcnt lgkmcnt(0)
	v_mfma_f32_16x16x32_bf16 v[62:65], v[148:151], v[190:193], v[62:65]
	v_mfma_f32_16x16x32_bf16 v[58:61], v[162:165], v[190:193], v[58:61]
	v_mfma_f32_16x16x32_bf16 v[54:57], v[148:151], v[198:201], v[54:57]
	v_mfma_f32_16x16x32_bf16 v[46:49], v[162:165], v[198:201], v[46:49]
	v_mfma_f32_16x16x32_bf16 v[38:41], v[148:151], v[206:209], v[38:41]
	v_mfma_f32_16x16x32_bf16 v[30:33], v[162:165], v[206:209], v[30:33]
	v_mfma_f32_16x16x32_bf16 v[22:25], v[148:151], v[214:217], v[22:25]
	v_mfma_f32_16x16x32_bf16 v[14:17], v[162:165], v[214:217], v[14:17]
	v_mfma_f32_16x16x32_bf16 v[62:65], v[158:161], v[194:197], v[62:65]
	v_mfma_f32_16x16x32_bf16 v[58:61], v[166:169], v[194:197], v[58:61]
	v_mfma_f32_16x16x32_bf16 v[54:57], v[158:161], v[202:205], v[54:57]
	v_mfma_f32_16x16x32_bf16 v[46:49], v[166:169], v[202:205], v[46:49]
	v_mfma_f32_16x16x32_bf16 v[38:41], v[158:161], v[210:213], v[38:41]
	v_mfma_f32_16x16x32_bf16 v[30:33], v[166:169], v[210:213], v[30:33]
	v_mfma_f32_16x16x32_bf16 v[22:25], v[158:161], v[218:221], v[22:25]
	v_mfma_f32_16x16x32_bf16 v[14:17], v[166:169], v[218:221], v[14:17]
	s_setprio 0
	s_setprio 1
	v_mfma_f32_16x16x32_bf16 v[50:53], v[170:173], v[190:193], v[50:53]
	v_mfma_f32_16x16x32_bf16 v[42:45], v[182:185], v[190:193], v[42:45]
	v_mfma_f32_16x16x32_bf16 v[34:37], v[170:173], v[198:201], v[34:37]
	v_mfma_f32_16x16x32_bf16 v[26:29], v[182:185], v[198:201], v[26:29]
	v_mfma_f32_16x16x32_bf16 v[18:21], v[170:173], v[206:209], v[18:21]
	v_mfma_f32_16x16x32_bf16 v[10:13], v[182:185], v[206:209], v[10:13]
	v_mfma_f32_16x16x32_bf16 v[6:9], v[170:173], v[214:217], v[6:9]
	v_mfma_f32_16x16x32_bf16 v[2:5], v[182:185], v[214:217], v[2:5]
	v_mfma_f32_16x16x32_bf16 v[50:53], v[174:177], v[194:197], v[50:53]
	v_mfma_f32_16x16x32_bf16 v[42:45], v[186:189], v[194:197], v[42:45]
	v_mfma_f32_16x16x32_bf16 v[34:37], v[174:177], v[202:205], v[34:37]
	v_mfma_f32_16x16x32_bf16 v[26:29], v[186:189], v[202:205], v[26:29]
	v_mfma_f32_16x16x32_bf16 v[18:21], v[174:177], v[210:213], v[18:21]
	v_mfma_f32_16x16x32_bf16 v[10:13], v[186:189], v[210:213], v[10:13]
	v_mfma_f32_16x16x32_bf16 v[6:9], v[174:177], v[218:221], v[6:9]
	v_mfma_f32_16x16x32_bf16 v[2:5], v[186:189], v[218:221], v[2:5]
	s_setprio 0
	s_barrier
; #define PG8_STAGE(bufoff, gbase, voff) do { _Pragma("unroll") for (int _i = 0; _i < 2; ++_i) \
;         __builtin_amdgcn_global_load_lds((const unsigned*)((const char*)(gbase) + (voff)[_i]), (PG8_LAS unsigned*)(lds + (bufoff) + ldsw + _i * 8192), 16, 0, 0); } while (0)
; #define PG8_LDA(dst, b, h) do { _Pragma("unroll") for (int m = 0; m < 4; ++m) _Pragma("unroll") for (int k = 0; k < 2; ++k) dst[m][k] = *(const PG8_LAS bf16x8*)(lds + PG8_SA(b, h) + aoff + m * 2048 + k * 1024); } while (0)
; #define PG8_LDB(dst, b, h) do { _Pragma("unroll") for (int n = 0; n < 2; ++n) _Pragma("unroll") for (int k = 0; k < 2; ++k) dst[n][k] = *(const PG8_LAS bf16x8*)(lds + PG8_SB(b, h) + boff + n * 2048 + k * 1024); } while (0)
; #define PG8_MMA(ai, bj, At, Bt) do { __builtin_amdgcn_s_setprio(1); _Pragma("unroll") for (int m = 0; m < 4; ++m) _Pragma("unroll") for (int n = 0; n < 2; ++n) _Pragma("unroll") for (int k = 0; k < 2; ++k) \
;         acc[ai][bj][m][n] = __builtin_amdgcn_mfma_f32_16x16x32_bf16(Bt[n][k], At[m][k], acc[ai][bj][m][n], 0, 0, 0); __builtin_amdgcn_s_setprio(0); } while (0)
; #define PG8_WAIT_V(n) asm volatile("s_waitcnt vmcnt(" #n ")" ::: "memory")
; #define PG8_WAIT_L(n) asm volatile("s_waitcnt lgkmcnt(" #n ")" ::: "memory")
; #define PG8_BAR __builtin_amdgcn_s_barrier()
; #define PG8_SCHED __builtin_amdgcn_sched_barrier(0)
; template <class Epi, class Sched, bool ALIGN_EPI = false, bool SP2 = false>
; __device__ __forceinline__ void gemm_phase(PG8_LAS unsigned char* lds, const Gemm g, const Sched& S, const Epi& E) {
;     ...
;             PG8_LDB(B0, 1, 0); PG8_LDB(B1, 1, 1); PG8_SCHED; PG8_LDA(At, 1, 0); PG8_STAGE(PG8_SA(0, 1), a2 + hstep, voffA);
;             PG8_WAIT_V(8); PG8_WAIT_L(0); PG8_BAR; PG8_MMA(0, 0, At, B0); PG8_MMA(0, 1, At, B1); PG8_BAR; PG8_SCHED;
	s_add_i32 s63, 0, 0x18000
	s_add_i32 s64, 0, 0x1c000
	v_add_u32_e32 v166, s63, v153
	v_add_u32_e32 v186, s64, v153
	ds_read_b128 v[148:151], v166
	ds_read_b128 v[158:161], v166 offset:1024
	ds_read_b128 v[162:165], v166 offset:2048
	ds_read_b128 v[166:169], v166 offset:3072
	ds_read_b128 v[170:173], v186
	ds_read_b128 v[174:177], v186 offset:1024
	ds_read_b128 v[182:185], v186 offset:2048
	ds_read_b128 v[186:189], v186 offset:3072
	s_add_u32 s28, s28, 0x40000
	s_addc_u32 s29, s29, 0
	s_mov_b32 m0, s36
	ds_read_b128 v[190:193], v157 offset:32768
	ds_read_b128 v[194:197], v157 offset:33792
	ds_read_b128 v[198:201], v157 offset:34816
	ds_read_b128 v[202:205], v157 offset:35840
	ds_read_b128 v[206:209], v157 offset:36864
	ds_read_b128 v[210:213], v157 offset:37888
	ds_read_b128 v[214:217], v157 offset:38912
	ds_read_b128 v[218:221], v157 offset:39936
	global_load_lds_dwordx4 v138, s[28:29]
	v_lshl_add_u64 v[228:229], s[28:29], 0, v[134:135]
	s_mov_b32 m0, s37
	s_nop 0
	global_load_lds_dwordx4 v134, s[28:29]
	s_waitcnt vmcnt(8)
	s_waitcnt lgkmcnt(0)
	s_barrier
	s_setprio 1
	s_waitcnt lgkmcnt(0)
	v_mfma_f32_16x16x32_bf16 v[126:129], v[148:151], v[190:193], v[126:129]
	v_mfma_f32_16x16x32_bf16 v[122:125], v[162:165], v[190:193], v[122:125]
	v_mfma_f32_16x16x32_bf16 v[118:121], v[148:151], v[198:201], v[118:121]
	v_mfma_f32_16x16x32_bf16 v[110:113], v[162:165], v[198:201], v[110:113]
	v_mfma_f32_16x16x32_bf16 v[102:105], v[148:151], v[206:209], v[102:105]
	v_mfma_f32_16x16x32_bf16 v[94:97], v[162:165], v[206:209], v[94:97]
	v_mfma_f32_16x16x32_bf16 v[86:89], v[148:151], v[214:217], v[86:89]
	v_mfma_f32_16x16x32_bf16 v[78:81], v[162:165], v[214:217], v[78:81]
	v_mfma_f32_16x16x32_bf16 v[126:129], v[158:161], v[194:197], v[126:129]
	v_mfma_f32_16x16x32_bf16 v[122:125], v[166:169], v[194:197], v[122:125]
	v_mfma_f32_16x16x32_bf16 v[118:121], v[158:161], v[202:205], v[118:121]
	v_mfma_f32_16x16x32_bf16 v[110:113], v[166:169], v[202:205], v[110:113]
	v_mfma_f32_16x16x32_bf16 v[102:105], v[158:161], v[210:213], v[102:105]
	v_mfma_f32_16x16x32_bf16 v[94:97], v[166:169], v[210:213], v[94:97]
	v_mfma_f32_16x16x32_bf16 v[86:89], v[158:161], v[218:221], v[86:89]
	v_mfma_f32_16x16x32_bf16 v[78:81], v[166:169], v[218:221], v[78:81]
	s_setprio 0
	s_setprio 1
	v_mfma_f32_16x16x32_bf16 v[114:117], v[170:173], v[190:193], v[114:117]
	v_mfma_f32_16x16x32_bf16 v[106:109], v[182:185], v[190:193], v[106:109]
	v_mfma_f32_16x16x32_bf16 v[98:101], v[170:173], v[198:201], v[98:101]
	v_mfma_f32_16x16x32_bf16 v[90:93], v[182:185], v[198:201], v[90:93]
	v_mfma_f32_16x16x32_bf16 v[82:85], v[170:173], v[206:209], v[82:85]
	v_mfma_f32_16x16x32_bf16 v[74:77], v[182:185], v[206:209], v[74:77]
	v_mfma_f32_16x16x32_bf16 v[70:73], v[170:173], v[214:217], v[70:73]
	v_mfma_f32_16x16x32_bf16 v[66:69], v[182:185], v[214:217], v[66:69]
	v_mfma_f32_16x16x32_bf16 v[114:117], v[174:177], v[194:197], v[114:117]
	v_mfma_f32_16x16x32_bf16 v[106:109], v[186:189], v[194:197], v[106:109]
	v_mfma_f32_16x16x32_bf16 v[98:101], v[174:177], v[202:205], v[98:101]
	v_mfma_f32_16x16x32_bf16 v[90:93], v[186:189], v[202:205], v[90:93]
	v_mfma_f32_16x16x32_bf16 v[82:85], v[174:177], v[210:213], v[82:85]
	v_mfma_f32_16x16x32_bf16 v[74:77], v[186:189], v[210:213], v[74:77]
	v_mfma_f32_16x16x32_bf16 v[70:73], v[174:177], v[218:221], v[70:73]
	v_mfma_f32_16x16x32_bf16 v[66:69], v[186:189], v[218:221], v[66:69]
	s_setprio 0
	s_barrier
; #define PG8_STAGE(bufoff, gbase, voff) do { _Pragma("unroll") for (int _i = 0; _i < 2; ++_i) \
;         __builtin_amdgcn_global_load_lds((const unsigned*)((const char*)(gbase) + (voff)[_i]), (PG8_LAS unsigned*)(lds + (bufoff) + ldsw + _i * 8192), 16, 0, 0); } while (0)
; #define PG8_LDA(dst, b, h) do { _Pragma("unroll") for (int m = 0; m < 4; ++m) _Pragma("unroll") for (int k = 0; k < 2; ++k) dst[m][k] = *(const PG8_LAS bf16x8*)(lds + PG8_SA(b, h) + aoff + m * 2048 + k * 1024); } while (0)
; #define PG8_MMA(ai, bj, At, Bt) do { __builtin_amdgcn_s_setprio(1); _Pragma("unroll") for (int m = 0; m < 4; ++m) _Pragma("unroll") for (int n = 0; n < 2; ++n) _Pragma("unroll") for (int k = 0; k < 2; ++k) \
;         acc[ai][bj][m][n] = __builtin_amdgcn_mfma_f32_16x16x32_bf16(Bt[n][k], At[m][k], acc[ai][bj][m][n], 0, 0, 0); __builtin_amdgcn_s_setprio(0); } while (0)
; #define PG8_WAIT_V(n) asm volatile("s_waitcnt vmcnt(" #n ")" ::: "memory")
; #define PG8_WAIT_L(n) asm volatile("s_waitcnt lgkmcnt(" #n ")" ::: "memory")
; #define PG8_BAR __builtin_amdgcn_s_barrier()
; #define PG8_SCHED __builtin_amdgcn_sched_barrier(0)
; template <class Epi, class Sched, bool ALIGN_EPI = false, bool SP2 = false>
; __device__ __forceinline__ void gemm_phase(PG8_LAS unsigned char* lds, const Gemm g, const Sched& S, const Epi& E) {
;     ...
;         for (int t = 0; t < nt; t += 2) {
;     ...
;             PG8_LDA(At, 1, 1); PG8_STAGE(PG8_SB(1, 0), b3, voffB); PG8_STAGE(PG8_SB(1, 1), b3 + hstep, voffB); PG8_STAGE(PG8_SA(1, 0), a3, voffA);
;             PG8_WAIT_V(8); PG8_WAIT_L(0); PG8_BAR; PG8_MMA(1, 0, At, B0); PG8_MMA(1, 1, At, B1); PG8_BAR; PG8_SCHED;
	s_add_i32 s28, s63, s30
	s_mov_b32 m0, s28
	ds_read_b128 v[190:193], v157 offset:49152
	ds_read_b128 v[194:197], v157 offset:50176
	ds_read_b128 v[198:201], v157 offset:51200
	ds_read_b128 v[202:205], v157 offset:52224
	ds_read_b128 v[206:209], v157 offset:53248
	ds_read_b128 v[210:213], v157 offset:54272
	ds_read_b128 v[214:217], v157 offset:55296
	ds_read_b128 v[218:221], v157 offset:56320
	s_add_u32 s98, s26, s10
	s_addc_u32 s99, s27, s11
	global_load_lds_dwordx4 v136, s[98:99]
	s_add_i32 m0, s28, 0x2000
	s_add_u32 s26, s26, 0x40080
	v_lshl_add_u64 v[178:179], v[222:223], 0, s[10:11]
	s_addc_u32 s27, s27, 0
	s_add_i32 s28, s64, s30
	global_load_lds_dwordx4 v[178:179], off
	s_mov_b32 m0, s28
	s_nop 0
	global_load_lds_dwordx4 v136, s[26:27]
	s_add_i32 m0, s28, 0x2000
	s_nop 0
	global_load_lds_dwordx4 v132, s[26:27]
	v_lshl_add_u64 v[178:179], v[224:225], 0, s[10:11]
	s_mov_b32 m0, s39
	s_nop 0
	global_load_lds_dwordx4 v[178:179], off
	v_lshl_add_u64 v[178:179], v[226:227], 0, s[10:11]
	s_mov_b32 m0, s40
	s_nop 0
	global_load_lds_dwordx4 v[178:179], off
	s_waitcnt vmcnt(8)
	s_waitcnt lgkmcnt(0)
	s_barrier
	s_setprio 1
	s_waitcnt lgkmcnt(0)
	v_mfma_f32_16x16x32_bf16 v[62:65], v[148:151], v[190:193], v[62:65]
	v_mfma_f32_16x16x32_bf16 v[58:61], v[162:165], v[190:193], v[58:61]
	v_mfma_f32_16x16x32_bf16 v[54:57], v[148:151], v[198:201], v[54:57]
	v_mfma_f32_16x16x32_bf16 v[46:49], v[162:165], v[198:201], v[46:49]
	v_mfma_f32_16x16x32_bf16 v[38:41], v[148:151], v[206:209], v[38:41]
	v_mfma_f32_16x16x32_bf16 v[30:33], v[162:165], v[206:209], v[30:33]
	v_mfma_f32_16x16x32_bf16 v[22:25], v[148:151], v[214:217], v[22:25]
	v_mfma_f32_16x16x32_bf16 v[14:17], v[162:165], v[214:217], v[14:17]
	v_mfma_f32_16x16x32_bf16 v[62:65], v[158:161], v[194:197], v[62:65]
	v_mfma_f32_16x16x32_bf16 v[58:61], v[166:169], v[194:197], v[58:61]
	v_mfma_f32_16x16x32_bf16 v[54:57], v[158:161], v[202:205], v[54:57]
	v_mfma_f32_16x16x32_bf16 v[46:49], v[166:169], v[202:205], v[46:49]
	v_mfma_f32_16x16x32_bf16 v[38:41], v[158:161], v[210:213], v[38:41]
	v_mfma_f32_16x16x32_bf16 v[30:33], v[166:169], v[210:213], v[30:33]
	v_mfma_f32_16x16x32_bf16 v[22:25], v[158:161], v[218:221], v[22:25]
	v_mfma_f32_16x16x32_bf16 v[14:17], v[166:169], v[218:221], v[14:17]
	s_setprio 0
	s_setprio 1
	v_mfma_f32_16x16x32_bf16 v[50:53], v[170:173], v[190:193], v[50:53]
	v_mfma_f32_16x16x32_bf16 v[42:45], v[182:185], v[190:193], v[42:45]
	v_mfma_f32_16x16x32_bf16 v[34:37], v[170:173], v[198:201], v[34:37]
	v_mfma_f32_16x16x32_bf16 v[26:29], v[182:185], v[198:201], v[26:29]
	v_mfma_f32_16x16x32_bf16 v[18:21], v[170:173], v[206:209], v[18:21]
	v_mfma_f32_16x16x32_bf16 v[10:13], v[182:185], v[206:209], v[10:13]
	v_mfma_f32_16x16x32_bf16 v[6:9], v[170:173], v[214:217], v[6:9]
	v_mfma_f32_16x16x32_bf16 v[2:5], v[182:185], v[214:217], v[2:5]
	v_mfma_f32_16x16x32_bf16 v[50:53], v[174:177], v[194:197], v[50:53]
	v_mfma_f32_16x16x32_bf16 v[42:45], v[186:189], v[194:197], v[42:45]
	v_mfma_f32_16x16x32_bf16 v[34:37], v[174:177], v[202:205], v[34:37]
	v_mfma_f32_16x16x32_bf16 v[26:29], v[186:189], v[202:205], v[26:29]
	v_mfma_f32_16x16x32_bf16 v[18:21], v[174:177], v[210:213], v[18:21]
	v_mfma_f32_16x16x32_bf16 v[10:13], v[186:189], v[210:213], v[10:13]
	v_mfma_f32_16x16x32_bf16 v[6:9], v[174:177], v[218:221], v[6:9]
	v_mfma_f32_16x16x32_bf16 v[2:5], v[186:189], v[218:221], v[2:5]
	s_setprio 0
	s_barrier
	s_add_i32 s62, s62, 2
	s_add_u32 s24, s24, 0x100
	s_addc_u32 s25, s25, 0
	s_add_u32 s58, s58, 0x100
	s_addc_u32 s59, s59, 0
	s_cmp_gt_u32 s62, 13
	s_cbranch_scc0 .LBB0_1310
	s_and_b64 vcc, exec, s[12:13]
	s_cbranch_vccz .LBB0_1313
	s_barrier

; #define PG8_STAGE(bufoff, gbase, voff) do { _Pragma("unroll") for (int _i = 0; _i < 2; ++_i) \
;         __builtin_amdgcn_global_load_lds((const unsigned*)((const char*)(gbase) + (voff)[_i]), (PG8_LAS unsigned*)(lds + (bufoff) + ldsw + _i * 8192), 16, 0, 0); } while (0)
; #define PG8_LDA(dst, b, h) do { _Pragma("unroll") for (int m = 0; m < 4; ++m) _Pragma("unroll") for (int k = 0; k < 2; ++k) dst[m][k] = *(const PG8_LAS bf16x8*)(lds + PG8_SA(b, h) + aoff + m * 2048 + k * 1024); } while (0)
; #define PG8_LDB(dst, b, h) do { _Pragma("unroll") for (int n = 0; n < 2; ++n) _Pragma("unroll") for (int k = 0; k < 2; ++k) dst[n][k] = *(const PG8_LAS bf16x8*)(lds + PG8_SB(b, h) + boff + n * 2048 + k * 1024); } while (0)
; #define PG8_MMA(ai, bj, At, Bt) do { __builtin_amdgcn_s_setprio(1); _Pragma("unroll") for (int m = 0; m < 4; ++m) _Pragma("unroll") for (int n = 0; n < 2; ++n) _Pragma("unroll") for (int k = 0; k < 2; ++k) \
;         acc[ai][bj][m][n] = __builtin_amdgcn_mfma_f32_16x16x32_bf16(Bt[n][k], At[m][k], acc[ai][bj][m][n], 0, 0, 0); __builtin_amdgcn_s_setprio(0); } while (0)
; #define PG8_WAIT_V(n) asm volatile("s_waitcnt vmcnt(" #n ")" ::: "memory")
; #define PG8_WAIT_L(n) asm volatile("s_waitcnt lgkmcnt(" #n ")" ::: "memory")
; template <class Epi, class Sched, bool ALIGN_EPI = false, bool SP2 = false>
; __device__ __forceinline__ void gemm_phase(PG8_LAS unsigned char* lds, const Gemm g, const Sched& S, const Epi& E) {
;     ...
;             const bool last = (t == nt - 2);
;             const char* a1 = cA + (size_t)(t + 1) * kstep;
;             const char* a2 = last ? nA : cA + (size_t)(t + 2) * kstep; const char* b2 = last ? nB : cB + (size_t)(t + 2) * kstep;
;             const char* a3 = a2 + kstep; const char* b3 = b2 + kstep;
;             if (last && has_next) S.a_ready(nxt);
;             if constexpr (SP2) {
;             PG8_LDB(B0, 0, 0); PG8_LDB(B1, 0, 1); PG8_SCHED; PG8_LDA(At, 0, 0); PG8_STAGE(PG8_SA(1, 1), a1 + hstep, voffA);
;             PG8_WAIT_V(8); PG8_WAIT_L(0); PG8_BAR; PG8_MMA(0, 0, At, B0); PG8_MMA(0, 1, At, B1); PG8_BAR; PG8_SCHED;
;             PG8_LDA(At, 0, 1); PG8_STAGE(PG8_SB(0, 0), b2, voffB); PG8_STAGE(PG8_SB(0, 1), b2 + hstep, voffB); PG8_STAGE(PG8_SA(0, 0), a2, voffA);
;             PG8_WAIT_V(8); PG8_WAIT_L(0); PG8_BAR; PG8_MMA(1, 0, At, B0); PG8_MMA(1, 1, At, B1); PG8_BAR; PG8_SCHED;
.LBB0_1425:
	ds_read_b128 v[152:155], v146
	ds_read_b128 v[156:159], v146 offset:1024
	ds_read_b128 v[160:163], v146 offset:2048
	ds_read_b128 v[164:167], v146 offset:3072
	ds_read_b128 v[168:171], v147
	ds_read_b128 v[172:175], v147 offset:1024
	ds_read_b128 v[176:179], v147 offset:2048
	ds_read_b128 v[182:185], v147 offset:3072
	s_add_u32 s18, s14, s16
	s_addc_u32 s19, s15, s17
	s_add_u32 s18, s18, 0x3c00100
	s_addc_u32 s19, s19, 0
	s_add_u32 s53, s36, s16
	s_addc_u32 s58, s37, s17
	s_cmpk_eq_i32 s16, 0x700
	s_cselect_b32 s21, s11, s19
	s_cselect_b32 s20, s10, s18
	s_cselect_b32 s19, s5, s58
	s_cselect_b32 s18, s4, s53
	s_mov_b32 m0, s39
	v_lshl_add_u64 v[218:219], v[140:141], 0, s[16:17]
	ds_read_b128 v[186:189], v148
	ds_read_b128 v[190:193], v148 offset:1024
	ds_read_b128 v[194:197], v148 offset:2048
	ds_read_b128 v[198:201], v148 offset:3072
	ds_read_b128 v[202:205], v148 offset:4096
	ds_read_b128 v[206:209], v148 offset:5120
	ds_read_b128 v[210:213], v148 offset:6144
	ds_read_b128 v[214:217], v148 offset:7168
	global_load_lds_dwordx4 v[218:219], off
	v_lshl_add_u64 v[218:219], v[142:143], 0, s[16:17]
	s_mov_b32 m0, s40
	s_nop 0
	global_load_lds_dwordx4 v[218:219], off
	s_waitcnt vmcnt(8)
	s_waitcnt lgkmcnt(0)
	s_barrier
	s_setprio 1
	s_waitcnt lgkmcnt(0)
	v_mfma_f32_16x16x32_bf16 v[126:129], v[152:155], v[186:189], v[126:129]
	v_mfma_f32_16x16x32_bf16 v[122:125], v[160:163], v[186:189], v[122:125]
	v_mfma_f32_16x16x32_bf16 v[118:121], v[152:155], v[194:197], v[118:121]
	v_mfma_f32_16x16x32_bf16 v[110:113], v[160:163], v[194:197], v[110:113]
	v_mfma_f32_16x16x32_bf16 v[102:105], v[152:155], v[202:205], v[102:105]
	v_mfma_f32_16x16x32_bf16 v[94:97], v[160:163], v[202:205], v[94:97]
	v_mfma_f32_16x16x32_bf16 v[86:89], v[152:155], v[210:213], v[86:89]
	v_mfma_f32_16x16x32_bf16 v[78:81], v[160:163], v[210:213], v[78:81]
	v_mfma_f32_16x16x32_bf16 v[126:129], v[156:159], v[190:193], v[126:129]
	v_mfma_f32_16x16x32_bf16 v[122:125], v[164:167], v[190:193], v[122:125]
	v_mfma_f32_16x16x32_bf16 v[118:121], v[156:159], v[198:201], v[118:121]
	v_mfma_f32_16x16x32_bf16 v[110:113], v[164:167], v[198:201], v[110:113]
	v_mfma_f32_16x16x32_bf16 v[102:105], v[156:159], v[206:209], v[102:105]
	v_mfma_f32_16x16x32_bf16 v[94:97], v[164:167], v[206:209], v[94:97]
	v_mfma_f32_16x16x32_bf16 v[86:89], v[156:159], v[214:217], v[86:89]
	v_mfma_f32_16x16x32_bf16 v[78:81], v[164:167], v[214:217], v[78:81]
	s_setprio 0
	s_setprio 1
	v_mfma_f32_16x16x32_bf16 v[114:117], v[168:171], v[186:189], v[114:117]
	v_mfma_f32_16x16x32_bf16 v[106:109], v[176:179], v[186:189], v[106:109]
	v_mfma_f32_16x16x32_bf16 v[98:101], v[168:171], v[194:197], v[98:101]
	v_mfma_f32_16x16x32_bf16 v[90:93], v[176:179], v[194:197], v[90:93]
	v_mfma_f32_16x16x32_bf16 v[82:85], v[168:171], v[202:205], v[82:85]
	v_mfma_f32_16x16x32_bf16 v[74:77], v[176:179], v[202:205], v[74:77]
	v_mfma_f32_16x16x32_bf16 v[70:73], v[168:171], v[210:213], v[70:73]
	v_mfma_f32_16x16x32_bf16 v[66:69], v[176:179], v[210:213], v[66:69]
	v_mfma_f32_16x16x32_bf16 v[114:117], v[172:175], v[190:193], v[114:117]
	v_mfma_f32_16x16x32_bf16 v[106:109], v[182:185], v[190:193], v[106:109]
	v_mfma_f32_16x16x32_bf16 v[98:101], v[172:175], v[198:201], v[98:101]
	v_mfma_f32_16x16x32_bf16 v[90:93], v[182:185], v[198:201], v[90:93]
	v_mfma_f32_16x16x32_bf16 v[82:85], v[172:175], v[206:209], v[82:85]
	v_mfma_f32_16x16x32_bf16 v[74:77], v[182:185], v[206:209], v[74:77]
	v_mfma_f32_16x16x32_bf16 v[70:73], v[172:175], v[214:217], v[70:73]
	v_mfma_f32_16x16x32_bf16 v[66:69], v[182:185], v[214:217], v[66:69]
	s_setprio 0
	s_barrier
	s_mov_b32 m0, s41
	v_lshl_add_u64 v[218:219], s[18:19], 0, v[136:137]
	s_add_u32 s58, s18, 0x40000
	ds_read_b128 v[186:189], v148 offset:16384
	ds_read_b128 v[190:193], v148 offset:17408
	ds_read_b128 v[194:197], v148 offset:18432
	ds_read_b128 v[198:201], v148 offset:19456
	ds_read_b128 v[202:205], v148 offset:20480
	ds_read_b128 v[206:209], v148 offset:21504
	ds_read_b128 v[210:213], v148 offset:22528
	ds_read_b128 v[214:217], v148 offset:23552
	global_load_lds_dwordx4 v136, s[18:19]
	v_lshl_add_u64 v[220:221], s[18:19], 0, v[132:133]
	s_mov_b32 m0, s42
	s_addc_u32 s59, s19, 0
	global_load_lds_dwordx4 v132, s[18:19]
	s_mov_b32 m0, s43
	v_lshl_add_u64 v[224:225], s[20:21], 0, v[134:135]
	global_load_lds_dwordx4 v136, s[58:59]
	s_mov_b32 m0, s44
	s_nop 0
	global_load_lds_dwordx4 v132, s[58:59]
	v_lshl_add_u64 v[222:223], s[20:21], 0, v[138:139]
	s_mov_b32 m0, s3
	s_nop 0
	global_load_lds_dwordx4 v138, s[20:21]
	s_mov_b32 m0, s28
	s_nop 0
	global_load_lds_dwordx4 v134, s[20:21]
	s_waitcnt vmcnt(8)
	s_waitcnt lgkmcnt(0)
	s_barrier
; #define PG8_STAGE(bufoff, gbase, voff) do { _Pragma("unroll") for (int _i = 0; _i < 2; ++_i) \
;         __builtin_amdgcn_global_load_lds((const unsigned*)((const char*)(gbase) + (voff)[_i]), (PG8_LAS unsigned*)(lds + (bufoff) + ldsw + _i * 8192), 16, 0, 0); } while (0)
; #define PG8_LDA(dst, b, h) do { _Pragma("unroll") for (int m = 0; m < 4; ++m) _Pragma("unroll") for (int k = 0; k < 2; ++k) dst[m][k] = *(const PG8_LAS bf16x8*)(lds + PG8_SA(b, h) + aoff + m * 2048 + k * 1024); } while (0)
; #define PG8_LDB(dst, b, h) do { _Pragma("unroll") for (int n = 0; n < 2; ++n) _Pragma("unroll") for (int k = 0; k < 2; ++k) dst[n][k] = *(const PG8_LAS bf16x8*)(lds + PG8_SB(b, h) + boff + n * 2048 + k * 1024); } while (0)
; #define PG8_MMA(ai, bj, At, Bt) do { __builtin_amdgcn_s_setprio(1); _Pragma("unroll") for (int m = 0; m < 4; ++m) _Pragma("unroll") for (int n = 0; n < 2; ++n) _Pragma("unroll") for (int k = 0; k < 2; ++k) \
;         acc[ai][bj][m][n] = __builtin_amdgcn_mfma_f32_16x16x32_bf16(Bt[n][k], At[m][k], acc[ai][bj][m][n], 0, 0, 0); __builtin_amdgcn_s_setprio(0); } while (0)
; #define PG8_WAIT_V(n) asm volatile("s_waitcnt vmcnt(" #n ")" ::: "memory")
; #define PG8_WAIT_L(n) asm volatile("s_waitcnt lgkmcnt(" #n ")" ::: "memory")
; #define PG8_BAR __builtin_amdgcn_s_barrier()
; #define PG8_SCHED __builtin_amdgcn_sched_barrier(0)
; template <class Epi, class Sched, bool ALIGN_EPI = false, bool SP2 = false>
; __device__ __forceinline__ void gemm_phase(PG8_LAS unsigned char* lds, const Gemm g, const Sched& S, const Epi& E) {
;     ...
;             PG8_WAIT_V(8); PG8_WAIT_L(0); PG8_BAR; PG8_MMA(1, 0, At, B0); PG8_MMA(1, 1, At, B1); PG8_BAR; PG8_SCHED;
;             PG8_LDB(B0, 1, 0); PG8_LDB(B1, 1, 1); PG8_SCHED; PG8_LDA(At, 1, 0); PG8_STAGE(PG8_SA(0, 1), a2 + hstep, voffA);
;             PG8_WAIT_V(8); PG8_WAIT_L(0); PG8_BAR; PG8_MMA(0, 0, At, B0); PG8_MMA(0, 1, At, B1); PG8_BAR; PG8_SCHED;
	s_setprio 1
	s_waitcnt lgkmcnt(0)
	v_mfma_f32_16x16x32_bf16 v[62:65], v[152:155], v[186:189], v[62:65]
	v_mfma_f32_16x16x32_bf16 v[58:61], v[160:163], v[186:189], v[58:61]
	v_mfma_f32_16x16x32_bf16 v[54:57], v[152:155], v[194:197], v[54:57]
	v_mfma_f32_16x16x32_bf16 v[46:49], v[160:163], v[194:197], v[46:49]
	v_mfma_f32_16x16x32_bf16 v[38:41], v[152:155], v[202:205], v[38:41]
	v_mfma_f32_16x16x32_bf16 v[30:33], v[160:163], v[202:205], v[30:33]
	v_mfma_f32_16x16x32_bf16 v[22:25], v[152:155], v[210:213], v[22:25]
	v_mfma_f32_16x16x32_bf16 v[14:17], v[160:163], v[210:213], v[14:17]
	v_mfma_f32_16x16x32_bf16 v[62:65], v[156:159], v[190:193], v[62:65]
	v_mfma_f32_16x16x32_bf16 v[58:61], v[164:167], v[190:193], v[58:61]
	v_mfma_f32_16x16x32_bf16 v[54:57], v[156:159], v[198:201], v[54:57]
	v_mfma_f32_16x16x32_bf16 v[46:49], v[164:167], v[198:201], v[46:49]
	v_mfma_f32_16x16x32_bf16 v[38:41], v[156:159], v[206:209], v[38:41]
	v_mfma_f32_16x16x32_bf16 v[30:33], v[164:167], v[206:209], v[30:33]
	v_mfma_f32_16x16x32_bf16 v[22:25], v[156:159], v[214:217], v[22:25]
	v_mfma_f32_16x16x32_bf16 v[14:17], v[164:167], v[214:217], v[14:17]
	s_setprio 0
	s_setprio 1
	v_mfma_f32_16x16x32_bf16 v[50:53], v[168:171], v[186:189], v[50:53]
	v_mfma_f32_16x16x32_bf16 v[42:45], v[176:179], v[186:189], v[42:45]
	v_mfma_f32_16x16x32_bf16 v[34:37], v[168:171], v[194:197], v[34:37]
	v_mfma_f32_16x16x32_bf16 v[26:29], v[176:179], v[194:197], v[26:29]
	v_mfma_f32_16x16x32_bf16 v[18:21], v[168:171], v[202:205], v[18:21]
	v_mfma_f32_16x16x32_bf16 v[10:13], v[176:179], v[202:205], v[10:13]
	v_mfma_f32_16x16x32_bf16 v[6:9], v[168:171], v[210:213], v[6:9]
	v_mfma_f32_16x16x32_bf16 v[2:5], v[176:179], v[210:213], v[2:5]
	v_mfma_f32_16x16x32_bf16 v[50:53], v[172:175], v[190:193], v[50:53]
	v_mfma_f32_16x16x32_bf16 v[42:45], v[182:185], v[190:193], v[42:45]
	v_mfma_f32_16x16x32_bf16 v[34:37], v[172:175], v[198:201], v[34:37]
	v_mfma_f32_16x16x32_bf16 v[26:29], v[182:185], v[198:201], v[26:29]
	v_mfma_f32_16x16x32_bf16 v[18:21], v[172:175], v[206:209], v[18:21]
	v_mfma_f32_16x16x32_bf16 v[10:13], v[182:185], v[206:209], v[10:13]
	v_mfma_f32_16x16x32_bf16 v[6:9], v[172:175], v[214:217], v[6:9]
	v_mfma_f32_16x16x32_bf16 v[2:5], v[182:185], v[214:217], v[2:5]
	s_setprio 0
	s_barrier
	ds_read_b128 v[152:155], v149
	ds_read_b128 v[156:159], v149 offset:1024
	ds_read_b128 v[160:163], v149 offset:2048
	ds_read_b128 v[164:167], v149 offset:3072
	ds_read_b128 v[168:171], v150
	ds_read_b128 v[172:175], v150 offset:1024
	ds_read_b128 v[176:179], v150 offset:2048
	ds_read_b128 v[182:185], v150 offset:3072
	s_add_u32 s20, s20, 0x40000
	s_addc_u32 s21, s21, 0
	s_mov_b32 m0, s29
	ds_read_b128 v[186:189], v148 offset:32768
	ds_read_b128 v[190:193], v148 offset:33792
	ds_read_b128 v[194:197], v148 offset:34816
	ds_read_b128 v[198:201], v148 offset:35840
	ds_read_b128 v[202:205], v148 offset:36864
	ds_read_b128 v[206:209], v148 offset:37888
	ds_read_b128 v[210:213], v148 offset:38912
	ds_read_b128 v[214:217], v148 offset:39936
	global_load_lds_dwordx4 v138, s[20:21]
	v_lshl_add_u64 v[226:227], s[20:21], 0, v[134:135]
	s_mov_b32 m0, s30
	s_nop 0
	global_load_lds_dwordx4 v134, s[20:21]
	s_waitcnt vmcnt(8)
	s_waitcnt lgkmcnt(0)
	s_barrier
	s_setprio 1
	s_waitcnt lgkmcnt(0)
	v_mfma_f32_16x16x32_bf16 v[126:129], v[152:155], v[186:189], v[126:129]
	v_mfma_f32_16x16x32_bf16 v[122:125], v[160:163], v[186:189], v[122:125]
	v_mfma_f32_16x16x32_bf16 v[118:121], v[152:155], v[194:197], v[118:121]
	v_mfma_f32_16x16x32_bf16 v[110:113], v[160:163], v[194:197], v[110:113]
	v_mfma_f32_16x16x32_bf16 v[102:105], v[152:155], v[202:205], v[102:105]
	v_mfma_f32_16x16x32_bf16 v[94:97], v[160:163], v[202:205], v[94:97]
	v_mfma_f32_16x16x32_bf16 v[86:89], v[152:155], v[210:213], v[86:89]
	v_mfma_f32_16x16x32_bf16 v[78:81], v[160:163], v[210:213], v[78:81]
	v_mfma_f32_16x16x32_bf16 v[126:129], v[156:159], v[190:193], v[126:129]
	v_mfma_f32_16x16x32_bf16 v[122:125], v[164:167], v[190:193], v[122:125]
	v_mfma_f32_16x16x32_bf16 v[118:121], v[156:159], v[198:201], v[118:121]
	v_mfma_f32_16x16x32_bf16 v[110:113], v[164:167], v[198:201], v[110:113]
	v_mfma_f32_16x16x32_bf16 v[102:105], v[156:159], v[206:209], v[102:105]
	v_mfma_f32_16x16x32_bf16 v[94:97], v[164:167], v[206:209], v[94:97]
	v_mfma_f32_16x16x32_bf16 v[86:89], v[156:159], v[214:217], v[86:89]
	v_mfma_f32_16x16x32_bf16 v[78:81], v[164:167], v[214:217], v[78:81]
	s_setprio 0
	s_setprio 1
	v_mfma_f32_16x16x32_bf16 v[114:117], v[168:171], v[186:189], v[114:117]
	v_mfma_f32_16x16x32_bf16 v[106:109], v[176:179], v[186:189], v[106:109]
	v_mfma_f32_16x16x32_bf16 v[98:101], v[168:171], v[194:197], v[98:101]
	v_mfma_f32_16x16x32_bf16 v[90:93], v[176:179], v[194:197], v[90:93]
	v_mfma_f32_16x16x32_bf16 v[82:85], v[168:171], v[202:205], v[82:85]
	v_mfma_f32_16x16x32_bf16 v[74:77], v[176:179], v[202:205], v[74:77]
	v_mfma_f32_16x16x32_bf16 v[70:73], v[168:171], v[210:213], v[70:73]
	v_mfma_f32_16x16x32_bf16 v[66:69], v[176:179], v[210:213], v[66:69]
	v_mfma_f32_16x16x32_bf16 v[114:117], v[172:175], v[190:193], v[114:117]
	v_mfma_f32_16x16x32_bf16 v[106:109], v[182:185], v[190:193], v[106:109]
	v_mfma_f32_16x16x32_bf16 v[98:101], v[172:175], v[198:201], v[98:101]
	v_mfma_f32_16x16x32_bf16 v[90:93], v[182:185], v[198:201], v[90:93]
	v_mfma_f32_16x16x32_bf16 v[82:85], v[172:175], v[206:209], v[82:85]
	v_mfma_f32_16x16x32_bf16 v[74:77], v[182:185], v[206:209], v[74:77]
	v_mfma_f32_16x16x32_bf16 v[70:73], v[172:175], v[214:217], v[70:73]
	v_mfma_f32_16x16x32_bf16 v[66:69], v[182:185], v[214:217], v[66:69]
	s_setprio 0
	s_barrier
; #define PG8_STAGE(bufoff, gbase, voff) do { _Pragma("unroll") for (int _i = 0; _i < 2; ++_i) \
;         __builtin_amdgcn_global_load_lds((const unsigned*)((const char*)(gbase) + (voff)[_i]), (PG8_LAS unsigned*)(lds + (bufoff) + ldsw + _i * 8192), 16, 0, 0); } while (0)
; #define PG8_LDA(dst, b, h) do { _Pragma("unroll") for (int m = 0; m < 4; ++m) _Pragma("unroll") for (int k = 0; k < 2; ++k) dst[m][k] = *(const PG8_LAS bf16x8*)(lds + PG8_SA(b, h) + aoff + m * 2048 + k * 1024); } while (0)
; #define PG8_MMA(ai, bj, At, Bt) do { __builtin_amdgcn_s_setprio(1); _Pragma("unroll") for (int m = 0; m < 4; ++m) _Pragma("unroll") for (int n = 0; n < 2; ++n) _Pragma("unroll") for (int k = 0; k < 2; ++k) \
;         acc[ai][bj][m][n] = __builtin_amdgcn_mfma_f32_16x16x32_bf16(Bt[n][k], At[m][k], acc[ai][bj][m][n], 0, 0, 0); __builtin_amdgcn_s_setprio(0); } while (0)
; #define PG8_WAIT_V(n) asm volatile("s_waitcnt vmcnt(" #n ")" ::: "memory")
; #define PG8_WAIT_L(n) asm volatile("s_waitcnt lgkmcnt(" #n ")" ::: "memory")
; #define PG8_BAR __builtin_amdgcn_s_barrier()
; #define PG8_SCHED __builtin_amdgcn_sched_barrier(0)
; template <class Epi, class Sched, bool ALIGN_EPI = false, bool SP2 = false>
; __device__ __forceinline__ void gemm_phase(PG8_LAS unsigned char* lds, const Gemm g, const Sched& S, const Epi& E) {
;     ...
;             PG8_LDA(At, 1, 1); PG8_STAGE(PG8_SB(1, 0), b3, voffB); PG8_STAGE(PG8_SB(1, 1), b3 + hstep, voffB); PG8_STAGE(PG8_SA(1, 0), a3, voffA);
;             PG8_WAIT_V(8); PG8_WAIT_L(0); PG8_BAR; PG8_MMA(1, 0, At, B0); PG8_MMA(1, 1, At, B1); PG8_BAR; PG8_SCHED;
	s_mov_b32 m0, s45
	v_lshl_add_u64 v[218:219], v[218:219], 0, s[12:13]
	s_add_u32 s18, s18, 0x40080
	ds_read_b128 v[186:189], v148 offset:49152
	ds_read_b128 v[190:193], v148 offset:50176
	ds_read_b128 v[194:197], v148 offset:51200
	ds_read_b128 v[198:201], v148 offset:52224
	ds_read_b128 v[202:205], v148 offset:53248
	ds_read_b128 v[206:209], v148 offset:54272
	ds_read_b128 v[210:213], v148 offset:55296
	ds_read_b128 v[214:217], v148 offset:56320
	global_load_lds_dwordx4 v[218:219], off
	v_lshl_add_u64 v[218:219], v[220:221], 0, s[12:13]
	s_mov_b32 m0, s48
	s_addc_u32 s19, s19, 0
	global_load_lds_dwordx4 v[218:219], off
	s_mov_b32 m0, s49
	s_nop 0
	global_load_lds_dwordx4 v136, s[18:19]
	s_mov_b32 m0, s52
	s_nop 0
	global_load_lds_dwordx4 v132, s[18:19]
	v_lshl_add_u64 v[218:219], v[222:223], 0, s[12:13]
	s_mov_b32 m0, s34
	s_nop 0
	global_load_lds_dwordx4 v[218:219], off
	v_lshl_add_u64 v[218:219], v[224:225], 0, s[12:13]
	s_mov_b32 m0, s35
	s_nop 0
	global_load_lds_dwordx4 v[218:219], off
	s_waitcnt vmcnt(8)
	s_waitcnt lgkmcnt(0)
	s_barrier
	s_setprio 1
	s_waitcnt lgkmcnt(0)
	v_mfma_f32_16x16x32_bf16 v[62:65], v[152:155], v[186:189], v[62:65]
	v_mfma_f32_16x16x32_bf16 v[58:61], v[160:163], v[186:189], v[58:61]
	v_mfma_f32_16x16x32_bf16 v[54:57], v[152:155], v[194:197], v[54:57]
	v_mfma_f32_16x16x32_bf16 v[46:49], v[160:163], v[194:197], v[46:49]
	v_mfma_f32_16x16x32_bf16 v[38:41], v[152:155], v[202:205], v[38:41]
	v_mfma_f32_16x16x32_bf16 v[30:33], v[160:163], v[202:205], v[30:33]
	v_mfma_f32_16x16x32_bf16 v[22:25], v[152:155], v[210:213], v[22:25]
	v_mfma_f32_16x16x32_bf16 v[14:17], v[160:163], v[210:213], v[14:17]
	v_mfma_f32_16x16x32_bf16 v[62:65], v[156:159], v[190:193], v[62:65]
	v_mfma_f32_16x16x32_bf16 v[58:61], v[164:167], v[190:193], v[58:61]
	v_mfma_f32_16x16x32_bf16 v[54:57], v[156:159], v[198:201], v[54:57]
	v_mfma_f32_16x16x32_bf16 v[46:49], v[164:167], v[198:201], v[46:49]
	v_mfma_f32_16x16x32_bf16 v[38:41], v[156:159], v[206:209], v[38:41]
	v_mfma_f32_16x16x32_bf16 v[30:33], v[164:167], v[206:209], v[30:33]
	v_mfma_f32_16x16x32_bf16 v[22:25], v[156:159], v[214:217], v[22:25]
	v_mfma_f32_16x16x32_bf16 v[14:17], v[164:167], v[214:217], v[14:17]
	s_setprio 0
	s_setprio 1
	v_mfma_f32_16x16x32_bf16 v[50:53], v[168:171], v[186:189], v[50:53]
	v_mfma_f32_16x16x32_bf16 v[42:45], v[176:179], v[186:189], v[42:45]
	v_mfma_f32_16x16x32_bf16 v[34:37], v[168:171], v[194:197], v[34:37]
	v_mfma_f32_16x16x32_bf16 v[26:29], v[176:179], v[194:197], v[26:29]
	v_mfma_f32_16x16x32_bf16 v[18:21], v[168:171], v[202:205], v[18:21]
	v_mfma_f32_16x16x32_bf16 v[10:13], v[176:179], v[202:205], v[10:13]
	v_mfma_f32_16x16x32_bf16 v[6:9], v[168:171], v[210:213], v[6:9]
	v_mfma_f32_16x16x32_bf16 v[2:5], v[176:179], v[210:213], v[2:5]
	v_mfma_f32_16x16x32_bf16 v[50:53], v[172:175], v[190:193], v[50:53]
	v_mfma_f32_16x16x32_bf16 v[42:45], v[182:185], v[190:193], v[42:45]
	v_mfma_f32_16x16x32_bf16 v[34:37], v[172:175], v[198:201], v[34:37]
	v_mfma_f32_16x16x32_bf16 v[26:29], v[182:185], v[198:201], v[26:29]
	v_mfma_f32_16x16x32_bf16 v[18:21], v[172:175], v[206:209], v[18:21]
	v_mfma_f32_16x16x32_bf16 v[10:13], v[182:185], v[206:209], v[10:13]
	v_mfma_f32_16x16x32_bf16 v[6:9], v[172:175], v[214:217], v[6:9]
	v_mfma_f32_16x16x32_bf16 v[2:5], v[182:185], v[214:217], v[2:5]
	s_setprio 0
	s_barrier
	s_add_i32 s38, s38, 2
	s_add_u32 s16, s16, 0x100
	s_addc_u32 s17, s17, 0
	s_cmp_gt_u32 s38, 13
	s_cbranch_scc0 .LBB0_1425
	s_cmpk_lt_u32 s22, 0x100
	s_cbranch_scc0 .LBB0_1428
	s_barrier

; __global__ void __launch_bounds__(mk::NTHR, 2) fwd_kernel(Args args) {
;     ...
;     if (IN(13)) {
;         for (int u = vcu; u < 1024; u += G) { const int qb = u & 31, gq = (u >> 5) & 3, kvh = (u >> 7) & 1, b = u >> 8, h = kvh * 4 + gq;
.LBB0_1582:
	s_nop 0
	s_nop 0
	s_nop 0
	s_nop 0
	s_nop 0
	s_nop 0
	s_nop 0
	s_nop 0
	s_nop 0
	s_nop 0
	s_nop 0
	s_nop 0
	s_nop 0
	s_nop 0
	s_cmp_lt_i32 s84, 14
	s_cselect_b64 s[4:5], -1, 0
	s_and_b64 s[28:29], s[4:5], s[2:3]
	s_xor_b64 s[2:3], s[28:29], -1
	s_cmpk_gt_i32 s33, 0x3ff
	s_cselect_b64 s[4:5], -1, 0
	s_or_b64 s[2:3], s[2:3], s[4:5]
	s_and_b64 vcc, exec, s[2:3]
	s_cbranch_vccnz .LBB0_1602
	v_readfirstlane_b32 s98, v0
	s_bitcmp1_b32 s98, 8
	s_cbranch_scc0 .Lattn_noprio
	s_setprio 1

; #define PG8_STAGE(bufoff, gbase, voff) do { _Pragma("unroll") for (int _i = 0; _i < 2; ++_i) \
;         __builtin_amdgcn_global_load_lds((const unsigned*)((const char*)(gbase) + (voff)[_i]), (PG8_LAS unsigned*)(lds + (bufoff) + ldsw + _i * 8192), 16, 0, 0); } while (0)
; #define PG8_LDA(dst, b, h) do { _Pragma("unroll") for (int m = 0; m < 4; ++m) _Pragma("unroll") for (int k = 0; k < 2; ++k) dst[m][k] = *(const PG8_LAS bf16x8*)(lds + PG8_SA(b, h) + aoff + m * 2048 + k * 1024); } while (0)
; #define PG8_LDB(dst, b, h) do { _Pragma("unroll") for (int n = 0; n < 2; ++n) _Pragma("unroll") for (int k = 0; k < 2; ++k) dst[n][k] = *(const PG8_LAS bf16x8*)(lds + PG8_SB(b, h) + boff + n * 2048 + k * 1024); } while (0)
; #define PG8_MMA(ai, bj, At, Bt) do { __builtin_amdgcn_s_setprio(1); _Pragma("unroll") for (int m = 0; m < 4; ++m) _Pragma("unroll") for (int n = 0; n < 2; ++n) _Pragma("unroll") for (int k = 0; k < 2; ++k) \
;         acc[ai][bj][m][n] = __builtin_amdgcn_mfma_f32_16x16x32_bf16(Bt[n][k], At[m][k], acc[ai][bj][m][n], 0, 0, 0); __builtin_amdgcn_s_setprio(0); } while (0)
; #define PG8_WAIT_V(n) asm volatile("s_waitcnt vmcnt(" #n ")" ::: "memory")
; #define PG8_WAIT_L(n) asm volatile("s_waitcnt lgkmcnt(" #n ")" ::: "memory")
; #define PG8_BAR __builtin_amdgcn_s_barrier()
; #define PG8_SCHED __builtin_amdgcn_sched_barrier(0)
; template <class Epi, class Sched, bool ALIGN_EPI = false, bool SP2 = false>
; __device__ __forceinline__ void gemm_phase(PG8_LAS unsigned char* lds, const Gemm g, const Sched& S, const Epi& E) {
;     ...
;             PG8_LDB(B0, 0, 0); PG8_LDB(B1, 0, 1); PG8_SCHED; PG8_LDA(At, 0, 0); PG8_STAGE(PG8_SA(1, 1), a1 + hstep, voffA);
;             PG8_WAIT_V(8); PG8_WAIT_L(0); PG8_BAR; PG8_MMA(0, 0, At, B0); PG8_MMA(0, 1, At, B1); PG8_BAR; PG8_SCHED;
;             PG8_LDA(At, 0, 1); PG8_STAGE(PG8_SB(0, 0), b2, voffB); PG8_STAGE(PG8_SB(0, 1), b2 + hstep, voffB); PG8_STAGE(PG8_SA(0, 0), a2, voffA);
;             PG8_WAIT_V(8); PG8_WAIT_L(0); PG8_BAR; PG8_MMA(1, 0, At, B0); PG8_MMA(1, 1, At, B1); PG8_BAR; PG8_SCHED;
.LBB0_1674:
	ds_read_b128 v[154:157], v151
	ds_read_b128 v[158:161], v151 offset:1024
	ds_read_b128 v[162:165], v151 offset:2048
	ds_read_b128 v[166:169], v151 offset:3072
	ds_read_b128 v[170:173], v152
	ds_read_b128 v[174:177], v152 offset:1024
	ds_read_b128 v[182:185], v152 offset:2048
	ds_read_b128 v[186:189], v152 offset:3072
	s_add_u32 s36, s34, 0xfffc0080
	s_addc_u32 s37, s35, -1
	s_cmp_eq_u32 s69, 12
	s_cselect_b32 s39, s25, s37
	s_cselect_b32 s38, s65, s36
	s_cselect_b32 s37, s23, s68
	s_cselect_b32 s36, s66, s67
	s_add_i32 m0, s31, 0xc000
	ds_read_b128 v[190:193], v153
	ds_read_b128 v[194:197], v153 offset:1024
	ds_read_b128 v[198:201], v153 offset:2048
	ds_read_b128 v[202:205], v153 offset:3072
	ds_read_b128 v[206:209], v153 offset:4096
	ds_read_b128 v[210:213], v153 offset:5120
	ds_read_b128 v[214:217], v153 offset:6144
	ds_read_b128 v[218:221], v153 offset:7168
	global_load_lds_dwordx4 v138, s[34:35]
	s_add_i32 m0, s31, 0xe000
	s_nop 0
	global_load_lds_dwordx4 v140, s[34:35]
	s_waitcnt vmcnt(8)
	s_waitcnt lgkmcnt(0)
	s_barrier
	s_setprio 1
	s_waitcnt lgkmcnt(0)
	v_mfma_f32_16x16x32_bf16 v[126:129], v[154:157], v[190:193], v[126:129]
	v_mfma_f32_16x16x32_bf16 v[122:125], v[162:165], v[190:193], v[122:125]
	v_mfma_f32_16x16x32_bf16 v[118:121], v[154:157], v[198:201], v[118:121]
	v_mfma_f32_16x16x32_bf16 v[110:113], v[162:165], v[198:201], v[110:113]
	v_mfma_f32_16x16x32_bf16 v[102:105], v[154:157], v[206:209], v[102:105]
	v_mfma_f32_16x16x32_bf16 v[94:97], v[162:165], v[206:209], v[94:97]
	v_mfma_f32_16x16x32_bf16 v[86:89], v[154:157], v[214:217], v[86:89]
	v_mfma_f32_16x16x32_bf16 v[78:81], v[162:165], v[214:217], v[78:81]
	v_mfma_f32_16x16x32_bf16 v[126:129], v[158:161], v[194:197], v[126:129]
	v_mfma_f32_16x16x32_bf16 v[122:125], v[166:169], v[194:197], v[122:125]
	v_mfma_f32_16x16x32_bf16 v[118:121], v[158:161], v[202:205], v[118:121]
	v_mfma_f32_16x16x32_bf16 v[110:113], v[166:169], v[202:205], v[110:113]
	v_mfma_f32_16x16x32_bf16 v[102:105], v[158:161], v[210:213], v[102:105]
	v_mfma_f32_16x16x32_bf16 v[94:97], v[166:169], v[210:213], v[94:97]
	v_mfma_f32_16x16x32_bf16 v[86:89], v[158:161], v[218:221], v[86:89]
	v_mfma_f32_16x16x32_bf16 v[78:81], v[166:169], v[218:221], v[78:81]
	s_setprio 0
	s_setprio 1
	v_mfma_f32_16x16x32_bf16 v[114:117], v[170:173], v[190:193], v[114:117]
	v_mfma_f32_16x16x32_bf16 v[106:109], v[182:185], v[190:193], v[106:109]
	v_mfma_f32_16x16x32_bf16 v[98:101], v[170:173], v[198:201], v[98:101]
	v_mfma_f32_16x16x32_bf16 v[90:93], v[182:185], v[198:201], v[90:93]
	v_mfma_f32_16x16x32_bf16 v[82:85], v[170:173], v[206:209], v[82:85]
	v_mfma_f32_16x16x32_bf16 v[74:77], v[182:185], v[206:209], v[74:77]
	v_mfma_f32_16x16x32_bf16 v[70:73], v[170:173], v[214:217], v[70:73]
	v_mfma_f32_16x16x32_bf16 v[66:69], v[182:185], v[214:217], v[66:69]
	v_mfma_f32_16x16x32_bf16 v[114:117], v[174:177], v[194:197], v[114:117]
	v_mfma_f32_16x16x32_bf16 v[106:109], v[186:189], v[194:197], v[106:109]
	v_mfma_f32_16x16x32_bf16 v[98:101], v[174:177], v[202:205], v[98:101]
	v_mfma_f32_16x16x32_bf16 v[90:93], v[186:189], v[202:205], v[90:93]
	v_mfma_f32_16x16x32_bf16 v[82:85], v[174:177], v[210:213], v[82:85]
	v_mfma_f32_16x16x32_bf16 v[74:77], v[186:189], v[210:213], v[74:77]
	v_mfma_f32_16x16x32_bf16 v[70:73], v[174:177], v[218:221], v[70:73]
	v_mfma_f32_16x16x32_bf16 v[66:69], v[186:189], v[218:221], v[66:69]
	s_setprio 0
	s_barrier
	s_add_i32 s70, s52, s40
	s_mov_b32 m0, s70
	ds_read_b128 v[190:193], v153 offset:16384
	ds_read_b128 v[194:197], v153 offset:17408
	ds_read_b128 v[198:201], v153 offset:18432
	ds_read_b128 v[202:205], v153 offset:19456
	ds_read_b128 v[206:209], v153 offset:20480
	ds_read_b128 v[210:213], v153 offset:21504
	ds_read_b128 v[214:217], v153 offset:22528
	ds_read_b128 v[218:221], v153 offset:23552
	global_load_lds_dwordx4 v132, s[36:37]
	s_add_i32 m0, s70, 0x2000
	s_add_u32 s70, s36, 0x40000
	v_lshl_add_u64 v[178:179], s[36:37], 0, v[136:137]
	s_addc_u32 s71, s37, 0
	s_add_i32 s72, s53, s40
	global_load_lds_dwordx4 v136, s[36:37]
	s_mov_b32 m0, s72
	v_lshl_add_u64 v[224:225], s[38:39], 0, v[134:135]
	global_load_lds_dwordx4 v132, s[70:71]
	s_add_i32 m0, s72, 0x2000
	s_nop 0
	global_load_lds_dwordx4 v136, s[70:71]
	v_lshl_add_u64 v[222:223], s[38:39], 0, v[130:131]
	s_mov_b32 m0, s31
	s_nop 0
	global_load_lds_dwordx4 v130, s[38:39]
	s_mov_b32 m0, s41
	s_nop 0
	global_load_lds_dwordx4 v134, s[38:39]
	s_waitcnt vmcnt(8)
	s_waitcnt lgkmcnt(0)
	s_barrier
	s_setprio 1
	s_waitcnt lgkmcnt(0)
	v_mfma_f32_16x16x32_bf16 v[62:65], v[154:157], v[190:193], v[62:65]
	v_mfma_f32_16x16x32_bf16 v[58:61], v[162:165], v[190:193], v[58:61]
	v_mfma_f32_16x16x32_bf16 v[54:57], v[154:157], v[198:201], v[54:57]
	v_mfma_f32_16x16x32_bf16 v[46:49], v[162:165], v[198:201], v[46:49]
	v_mfma_f32_16x16x32_bf16 v[38:41], v[154:157], v[206:209], v[38:41]
	v_mfma_f32_16x16x32_bf16 v[30:33], v[162:165], v[206:209], v[30:33]
	v_mfma_f32_16x16x32_bf16 v[22:25], v[154:157], v[214:217], v[22:25]
	v_mfma_f32_16x16x32_bf16 v[14:17], v[162:165], v[214:217], v[14:17]
	v_mfma_f32_16x16x32_bf16 v[62:65], v[158:161], v[194:197], v[62:65]
	v_mfma_f32_16x16x32_bf16 v[58:61], v[166:169], v[194:197], v[58:61]
	v_mfma_f32_16x16x32_bf16 v[54:57], v[158:161], v[202:205], v[54:57]
	v_mfma_f32_16x16x32_bf16 v[46:49], v[166:169], v[202:205], v[46:49]
	v_mfma_f32_16x16x32_bf16 v[38:41], v[158:161], v[210:213], v[38:41]
	v_mfma_f32_16x16x32_bf16 v[30:33], v[166:169], v[210:213], v[30:33]
	v_mfma_f32_16x16x32_bf16 v[22:25], v[158:161], v[218:221], v[22:25]
	v_mfma_f32_16x16x32_bf16 v[14:17], v[166:169], v[218:221], v[14:17]
	s_setprio 0
	s_setprio 1
	v_mfma_f32_16x16x32_bf16 v[50:53], v[170:173], v[190:193], v[50:53]
	v_mfma_f32_16x16x32_bf16 v[42:45], v[182:185], v[190:193], v[42:45]
	v_mfma_f32_16x16x32_bf16 v[34:37], v[170:173], v[198:201], v[34:37]
	v_mfma_f32_16x16x32_bf16 v[26:29], v[182:185], v[198:201], v[26:29]
	v_mfma_f32_16x16x32_bf16 v[18:21], v[170:173], v[206:209], v[18:21]
	v_mfma_f32_16x16x32_bf16 v[10:13], v[182:185], v[206:209], v[10:13]
	v_mfma_f32_16x16x32_bf16 v[6:9], v[170:173], v[214:217], v[6:9]
	v_mfma_f32_16x16x32_bf16 v[2:5], v[182:185], v[214:217], v[2:5]
	v_mfma_f32_16x16x32_bf16 v[50:53], v[174:177], v[194:197], v[50:53]
	v_mfma_f32_16x16x32_bf16 v[42:45], v[186:189], v[194:197], v[42:45]
	v_mfma_f32_16x16x32_bf16 v[34:37], v[174:177], v[202:205], v[34:37]
	v_mfma_f32_16x16x32_bf16 v[26:29], v[186:189], v[202:205], v[26:29]
	v_mfma_f32_16x16x32_bf16 v[18:21], v[174:177], v[210:213], v[18:21]
	v_mfma_f32_16x16x32_bf16 v[10:13], v[186:189], v[210:213], v[10:13]
	v_mfma_f32_16x16x32_bf16 v[6:9], v[174:177], v[218:221], v[6:9]
	v_mfma_f32_16x16x32_bf16 v[2:5], v[186:189], v[218:221], v[2:5]
	s_setprio 0
	s_barrier
; #define PG8_STAGE(bufoff, gbase, voff) do { _Pragma("unroll") for (int _i = 0; _i < 2; ++_i) \
;         __builtin_amdgcn_global_load_lds((const unsigned*)((const char*)(gbase) + (voff)[_i]), (PG8_LAS unsigned*)(lds + (bufoff) + ldsw + _i * 8192), 16, 0, 0); } while (0)
; #define PG8_LDA(dst, b, h) do { _Pragma("unroll") for (int m = 0; m < 4; ++m) _Pragma("unroll") for (int k = 0; k < 2; ++k) dst[m][k] = *(const PG8_LAS bf16x8*)(lds + PG8_SA(b, h) + aoff + m * 2048 + k * 1024); } while (0)
; #define PG8_LDB(dst, b, h) do { _Pragma("unroll") for (int n = 0; n < 2; ++n) _Pragma("unroll") for (int k = 0; k < 2; ++k) dst[n][k] = *(const PG8_LAS bf16x8*)(lds + PG8_SB(b, h) + boff + n * 2048 + k * 1024); } while (0)
; #define PG8_MMA(ai, bj, At, Bt) do { __builtin_amdgcn_s_setprio(1); _Pragma("unroll") for (int m = 0; m < 4; ++m) _Pragma("unroll") for (int n = 0; n < 2; ++n) _Pragma("unroll") for (int k = 0; k < 2; ++k) \
;         acc[ai][bj][m][n] = __builtin_amdgcn_mfma_f32_16x16x32_bf16(Bt[n][k], At[m][k], acc[ai][bj][m][n], 0, 0, 0); __builtin_amdgcn_s_setprio(0); } while (0)
; #define PG8_WAIT_V(n) asm volatile("s_waitcnt vmcnt(" #n ")" ::: "memory")
; #define PG8_WAIT_L(n) asm volatile("s_waitcnt lgkmcnt(" #n ")" ::: "memory")
; #define PG8_BAR __builtin_amdgcn_s_barrier()
; #define PG8_SCHED __builtin_amdgcn_sched_barrier(0)
; template <class Epi, class Sched, bool ALIGN_EPI = false, bool SP2 = false>
; __device__ __forceinline__ void gemm_phase(PG8_LAS unsigned char* lds, const Gemm g, const Sched& S, const Epi& E) {
;     ...
;             PG8_LDB(B0, 1, 0); PG8_LDB(B1, 1, 1); PG8_SCHED; PG8_LDA(At, 1, 0); PG8_STAGE(PG8_SA(0, 1), a2 + hstep, voffA);
;             PG8_WAIT_V(8); PG8_WAIT_L(0); PG8_BAR; PG8_MMA(0, 0, At, B0); PG8_MMA(0, 1, At, B1); PG8_BAR; PG8_SCHED;
	s_add_i32 s70, 0, 0x18000
	s_add_i32 s71, 0, 0x1c000
	v_add_u32_e32 v166, s70, v149
	v_add_u32_e32 v181, s71, v149
	ds_read_b128 v[154:157], v166
	ds_read_b128 v[158:161], v166 offset:1024
	ds_read_b128 v[162:165], v166 offset:2048
	ds_read_b128 v[166:169], v166 offset:3072
	ds_read_b128 v[170:173], v181
	ds_read_b128 v[174:177], v181 offset:1024
	ds_read_b128 v[182:185], v181 offset:2048
	ds_read_b128 v[186:189], v181 offset:3072
	s_add_u32 s38, s38, 0x40000
	s_addc_u32 s39, s39, 0
	s_mov_b32 m0, s42
	ds_read_b128 v[190:193], v153 offset:32768
	ds_read_b128 v[194:197], v153 offset:33792
	ds_read_b128 v[198:201], v153 offset:34816
	ds_read_b128 v[202:205], v153 offset:35840
	ds_read_b128 v[206:209], v153 offset:36864
	ds_read_b128 v[210:213], v153 offset:37888
	ds_read_b128 v[214:217], v153 offset:38912
	ds_read_b128 v[218:221], v153 offset:39936
	global_load_lds_dwordx4 v130, s[38:39]
	v_lshl_add_u64 v[226:227], s[38:39], 0, v[134:135]
	s_mov_b32 m0, s43
	s_nop 0
	global_load_lds_dwordx4 v134, s[38:39]
	s_waitcnt vmcnt(8)
	s_waitcnt lgkmcnt(0)
	s_barrier
	s_setprio 1
	s_waitcnt lgkmcnt(0)
	v_mfma_f32_16x16x32_bf16 v[126:129], v[154:157], v[190:193], v[126:129]
	v_mfma_f32_16x16x32_bf16 v[122:125], v[162:165], v[190:193], v[122:125]
	v_mfma_f32_16x16x32_bf16 v[118:121], v[154:157], v[198:201], v[118:121]
	v_mfma_f32_16x16x32_bf16 v[110:113], v[162:165], v[198:201], v[110:113]
	v_mfma_f32_16x16x32_bf16 v[102:105], v[154:157], v[206:209], v[102:105]
	v_mfma_f32_16x16x32_bf16 v[94:97], v[162:165], v[206:209], v[94:97]
	v_mfma_f32_16x16x32_bf16 v[86:89], v[154:157], v[214:217], v[86:89]
	v_mfma_f32_16x16x32_bf16 v[78:81], v[162:165], v[214:217], v[78:81]
	v_mfma_f32_16x16x32_bf16 v[126:129], v[158:161], v[194:197], v[126:129]
	v_mfma_f32_16x16x32_bf16 v[122:125], v[166:169], v[194:197], v[122:125]
	v_mfma_f32_16x16x32_bf16 v[118:121], v[158:161], v[202:205], v[118:121]
	v_mfma_f32_16x16x32_bf16 v[110:113], v[166:169], v[202:205], v[110:113]
	v_mfma_f32_16x16x32_bf16 v[102:105], v[158:161], v[210:213], v[102:105]
	v_mfma_f32_16x16x32_bf16 v[94:97], v[166:169], v[210:213], v[94:97]
	v_mfma_f32_16x16x32_bf16 v[86:89], v[158:161], v[218:221], v[86:89]
	v_mfma_f32_16x16x32_bf16 v[78:81], v[166:169], v[218:221], v[78:81]
	s_setprio 0
	s_setprio 1
	v_mfma_f32_16x16x32_bf16 v[114:117], v[170:173], v[190:193], v[114:117]
	v_mfma_f32_16x16x32_bf16 v[106:109], v[182:185], v[190:193], v[106:109]
	v_mfma_f32_16x16x32_bf16 v[98:101], v[170:173], v[198:201], v[98:101]
	v_mfma_f32_16x16x32_bf16 v[90:93], v[182:185], v[198:201], v[90:93]
	v_mfma_f32_16x16x32_bf16 v[82:85], v[170:173], v[206:209], v[82:85]
	v_mfma_f32_16x16x32_bf16 v[74:77], v[182:185], v[206:209], v[74:77]
	v_mfma_f32_16x16x32_bf16 v[70:73], v[170:173], v[214:217], v[70:73]
	v_mfma_f32_16x16x32_bf16 v[66:69], v[182:185], v[214:217], v[66:69]
	v_mfma_f32_16x16x32_bf16 v[114:117], v[174:177], v[194:197], v[114:117]
	v_mfma_f32_16x16x32_bf16 v[106:109], v[186:189], v[194:197], v[106:109]
	v_mfma_f32_16x16x32_bf16 v[98:101], v[174:177], v[202:205], v[98:101]
	v_mfma_f32_16x16x32_bf16 v[90:93], v[186:189], v[202:205], v[90:93]
	v_mfma_f32_16x16x32_bf16 v[82:85], v[174:177], v[210:213], v[82:85]
	v_mfma_f32_16x16x32_bf16 v[74:77], v[186:189], v[210:213], v[74:77]
	v_mfma_f32_16x16x32_bf16 v[70:73], v[174:177], v[218:221], v[70:73]
	v_mfma_f32_16x16x32_bf16 v[66:69], v[186:189], v[218:221], v[66:69]
	s_setprio 0
	s_barrier
; #define PG8_STAGE(bufoff, gbase, voff) do { _Pragma("unroll") for (int _i = 0; _i < 2; ++_i) \
;         __builtin_amdgcn_global_load_lds((const unsigned*)((const char*)(gbase) + (voff)[_i]), (PG8_LAS unsigned*)(lds + (bufoff) + ldsw + _i * 8192), 16, 0, 0); } while (0)
; #define PG8_LDA(dst, b, h) do { _Pragma("unroll") for (int m = 0; m < 4; ++m) _Pragma("unroll") for (int k = 0; k < 2; ++k) dst[m][k] = *(const PG8_LAS bf16x8*)(lds + PG8_SA(b, h) + aoff + m * 2048 + k * 1024); } while (0)
; #define PG8_MMA(ai, bj, At, Bt) do { __builtin_amdgcn_s_setprio(1); _Pragma("unroll") for (int m = 0; m < 4; ++m) _Pragma("unroll") for (int n = 0; n < 2; ++n) _Pragma("unroll") for (int k = 0; k < 2; ++k) \
;         acc[ai][bj][m][n] = __builtin_amdgcn_mfma_f32_16x16x32_bf16(Bt[n][k], At[m][k], acc[ai][bj][m][n], 0, 0, 0); __builtin_amdgcn_s_setprio(0); } while (0)
; #define PG8_WAIT_V(n) asm volatile("s_waitcnt vmcnt(" #n ")" ::: "memory")
; #define PG8_WAIT_L(n) asm volatile("s_waitcnt lgkmcnt(" #n ")" ::: "memory")
; #define PG8_BAR __builtin_amdgcn_s_barrier()
; #define PG8_SCHED __builtin_amdgcn_sched_barrier(0)
; template <class Epi, class Sched, bool ALIGN_EPI = false, bool SP2 = false>
; __device__ __forceinline__ void gemm_phase(PG8_LAS unsigned char* lds, const Gemm g, const Sched& S, const Epi& E) {
;     ...
;         for (int t = 0; t < nt; t += 2) {
;             const bool last = (t == nt - 2);
;             const char* a1 = cA + (size_t)(t + 1) * kstep;
;             const char* a2 = last ? nA : cA + (size_t)(t + 2) * kstep; const char* b2 = last ? nB : cB + (size_t)(t + 2) * kstep;
;     ...
;             PG8_LDA(At, 1, 1); PG8_STAGE(PG8_SB(1, 0), b3, voffB); PG8_STAGE(PG8_SB(1, 1), b3 + hstep, voffB); PG8_STAGE(PG8_SA(1, 0), a3, voffA);
;             PG8_WAIT_V(8); PG8_WAIT_L(0); PG8_BAR; PG8_MMA(1, 0, At, B0); PG8_MMA(1, 1, At, B1); PG8_BAR; PG8_SCHED;
	s_add_i32 s38, s70, s40
	s_mov_b32 m0, s38
	ds_read_b128 v[190:193], v153 offset:49152
	ds_read_b128 v[194:197], v153 offset:50176
	ds_read_b128 v[198:201], v153 offset:51200
	ds_read_b128 v[202:205], v153 offset:52224
	ds_read_b128 v[206:209], v153 offset:53248
	ds_read_b128 v[210:213], v153 offset:54272
	ds_read_b128 v[214:217], v153 offset:55296
	ds_read_b128 v[218:221], v153 offset:56320
	s_add_u32 s98, s36, s12
	s_addc_u32 s99, s37, s13
	global_load_lds_dwordx4 v132, s[98:99]
	s_add_i32 m0, s38, 0x2000
	s_add_u32 s36, s36, 0x40080
	v_lshl_add_u64 v[146:147], v[178:179], 0, s[12:13]
	s_addc_u32 s37, s37, 0
	s_add_i32 s38, s71, s40
	global_load_lds_dwordx4 v[146:147], off
	s_mov_b32 m0, s38
	s_nop 0
	global_load_lds_dwordx4 v132, s[36:37]
	s_add_i32 m0, s38, 0x2000
	s_nop 0
	global_load_lds_dwordx4 v136, s[36:37]
	v_lshl_add_u64 v[146:147], v[222:223], 0, s[12:13]
	s_mov_b32 m0, s45
	s_nop 0
	global_load_lds_dwordx4 v[146:147], off
	v_lshl_add_u64 v[146:147], v[224:225], 0, s[12:13]
	s_mov_b32 m0, s47
	s_nop 0
	global_load_lds_dwordx4 v[146:147], off
	s_waitcnt vmcnt(8)
	s_waitcnt lgkmcnt(0)
	s_barrier
	s_setprio 1
	s_waitcnt lgkmcnt(0)
	v_mfma_f32_16x16x32_bf16 v[62:65], v[154:157], v[190:193], v[62:65]
	v_mfma_f32_16x16x32_bf16 v[58:61], v[162:165], v[190:193], v[58:61]
	v_mfma_f32_16x16x32_bf16 v[54:57], v[154:157], v[198:201], v[54:57]
	v_mfma_f32_16x16x32_bf16 v[46:49], v[162:165], v[198:201], v[46:49]
	v_mfma_f32_16x16x32_bf16 v[38:41], v[154:157], v[206:209], v[38:41]
	v_mfma_f32_16x16x32_bf16 v[30:33], v[162:165], v[206:209], v[30:33]
	v_mfma_f32_16x16x32_bf16 v[22:25], v[154:157], v[214:217], v[22:25]
	v_mfma_f32_16x16x32_bf16 v[14:17], v[162:165], v[214:217], v[14:17]
	v_mfma_f32_16x16x32_bf16 v[62:65], v[158:161], v[194:197], v[62:65]
	v_mfma_f32_16x16x32_bf16 v[58:61], v[166:169], v[194:197], v[58:61]
	v_mfma_f32_16x16x32_bf16 v[54:57], v[158:161], v[202:205], v[54:57]
	v_mfma_f32_16x16x32_bf16 v[46:49], v[166:169], v[202:205], v[46:49]
	v_mfma_f32_16x16x32_bf16 v[38:41], v[158:161], v[210:213], v[38:41]
	v_mfma_f32_16x16x32_bf16 v[30:33], v[166:169], v[210:213], v[30:33]
	v_mfma_f32_16x16x32_bf16 v[22:25], v[158:161], v[218:221], v[22:25]
	v_mfma_f32_16x16x32_bf16 v[14:17], v[166:169], v[218:221], v[14:17]
	s_setprio 0
	s_setprio 1
	v_mfma_f32_16x16x32_bf16 v[50:53], v[170:173], v[190:193], v[50:53]
	v_mfma_f32_16x16x32_bf16 v[42:45], v[182:185], v[190:193], v[42:45]
	v_mfma_f32_16x16x32_bf16 v[34:37], v[170:173], v[198:201], v[34:37]
	v_mfma_f32_16x16x32_bf16 v[26:29], v[182:185], v[198:201], v[26:29]
	v_mfma_f32_16x16x32_bf16 v[18:21], v[170:173], v[206:209], v[18:21]
	v_mfma_f32_16x16x32_bf16 v[10:13], v[182:185], v[206:209], v[10:13]
	v_mfma_f32_16x16x32_bf16 v[6:9], v[170:173], v[214:217], v[6:9]
	v_mfma_f32_16x16x32_bf16 v[2:5], v[182:185], v[214:217], v[2:5]
	v_mfma_f32_16x16x32_bf16 v[50:53], v[174:177], v[194:197], v[50:53]
	v_mfma_f32_16x16x32_bf16 v[42:45], v[186:189], v[194:197], v[42:45]
	v_mfma_f32_16x16x32_bf16 v[34:37], v[174:177], v[202:205], v[34:37]
	v_mfma_f32_16x16x32_bf16 v[26:29], v[186:189], v[202:205], v[26:29]
	v_mfma_f32_16x16x32_bf16 v[18:21], v[174:177], v[210:213], v[18:21]
	v_mfma_f32_16x16x32_bf16 v[10:13], v[186:189], v[210:213], v[10:13]
	v_mfma_f32_16x16x32_bf16 v[6:9], v[174:177], v[218:221], v[6:9]
	v_mfma_f32_16x16x32_bf16 v[2:5], v[186:189], v[218:221], v[2:5]
	s_setprio 0
	s_barrier
	s_add_i32 s69, s69, 2
	s_add_u32 s34, s34, 0x100
	s_addc_u32 s35, s35, 0
	s_add_u32 s67, s67, 0x100
	s_addc_u32 s68, s68, 0
	s_cmp_gt_u32 s69, 13
	s_cbranch_scc0 .LBB0_1674
	s_and_b64 vcc, exec, s[14:15]
	s_cbranch_vccz .LBB0_1677
	s_barrier

; #define PG8_STAGE(bufoff, gbase, voff) do { _Pragma("unroll") for (int _i = 0; _i < 2; ++_i) \
;         __builtin_amdgcn_global_load_lds((const unsigned*)((const char*)(gbase) + (voff)[_i]), (PG8_LAS unsigned*)(lds + (bufoff) + ldsw + _i * 8192), 16, 0, 0); } while (0)
; #define PG8_LDA(dst, b, h) do { _Pragma("unroll") for (int m = 0; m < 4; ++m) _Pragma("unroll") for (int k = 0; k < 2; ++k) dst[m][k] = *(const PG8_LAS bf16x8*)(lds + PG8_SA(b, h) + aoff + m * 2048 + k * 1024); } while (0)
; #define PG8_LDB(dst, b, h) do { _Pragma("unroll") for (int n = 0; n < 2; ++n) _Pragma("unroll") for (int k = 0; k < 2; ++k) dst[n][k] = *(const PG8_LAS bf16x8*)(lds + PG8_SB(b, h) + boff + n * 2048 + k * 1024); } while (0)
; #define PG8_MMA(ai, bj, At, Bt) do { __builtin_amdgcn_s_setprio(1); _Pragma("unroll") for (int m = 0; m < 4; ++m) _Pragma("unroll") for (int n = 0; n < 2; ++n) _Pragma("unroll") for (int k = 0; k < 2; ++k) \
;         acc[ai][bj][m][n] = __builtin_amdgcn_mfma_f32_16x16x32_bf16(Bt[n][k], At[m][k], acc[ai][bj][m][n], 0, 0, 0); __builtin_amdgcn_s_setprio(0); } while (0)
; #define PG8_WAIT_V(n) asm volatile("s_waitcnt vmcnt(" #n ")" ::: "memory")
; #define PG8_WAIT_L(n) asm volatile("s_waitcnt lgkmcnt(" #n ")" ::: "memory")
; #define PG8_BAR __builtin_amdgcn_s_barrier()
; #define PG8_SCHED __builtin_amdgcn_sched_barrier(0)
; template <class Epi, class Sched, bool ALIGN_EPI = false, bool SP2 = false>
; __device__ __forceinline__ void gemm_phase(PG8_LAS unsigned char* lds, const Gemm g, const Sched& S, const Epi& E) {
;     ...
;             PG8_LDB(B0, 0, 0); PG8_LDB(B1, 0, 1); PG8_SCHED; PG8_LDA(At, 0, 0); PG8_STAGE(PG8_SA(1, 1), a1 + hstep, voffA);
;             PG8_WAIT_V(8); PG8_WAIT_L(0); PG8_BAR; PG8_MMA(0, 0, At, B0); PG8_MMA(0, 1, At, B1); PG8_BAR; PG8_SCHED;
;             PG8_LDA(At, 0, 1); PG8_STAGE(PG8_SB(0, 0), b2, voffB); PG8_STAGE(PG8_SB(0, 1), b2 + hstep, voffB); PG8_STAGE(PG8_SA(0, 0), a2, voffA);
;             PG8_WAIT_V(8); PG8_WAIT_L(0); PG8_BAR; PG8_MMA(1, 0, At, B0); PG8_MMA(1, 1, At, B1); PG8_BAR; PG8_SCHED;
.LBB0_1874:
	ds_read_b128 v[146:149], v153
	ds_read_b128 v[156:159], v153 offset:1024
	ds_read_b128 v[160:163], v153 offset:2048
	ds_read_b128 v[164:167], v153 offset:3072
	ds_read_b128 v[168:171], v154
	ds_read_b128 v[172:175], v154 offset:1024
	ds_read_b128 v[176:179], v154 offset:2048
	ds_read_b128 v[182:185], v154 offset:3072
	s_add_u32 s26, s24, 0xfffc0080
	s_addc_u32 s27, s25, -1
	s_cmp_eq_u32 s57, 12
	s_cselect_b32 s29, s17, s27
	s_cselect_b32 s28, s49, s26
	s_cselect_b32 s27, s15, s56
	s_cselect_b32 s26, s52, s53
	s_add_i32 m0, s23, 0xc000
	ds_read_b128 v[186:189], v155
	ds_read_b128 v[190:193], v155 offset:1024
	ds_read_b128 v[194:197], v155 offset:2048
	ds_read_b128 v[198:201], v155 offset:3072
	ds_read_b128 v[202:205], v155 offset:4096
	ds_read_b128 v[206:209], v155 offset:5120
	ds_read_b128 v[210:213], v155 offset:6144
	ds_read_b128 v[214:217], v155 offset:7168
	global_load_lds_dwordx4 v138, s[24:25]
	s_add_i32 m0, s23, 0xe000
	s_nop 0
	global_load_lds_dwordx4 v140, s[24:25]
	s_waitcnt vmcnt(8)
	s_waitcnt lgkmcnt(0)
	s_barrier
	s_setprio 1
	s_waitcnt lgkmcnt(0)
	v_mfma_f32_16x16x32_bf16 v[126:129], v[146:149], v[186:189], v[126:129]
	v_mfma_f32_16x16x32_bf16 v[122:125], v[160:163], v[186:189], v[122:125]
	v_mfma_f32_16x16x32_bf16 v[110:113], v[146:149], v[194:197], v[110:113]
	v_mfma_f32_16x16x32_bf16 v[106:109], v[160:163], v[194:197], v[106:109]
	v_mfma_f32_16x16x32_bf16 v[94:97], v[146:149], v[202:205], v[94:97]
	v_mfma_f32_16x16x32_bf16 v[90:93], v[160:163], v[202:205], v[90:93]
	v_mfma_f32_16x16x32_bf16 v[78:81], v[146:149], v[210:213], v[78:81]
	v_mfma_f32_16x16x32_bf16 v[74:77], v[160:163], v[210:213], v[74:77]
	v_mfma_f32_16x16x32_bf16 v[126:129], v[156:159], v[190:193], v[126:129]
	v_mfma_f32_16x16x32_bf16 v[122:125], v[164:167], v[190:193], v[122:125]
	v_mfma_f32_16x16x32_bf16 v[110:113], v[156:159], v[198:201], v[110:113]
	v_mfma_f32_16x16x32_bf16 v[106:109], v[164:167], v[198:201], v[106:109]
	v_mfma_f32_16x16x32_bf16 v[94:97], v[156:159], v[206:209], v[94:97]
	v_mfma_f32_16x16x32_bf16 v[90:93], v[164:167], v[206:209], v[90:93]
	v_mfma_f32_16x16x32_bf16 v[78:81], v[156:159], v[214:217], v[78:81]
	v_mfma_f32_16x16x32_bf16 v[74:77], v[164:167], v[214:217], v[74:77]
	s_setprio 0
	s_setprio 1
	v_mfma_f32_16x16x32_bf16 v[118:121], v[168:171], v[186:189], v[118:121]
	v_mfma_f32_16x16x32_bf16 v[114:117], v[176:179], v[186:189], v[114:117]
	v_mfma_f32_16x16x32_bf16 v[102:105], v[168:171], v[194:197], v[102:105]
	v_mfma_f32_16x16x32_bf16 v[98:101], v[176:179], v[194:197], v[98:101]
	v_mfma_f32_16x16x32_bf16 v[86:89], v[168:171], v[202:205], v[86:89]
	v_mfma_f32_16x16x32_bf16 v[82:85], v[176:179], v[202:205], v[82:85]
	v_mfma_f32_16x16x32_bf16 v[70:73], v[168:171], v[210:213], v[70:73]
	v_mfma_f32_16x16x32_bf16 v[66:69], v[176:179], v[210:213], v[66:69]
	v_mfma_f32_16x16x32_bf16 v[118:121], v[172:175], v[190:193], v[118:121]
	v_mfma_f32_16x16x32_bf16 v[114:117], v[182:185], v[190:193], v[114:117]
	v_mfma_f32_16x16x32_bf16 v[102:105], v[172:175], v[198:201], v[102:105]
	v_mfma_f32_16x16x32_bf16 v[98:101], v[182:185], v[198:201], v[98:101]
	v_mfma_f32_16x16x32_bf16 v[86:89], v[172:175], v[206:209], v[86:89]
	v_mfma_f32_16x16x32_bf16 v[82:85], v[182:185], v[206:209], v[82:85]
	v_mfma_f32_16x16x32_bf16 v[70:73], v[172:175], v[214:217], v[70:73]
	v_mfma_f32_16x16x32_bf16 v[66:69], v[182:185], v[214:217], v[66:69]
	s_setprio 0
	s_barrier
	s_add_i32 s58, s44, s33
	s_mov_b32 m0, s58
	ds_read_b128 v[186:189], v155 offset:16384
	ds_read_b128 v[190:193], v155 offset:17408
	ds_read_b128 v[194:197], v155 offset:18432
	ds_read_b128 v[198:201], v155 offset:19456
	ds_read_b128 v[202:205], v155 offset:20480
	ds_read_b128 v[206:209], v155 offset:21504
	ds_read_b128 v[210:213], v155 offset:22528
	ds_read_b128 v[214:217], v155 offset:23552
	global_load_lds_dwordx4 v134, s[26:27]
	s_add_i32 m0, s58, 0x2000
	s_add_u32 s58, s26, 0x40000
	v_lshl_add_u64 v[220:221], s[26:27], 0, v[130:131]
	s_addc_u32 s59, s27, 0
	s_add_i32 s62, s45, s33
	global_load_lds_dwordx4 v130, s[26:27]
	s_mov_b32 m0, s62
	v_lshl_add_u64 v[224:225], s[28:29], 0, v[132:133]
	global_load_lds_dwordx4 v134, s[58:59]
	s_add_i32 m0, s62, 0x2000
	s_nop 0
	global_load_lds_dwordx4 v130, s[58:59]
	v_lshl_add_u64 v[222:223], s[28:29], 0, v[136:137]
	s_mov_b32 m0, s23
	s_nop 0
	global_load_lds_dwordx4 v136, s[28:29]
	s_mov_b32 m0, s36
	s_nop 0
	global_load_lds_dwordx4 v132, s[28:29]
	s_waitcnt vmcnt(8)
	s_waitcnt lgkmcnt(0)
	s_barrier
	s_setprio 1
	s_waitcnt lgkmcnt(0)
	v_mfma_f32_16x16x32_bf16 v[62:65], v[146:149], v[186:189], v[62:65]
	v_mfma_f32_16x16x32_bf16 v[58:61], v[160:163], v[186:189], v[58:61]
	v_mfma_f32_16x16x32_bf16 v[46:49], v[146:149], v[194:197], v[46:49]
	v_mfma_f32_16x16x32_bf16 v[42:45], v[160:163], v[194:197], v[42:45]
	v_mfma_f32_16x16x32_bf16 v[30:33], v[146:149], v[202:205], v[30:33]
	v_mfma_f32_16x16x32_bf16 v[26:29], v[160:163], v[202:205], v[26:29]
	v_mfma_f32_16x16x32_bf16 v[14:17], v[146:149], v[210:213], v[14:17]
	v_mfma_f32_16x16x32_bf16 v[10:13], v[160:163], v[210:213], v[10:13]
	v_mfma_f32_16x16x32_bf16 v[62:65], v[156:159], v[190:193], v[62:65]
	v_mfma_f32_16x16x32_bf16 v[58:61], v[164:167], v[190:193], v[58:61]
	v_mfma_f32_16x16x32_bf16 v[46:49], v[156:159], v[198:201], v[46:49]
	v_mfma_f32_16x16x32_bf16 v[42:45], v[164:167], v[198:201], v[42:45]
	v_mfma_f32_16x16x32_bf16 v[30:33], v[156:159], v[206:209], v[30:33]
	v_mfma_f32_16x16x32_bf16 v[26:29], v[164:167], v[206:209], v[26:29]
	v_mfma_f32_16x16x32_bf16 v[14:17], v[156:159], v[214:217], v[14:17]
	v_mfma_f32_16x16x32_bf16 v[10:13], v[164:167], v[214:217], v[10:13]
	s_setprio 0
	s_setprio 1
	v_mfma_f32_16x16x32_bf16 v[54:57], v[168:171], v[186:189], v[54:57]
	v_mfma_f32_16x16x32_bf16 v[50:53], v[176:179], v[186:189], v[50:53]
	v_mfma_f32_16x16x32_bf16 v[38:41], v[168:171], v[194:197], v[38:41]
	v_mfma_f32_16x16x32_bf16 v[34:37], v[176:179], v[194:197], v[34:37]
	v_mfma_f32_16x16x32_bf16 v[22:25], v[168:171], v[202:205], v[22:25]
	v_mfma_f32_16x16x32_bf16 v[18:21], v[176:179], v[202:205], v[18:21]
	v_mfma_f32_16x16x32_bf16 v[6:9], v[168:171], v[210:213], v[6:9]
	v_mfma_f32_16x16x32_bf16 v[2:5], v[176:179], v[210:213], v[2:5]
	v_mfma_f32_16x16x32_bf16 v[54:57], v[172:175], v[190:193], v[54:57]
	v_mfma_f32_16x16x32_bf16 v[50:53], v[182:185], v[190:193], v[50:53]
	v_mfma_f32_16x16x32_bf16 v[38:41], v[172:175], v[198:201], v[38:41]
	v_mfma_f32_16x16x32_bf16 v[34:37], v[182:185], v[198:201], v[34:37]
	v_mfma_f32_16x16x32_bf16 v[22:25], v[172:175], v[206:209], v[22:25]
	v_mfma_f32_16x16x32_bf16 v[18:21], v[182:185], v[206:209], v[18:21]
	v_mfma_f32_16x16x32_bf16 v[6:9], v[172:175], v[214:217], v[6:9]
	v_mfma_f32_16x16x32_bf16 v[2:5], v[182:185], v[214:217], v[2:5]
	s_setprio 0
	s_barrier
; #define PG8_STAGE(bufoff, gbase, voff) do { _Pragma("unroll") for (int _i = 0; _i < 2; ++_i) \
;         __builtin_amdgcn_global_load_lds((const unsigned*)((const char*)(gbase) + (voff)[_i]), (PG8_LAS unsigned*)(lds + (bufoff) + ldsw + _i * 8192), 16, 0, 0); } while (0)
; #define PG8_LDA(dst, b, h) do { _Pragma("unroll") for (int m = 0; m < 4; ++m) _Pragma("unroll") for (int k = 0; k < 2; ++k) dst[m][k] = *(const PG8_LAS bf16x8*)(lds + PG8_SA(b, h) + aoff + m * 2048 + k * 1024); } while (0)
; #define PG8_LDB(dst, b, h) do { _Pragma("unroll") for (int n = 0; n < 2; ++n) _Pragma("unroll") for (int k = 0; k < 2; ++k) dst[n][k] = *(const PG8_LAS bf16x8*)(lds + PG8_SB(b, h) + boff + n * 2048 + k * 1024); } while (0)
; #define PG8_MMA(ai, bj, At, Bt) do { __builtin_amdgcn_s_setprio(1); _Pragma("unroll") for (int m = 0; m < 4; ++m) _Pragma("unroll") for (int n = 0; n < 2; ++n) _Pragma("unroll") for (int k = 0; k < 2; ++k) \
;         acc[ai][bj][m][n] = __builtin_amdgcn_mfma_f32_16x16x32_bf16(Bt[n][k], At[m][k], acc[ai][bj][m][n], 0, 0, 0); __builtin_amdgcn_s_setprio(0); } while (0)
; #define PG8_WAIT_V(n) asm volatile("s_waitcnt vmcnt(" #n ")" ::: "memory")
; #define PG8_WAIT_L(n) asm volatile("s_waitcnt lgkmcnt(" #n ")" ::: "memory")
; #define PG8_BAR __builtin_amdgcn_s_barrier()
; #define PG8_SCHED __builtin_amdgcn_sched_barrier(0)
; template <class Epi, class Sched, bool ALIGN_EPI = false, bool SP2 = false>
; __device__ __forceinline__ void gemm_phase(PG8_LAS unsigned char* lds, const Gemm g, const Sched& S, const Epi& E) {
;     ...
;             PG8_LDB(B0, 1, 0); PG8_LDB(B1, 1, 1); PG8_SCHED; PG8_LDA(At, 1, 0); PG8_STAGE(PG8_SA(0, 1), a2 + hstep, voffA);
;             PG8_WAIT_V(8); PG8_WAIT_L(0); PG8_BAR; PG8_MMA(0, 0, At, B0); PG8_MMA(0, 1, At, B1); PG8_BAR; PG8_SCHED;
	s_add_i32 s58, 0, 0x18000
	s_add_i32 s59, 0, 0x1c000
	v_add_u32_e32 v164, s58, v151
	v_add_u32_e32 v181, s59, v151
	ds_read_b128 v[146:149], v164
	ds_read_b128 v[156:159], v164 offset:1024
	ds_read_b128 v[160:163], v164 offset:2048
	ds_read_b128 v[164:167], v164 offset:3072
	ds_read_b128 v[168:171], v181
	ds_read_b128 v[172:175], v181 offset:1024
	ds_read_b128 v[176:179], v181 offset:2048
	ds_read_b128 v[182:185], v181 offset:3072
	s_add_u32 s28, s28, 0x40000
	s_addc_u32 s29, s29, 0
	s_mov_b32 m0, s37
	ds_read_b128 v[186:189], v155 offset:32768
	ds_read_b128 v[190:193], v155 offset:33792
	ds_read_b128 v[194:197], v155 offset:34816
	ds_read_b128 v[198:201], v155 offset:35840
	ds_read_b128 v[202:205], v155 offset:36864
	ds_read_b128 v[206:209], v155 offset:37888
	ds_read_b128 v[210:213], v155 offset:38912
	ds_read_b128 v[214:217], v155 offset:39936
	global_load_lds_dwordx4 v136, s[28:29]
	v_lshl_add_u64 v[226:227], s[28:29], 0, v[132:133]
	s_mov_b32 m0, s38
	s_nop 0
	global_load_lds_dwordx4 v132, s[28:29]
	s_waitcnt vmcnt(8)
	s_waitcnt lgkmcnt(0)
	s_barrier
	s_setprio 1
	s_waitcnt lgkmcnt(0)
	v_mfma_f32_16x16x32_bf16 v[126:129], v[146:149], v[186:189], v[126:129]
	v_mfma_f32_16x16x32_bf16 v[122:125], v[160:163], v[186:189], v[122:125]
	v_mfma_f32_16x16x32_bf16 v[110:113], v[146:149], v[194:197], v[110:113]
	v_mfma_f32_16x16x32_bf16 v[106:109], v[160:163], v[194:197], v[106:109]
	v_mfma_f32_16x16x32_bf16 v[94:97], v[146:149], v[202:205], v[94:97]
	v_mfma_f32_16x16x32_bf16 v[90:93], v[160:163], v[202:205], v[90:93]
	v_mfma_f32_16x16x32_bf16 v[78:81], v[146:149], v[210:213], v[78:81]
	v_mfma_f32_16x16x32_bf16 v[74:77], v[160:163], v[210:213], v[74:77]
	v_mfma_f32_16x16x32_bf16 v[126:129], v[156:159], v[190:193], v[126:129]
	v_mfma_f32_16x16x32_bf16 v[122:125], v[164:167], v[190:193], v[122:125]
	v_mfma_f32_16x16x32_bf16 v[110:113], v[156:159], v[198:201], v[110:113]
	v_mfma_f32_16x16x32_bf16 v[106:109], v[164:167], v[198:201], v[106:109]
	v_mfma_f32_16x16x32_bf16 v[94:97], v[156:159], v[206:209], v[94:97]
	v_mfma_f32_16x16x32_bf16 v[90:93], v[164:167], v[206:209], v[90:93]
	v_mfma_f32_16x16x32_bf16 v[78:81], v[156:159], v[214:217], v[78:81]
	v_mfma_f32_16x16x32_bf16 v[74:77], v[164:167], v[214:217], v[74:77]
	s_setprio 0
	s_setprio 1
	v_mfma_f32_16x16x32_bf16 v[118:121], v[168:171], v[186:189], v[118:121]
	v_mfma_f32_16x16x32_bf16 v[114:117], v[176:179], v[186:189], v[114:117]
	v_mfma_f32_16x16x32_bf16 v[102:105], v[168:171], v[194:197], v[102:105]
	v_mfma_f32_16x16x32_bf16 v[98:101], v[176:179], v[194:197], v[98:101]
	v_mfma_f32_16x16x32_bf16 v[86:89], v[168:171], v[202:205], v[86:89]
	v_mfma_f32_16x16x32_bf16 v[82:85], v[176:179], v[202:205], v[82:85]
	v_mfma_f32_16x16x32_bf16 v[70:73], v[168:171], v[210:213], v[70:73]
	v_mfma_f32_16x16x32_bf16 v[66:69], v[176:179], v[210:213], v[66:69]
	v_mfma_f32_16x16x32_bf16 v[118:121], v[172:175], v[190:193], v[118:121]
	v_mfma_f32_16x16x32_bf16 v[114:117], v[182:185], v[190:193], v[114:117]
	v_mfma_f32_16x16x32_bf16 v[102:105], v[172:175], v[198:201], v[102:105]
	v_mfma_f32_16x16x32_bf16 v[98:101], v[182:185], v[198:201], v[98:101]
	v_mfma_f32_16x16x32_bf16 v[86:89], v[172:175], v[206:209], v[86:89]
	v_mfma_f32_16x16x32_bf16 v[82:85], v[182:185], v[206:209], v[82:85]
	v_mfma_f32_16x16x32_bf16 v[70:73], v[172:175], v[214:217], v[70:73]
	v_mfma_f32_16x16x32_bf16 v[66:69], v[182:185], v[214:217], v[66:69]
	s_setprio 0
	s_barrier
; #define PG8_STAGE(bufoff, gbase, voff) do { _Pragma("unroll") for (int _i = 0; _i < 2; ++_i) \
;         __builtin_amdgcn_global_load_lds((const unsigned*)((const char*)(gbase) + (voff)[_i]), (PG8_LAS unsigned*)(lds + (bufoff) + ldsw + _i * 8192), 16, 0, 0); } while (0)
; #define PG8_LDA(dst, b, h) do { _Pragma("unroll") for (int m = 0; m < 4; ++m) _Pragma("unroll") for (int k = 0; k < 2; ++k) dst[m][k] = *(const PG8_LAS bf16x8*)(lds + PG8_SA(b, h) + aoff + m * 2048 + k * 1024); } while (0)
; #define PG8_MMA(ai, bj, At, Bt) do { __builtin_amdgcn_s_setprio(1); _Pragma("unroll") for (int m = 0; m < 4; ++m) _Pragma("unroll") for (int n = 0; n < 2; ++n) _Pragma("unroll") for (int k = 0; k < 2; ++k) \
;         acc[ai][bj][m][n] = __builtin_amdgcn_mfma_f32_16x16x32_bf16(Bt[n][k], At[m][k], acc[ai][bj][m][n], 0, 0, 0); __builtin_amdgcn_s_setprio(0); } while (0)
; #define PG8_WAIT_V(n) asm volatile("s_waitcnt vmcnt(" #n ")" ::: "memory")
; #define PG8_WAIT_L(n) asm volatile("s_waitcnt lgkmcnt(" #n ")" ::: "memory")
; #define PG8_BAR __builtin_amdgcn_s_barrier()
; #define PG8_SCHED __builtin_amdgcn_sched_barrier(0)
; template <class Epi, class Sched, bool ALIGN_EPI = false, bool SP2 = false>
; __device__ __forceinline__ void gemm_phase(PG8_LAS unsigned char* lds, const Gemm g, const Sched& S, const Epi& E) {
;     ...
;         for (int t = 0; t < nt; t += 2) {
;             const bool last = (t == nt - 2);
;             const char* a1 = cA + (size_t)(t + 1) * kstep;
;             const char* a2 = last ? nA : cA + (size_t)(t + 2) * kstep; const char* b2 = last ? nB : cB + (size_t)(t + 2) * kstep;
;     ...
;             PG8_LDA(At, 1, 1); PG8_STAGE(PG8_SB(1, 0), b3, voffB); PG8_STAGE(PG8_SB(1, 1), b3 + hstep, voffB); PG8_STAGE(PG8_SA(1, 0), a3, voffA);
;             PG8_WAIT_V(8); PG8_WAIT_L(0); PG8_BAR; PG8_MMA(1, 0, At, B0); PG8_MMA(1, 1, At, B1); PG8_BAR; PG8_SCHED;
	s_add_i32 s28, s58, s33
	s_mov_b32 m0, s28
	ds_read_b128 v[186:189], v155 offset:49152
	ds_read_b128 v[190:193], v155 offset:50176
	ds_read_b128 v[194:197], v155 offset:51200
	ds_read_b128 v[198:201], v155 offset:52224
	ds_read_b128 v[202:205], v155 offset:53248
	ds_read_b128 v[206:209], v155 offset:54272
	ds_read_b128 v[210:213], v155 offset:55296
	ds_read_b128 v[214:217], v155 offset:56320
	s_add_u32 s98, s26, s10
	s_addc_u32 s99, s27, s11
	global_load_lds_dwordx4 v134, s[98:99]
	s_add_i32 m0, s28, 0x2000
	s_add_u32 s26, s26, 0x40080
	v_lshl_add_u64 v[218:219], v[220:221], 0, s[10:11]
	s_addc_u32 s27, s27, 0
	s_add_i32 s28, s59, s33
	global_load_lds_dwordx4 v[218:219], off
	s_mov_b32 m0, s28
	s_nop 0
	global_load_lds_dwordx4 v134, s[26:27]
	s_add_i32 m0, s28, 0x2000
	s_nop 0
	global_load_lds_dwordx4 v130, s[26:27]
	v_lshl_add_u64 v[218:219], v[222:223], 0, s[10:11]
	s_mov_b32 m0, s40
	s_nop 0
	global_load_lds_dwordx4 v[218:219], off
	v_lshl_add_u64 v[218:219], v[224:225], 0, s[10:11]
	s_mov_b32 m0, s41
	s_nop 0
	global_load_lds_dwordx4 v[218:219], off
	s_waitcnt vmcnt(8)
	s_waitcnt lgkmcnt(0)
	s_barrier
	s_setprio 1
	s_waitcnt lgkmcnt(0)
	v_mfma_f32_16x16x32_bf16 v[62:65], v[146:149], v[186:189], v[62:65]
	v_mfma_f32_16x16x32_bf16 v[58:61], v[160:163], v[186:189], v[58:61]
	v_mfma_f32_16x16x32_bf16 v[46:49], v[146:149], v[194:197], v[46:49]
	v_mfma_f32_16x16x32_bf16 v[42:45], v[160:163], v[194:197], v[42:45]
	v_mfma_f32_16x16x32_bf16 v[30:33], v[146:149], v[202:205], v[30:33]
	v_mfma_f32_16x16x32_bf16 v[26:29], v[160:163], v[202:205], v[26:29]
	v_mfma_f32_16x16x32_bf16 v[14:17], v[146:149], v[210:213], v[14:17]
	v_mfma_f32_16x16x32_bf16 v[10:13], v[160:163], v[210:213], v[10:13]
	v_mfma_f32_16x16x32_bf16 v[62:65], v[156:159], v[190:193], v[62:65]
	v_mfma_f32_16x16x32_bf16 v[58:61], v[164:167], v[190:193], v[58:61]
	v_mfma_f32_16x16x32_bf16 v[46:49], v[156:159], v[198:201], v[46:49]
	v_mfma_f32_16x16x32_bf16 v[42:45], v[164:167], v[198:201], v[42:45]
	v_mfma_f32_16x16x32_bf16 v[30:33], v[156:159], v[206:209], v[30:33]
	v_mfma_f32_16x16x32_bf16 v[26:29], v[164:167], v[206:209], v[26:29]
	v_mfma_f32_16x16x32_bf16 v[14:17], v[156:159], v[214:217], v[14:17]
	v_mfma_f32_16x16x32_bf16 v[10:13], v[164:167], v[214:217], v[10:13]
	s_setprio 0
	s_setprio 1
	v_mfma_f32_16x16x32_bf16 v[54:57], v[168:171], v[186:189], v[54:57]
	v_mfma_f32_16x16x32_bf16 v[50:53], v[176:179], v[186:189], v[50:53]
	v_mfma_f32_16x16x32_bf16 v[38:41], v[168:171], v[194:197], v[38:41]
	v_mfma_f32_16x16x32_bf16 v[34:37], v[176:179], v[194:197], v[34:37]
	v_mfma_f32_16x16x32_bf16 v[22:25], v[168:171], v[202:205], v[22:25]
	v_mfma_f32_16x16x32_bf16 v[18:21], v[176:179], v[202:205], v[18:21]
	v_mfma_f32_16x16x32_bf16 v[6:9], v[168:171], v[210:213], v[6:9]
	v_mfma_f32_16x16x32_bf16 v[2:5], v[176:179], v[210:213], v[2:5]
	v_mfma_f32_16x16x32_bf16 v[54:57], v[172:175], v[190:193], v[54:57]
	v_mfma_f32_16x16x32_bf16 v[50:53], v[182:185], v[190:193], v[50:53]
	v_mfma_f32_16x16x32_bf16 v[38:41], v[172:175], v[198:201], v[38:41]
	v_mfma_f32_16x16x32_bf16 v[34:37], v[182:185], v[198:201], v[34:37]
	v_mfma_f32_16x16x32_bf16 v[22:25], v[172:175], v[206:209], v[22:25]
	v_mfma_f32_16x16x32_bf16 v[18:21], v[182:185], v[206:209], v[18:21]
	v_mfma_f32_16x16x32_bf16 v[6:9], v[172:175], v[214:217], v[6:9]
	v_mfma_f32_16x16x32_bf16 v[2:5], v[182:185], v[214:217], v[2:5]
	s_setprio 0
	s_barrier
	s_add_i32 s57, s57, 2
	s_add_u32 s24, s24, 0x100
	s_addc_u32 s25, s25, 0
	s_add_u32 s53, s53, 0x100
	s_addc_u32 s56, s56, 0
	s_cmp_gt_u32 s57, 13
	s_cbranch_scc0 .LBB0_1874
	s_and_b64 vcc, exec, s[12:13]
	s_cbranch_vccz .LBB0_1877
	s_barrier

; #define PG8_STAGE(bufoff, gbase, voff) do { _Pragma("unroll") for (int _i = 0; _i < 2; ++_i) \
;         __builtin_amdgcn_global_load_lds((const unsigned*)((const char*)(gbase) + (voff)[_i]), (PG8_LAS unsigned*)(lds + (bufoff) + ldsw + _i * 8192), 16, 0, 0); } while (0)
; #define PG8_LDA(dst, b, h) do { _Pragma("unroll") for (int m = 0; m < 4; ++m) _Pragma("unroll") for (int k = 0; k < 2; ++k) dst[m][k] = *(const PG8_LAS bf16x8*)(lds + PG8_SA(b, h) + aoff + m * 2048 + k * 1024); } while (0)
; #define PG8_LDB(dst, b, h) do { _Pragma("unroll") for (int n = 0; n < 2; ++n) _Pragma("unroll") for (int k = 0; k < 2; ++k) dst[n][k] = *(const PG8_LAS bf16x8*)(lds + PG8_SB(b, h) + boff + n * 2048 + k * 1024); } while (0)
; #define PG8_MMA(ai, bj, At, Bt) do { __builtin_amdgcn_s_setprio(1); _Pragma("unroll") for (int m = 0; m < 4; ++m) _Pragma("unroll") for (int n = 0; n < 2; ++n) _Pragma("unroll") for (int k = 0; k < 2; ++k) \
;         acc[ai][bj][m][n] = __builtin_amdgcn_mfma_f32_16x16x32_bf16(Bt[n][k], At[m][k], acc[ai][bj][m][n], 0, 0, 0); __builtin_amdgcn_s_setprio(0); } while (0)
; #define PG8_WAIT_V(n) asm volatile("s_waitcnt vmcnt(" #n ")" ::: "memory")
; #define PG8_WAIT_L(n) asm volatile("s_waitcnt lgkmcnt(" #n ")" ::: "memory")
; #define PG8_BAR __builtin_amdgcn_s_barrier()
; #define PG8_SCHED __builtin_amdgcn_sched_barrier(0)
; template <class Epi, class Sched, bool ALIGN_EPI = false, bool SP2 = false>
; __device__ __forceinline__ void gemm_phase(PG8_LAS unsigned char* lds, const Gemm g, const Sched& S, const Epi& E) {
;     ...
;             PG8_LDB(B0, 0, 0); PG8_LDB(B1, 0, 1); PG8_SCHED; PG8_LDA(At, 0, 0); PG8_STAGE(PG8_SA(1, 1), a1 + hstep, voffA);
;             PG8_WAIT_V(8); PG8_WAIT_L(0); PG8_BAR; PG8_MMA(0, 0, At, B0); PG8_MMA(0, 1, At, B1); PG8_BAR; PG8_SCHED;
;             PG8_LDA(At, 0, 1); PG8_STAGE(PG8_SB(0, 0), b2, voffB); PG8_STAGE(PG8_SB(0, 1), b2 + hstep, voffB); PG8_STAGE(PG8_SA(0, 0), a2, voffA);
;             PG8_WAIT_V(8); PG8_WAIT_L(0); PG8_BAR; PG8_MMA(1, 0, At, B0); PG8_MMA(1, 1, At, B1); PG8_BAR; PG8_SCHED;
.LBB0_1957:
	ds_read_b128 v[154:157], v151
	ds_read_b128 v[158:161], v151 offset:1024
	ds_read_b128 v[162:165], v151 offset:2048
	ds_read_b128 v[166:169], v151 offset:3072
	ds_read_b128 v[170:173], v152
	ds_read_b128 v[174:177], v152 offset:1024
	ds_read_b128 v[182:185], v152 offset:2048
	ds_read_b128 v[186:189], v152 offset:3072
	s_add_u32 s28, s26, 0xfff50080
	s_addc_u32 s29, s27, -1
	s_cmp_eq_u32 s63, 40
	s_cselect_b32 s31, s5, s29
	s_cselect_b32 s30, s4, s28
	s_cselect_b32 s29, s25, s62
	s_cselect_b32 s28, s24, s59
	s_add_i32 m0, s37, 0xc000
	ds_read_b128 v[190:193], v153
	ds_read_b128 v[194:197], v153 offset:1024
	ds_read_b128 v[198:201], v153 offset:2048
	ds_read_b128 v[202:205], v153 offset:3072
	ds_read_b128 v[206:209], v153 offset:4096
	ds_read_b128 v[210:213], v153 offset:5120
	ds_read_b128 v[214:217], v153 offset:6144
	ds_read_b128 v[218:221], v153 offset:7168
	global_load_lds_dwordx4 v138, s[26:27]
	s_add_i32 m0, s37, 0xe000
	s_nop 0
	global_load_lds_dwordx4 v140, s[26:27]
	s_waitcnt vmcnt(8)
	s_waitcnt lgkmcnt(0)
	s_barrier
	s_setprio 1
	s_waitcnt lgkmcnt(0)
	v_mfma_f32_16x16x32_bf16 v[126:129], v[154:157], v[190:193], v[126:129]
	v_mfma_f32_16x16x32_bf16 v[122:125], v[162:165], v[190:193], v[122:125]
	v_mfma_f32_16x16x32_bf16 v[118:121], v[154:157], v[198:201], v[118:121]
	v_mfma_f32_16x16x32_bf16 v[110:113], v[162:165], v[198:201], v[110:113]
	v_mfma_f32_16x16x32_bf16 v[102:105], v[154:157], v[206:209], v[102:105]
	v_mfma_f32_16x16x32_bf16 v[94:97], v[162:165], v[206:209], v[94:97]
	v_mfma_f32_16x16x32_bf16 v[86:89], v[154:157], v[214:217], v[86:89]
	v_mfma_f32_16x16x32_bf16 v[78:81], v[162:165], v[214:217], v[78:81]
	v_mfma_f32_16x16x32_bf16 v[126:129], v[158:161], v[194:197], v[126:129]
	v_mfma_f32_16x16x32_bf16 v[122:125], v[166:169], v[194:197], v[122:125]
	v_mfma_f32_16x16x32_bf16 v[118:121], v[158:161], v[202:205], v[118:121]
	v_mfma_f32_16x16x32_bf16 v[110:113], v[166:169], v[202:205], v[110:113]
	v_mfma_f32_16x16x32_bf16 v[102:105], v[158:161], v[210:213], v[102:105]
	v_mfma_f32_16x16x32_bf16 v[94:97], v[166:169], v[210:213], v[94:97]
	v_mfma_f32_16x16x32_bf16 v[86:89], v[158:161], v[218:221], v[86:89]
	v_mfma_f32_16x16x32_bf16 v[78:81], v[166:169], v[218:221], v[78:81]
	s_setprio 0
	s_setprio 1
	v_mfma_f32_16x16x32_bf16 v[114:117], v[170:173], v[190:193], v[114:117]
	v_mfma_f32_16x16x32_bf16 v[106:109], v[182:185], v[190:193], v[106:109]
	v_mfma_f32_16x16x32_bf16 v[98:101], v[170:173], v[198:201], v[98:101]
	v_mfma_f32_16x16x32_bf16 v[90:93], v[182:185], v[198:201], v[90:93]
	v_mfma_f32_16x16x32_bf16 v[82:85], v[170:173], v[206:209], v[82:85]
	v_mfma_f32_16x16x32_bf16 v[74:77], v[182:185], v[206:209], v[74:77]
	v_mfma_f32_16x16x32_bf16 v[70:73], v[170:173], v[214:217], v[70:73]
	v_mfma_f32_16x16x32_bf16 v[66:69], v[182:185], v[214:217], v[66:69]
	v_mfma_f32_16x16x32_bf16 v[114:117], v[174:177], v[194:197], v[114:117]
	v_mfma_f32_16x16x32_bf16 v[106:109], v[186:189], v[194:197], v[106:109]
	v_mfma_f32_16x16x32_bf16 v[98:101], v[174:177], v[202:205], v[98:101]
	v_mfma_f32_16x16x32_bf16 v[90:93], v[186:189], v[202:205], v[90:93]
	v_mfma_f32_16x16x32_bf16 v[82:85], v[174:177], v[210:213], v[82:85]
	v_mfma_f32_16x16x32_bf16 v[74:77], v[186:189], v[210:213], v[74:77]
	v_mfma_f32_16x16x32_bf16 v[70:73], v[174:177], v[218:221], v[70:73]
	v_mfma_f32_16x16x32_bf16 v[66:69], v[186:189], v[218:221], v[66:69]
	s_setprio 0
	s_barrier
	s_add_i32 s64, s47, s36
	s_mov_b32 m0, s64
	ds_read_b128 v[190:193], v153 offset:16384
	ds_read_b128 v[194:197], v153 offset:17408
	ds_read_b128 v[198:201], v153 offset:18432
	ds_read_b128 v[202:205], v153 offset:19456
	ds_read_b128 v[206:209], v153 offset:20480
	ds_read_b128 v[210:213], v153 offset:21504
	ds_read_b128 v[214:217], v153 offset:22528
	ds_read_b128 v[218:221], v153 offset:23552
	global_load_lds_dwordx4 v132, s[28:29]
	s_add_i32 m0, s64, 0x2000
	s_add_u32 s64, s28, 0xb0000
	v_lshl_add_u64 v[178:179], s[28:29], 0, v[136:137]
	s_addc_u32 s65, s29, 0
	s_add_i32 s66, s48, s36
	global_load_lds_dwordx4 v136, s[28:29]
	s_mov_b32 m0, s66
	v_lshl_add_u64 v[224:225], s[30:31], 0, v[134:135]
	global_load_lds_dwordx4 v132, s[64:65]
	s_add_i32 m0, s66, 0x2000
	s_nop 0
	global_load_lds_dwordx4 v136, s[64:65]
	v_lshl_add_u64 v[222:223], s[30:31], 0, v[130:131]
	s_mov_b32 m0, s37
	s_nop 0
	global_load_lds_dwordx4 v130, s[30:31]
	s_mov_b32 m0, s38
	s_nop 0
	global_load_lds_dwordx4 v134, s[30:31]
	s_waitcnt vmcnt(8)
	s_waitcnt lgkmcnt(0)
	s_barrier
	s_setprio 1
	s_waitcnt lgkmcnt(0)
	v_mfma_f32_16x16x32_bf16 v[62:65], v[154:157], v[190:193], v[62:65]
	v_mfma_f32_16x16x32_bf16 v[58:61], v[162:165], v[190:193], v[58:61]
	v_mfma_f32_16x16x32_bf16 v[54:57], v[154:157], v[198:201], v[54:57]
	v_mfma_f32_16x16x32_bf16 v[46:49], v[162:165], v[198:201], v[46:49]
	v_mfma_f32_16x16x32_bf16 v[38:41], v[154:157], v[206:209], v[38:41]
	v_mfma_f32_16x16x32_bf16 v[30:33], v[162:165], v[206:209], v[30:33]
	v_mfma_f32_16x16x32_bf16 v[22:25], v[154:157], v[214:217], v[22:25]
	v_mfma_f32_16x16x32_bf16 v[14:17], v[162:165], v[214:217], v[14:17]
	v_mfma_f32_16x16x32_bf16 v[62:65], v[158:161], v[194:197], v[62:65]
	v_mfma_f32_16x16x32_bf16 v[58:61], v[166:169], v[194:197], v[58:61]
	v_mfma_f32_16x16x32_bf16 v[54:57], v[158:161], v[202:205], v[54:57]
	v_mfma_f32_16x16x32_bf16 v[46:49], v[166:169], v[202:205], v[46:49]
	v_mfma_f32_16x16x32_bf16 v[38:41], v[158:161], v[210:213], v[38:41]
	v_mfma_f32_16x16x32_bf16 v[30:33], v[166:169], v[210:213], v[30:33]
	v_mfma_f32_16x16x32_bf16 v[22:25], v[158:161], v[218:221], v[22:25]
	v_mfma_f32_16x16x32_bf16 v[14:17], v[166:169], v[218:221], v[14:17]
	s_setprio 0
	s_setprio 1
	v_mfma_f32_16x16x32_bf16 v[50:53], v[170:173], v[190:193], v[50:53]
	v_mfma_f32_16x16x32_bf16 v[42:45], v[182:185], v[190:193], v[42:45]
	v_mfma_f32_16x16x32_bf16 v[34:37], v[170:173], v[198:201], v[34:37]
	v_mfma_f32_16x16x32_bf16 v[26:29], v[182:185], v[198:201], v[26:29]
	v_mfma_f32_16x16x32_bf16 v[18:21], v[170:173], v[206:209], v[18:21]
	v_mfma_f32_16x16x32_bf16 v[10:13], v[182:185], v[206:209], v[10:13]
	v_mfma_f32_16x16x32_bf16 v[6:9], v[170:173], v[214:217], v[6:9]
	v_mfma_f32_16x16x32_bf16 v[2:5], v[182:185], v[214:217], v[2:5]
	v_mfma_f32_16x16x32_bf16 v[50:53], v[174:177], v[194:197], v[50:53]
	v_mfma_f32_16x16x32_bf16 v[42:45], v[186:189], v[194:197], v[42:45]
	v_mfma_f32_16x16x32_bf16 v[34:37], v[174:177], v[202:205], v[34:37]
	v_mfma_f32_16x16x32_bf16 v[26:29], v[186:189], v[202:205], v[26:29]
	v_mfma_f32_16x16x32_bf16 v[18:21], v[174:177], v[210:213], v[18:21]
	v_mfma_f32_16x16x32_bf16 v[10:13], v[186:189], v[210:213], v[10:13]
	v_mfma_f32_16x16x32_bf16 v[6:9], v[174:177], v[218:221], v[6:9]
	v_mfma_f32_16x16x32_bf16 v[2:5], v[186:189], v[218:221], v[2:5]
	s_setprio 0
	s_barrier
; #define PG8_STAGE(bufoff, gbase, voff) do { _Pragma("unroll") for (int _i = 0; _i < 2; ++_i) \
;         __builtin_amdgcn_global_load_lds((const unsigned*)((const char*)(gbase) + (voff)[_i]), (PG8_LAS unsigned*)(lds + (bufoff) + ldsw + _i * 8192), 16, 0, 0); } while (0)
; #define PG8_LDA(dst, b, h) do { _Pragma("unroll") for (int m = 0; m < 4; ++m) _Pragma("unroll") for (int k = 0; k < 2; ++k) dst[m][k] = *(const PG8_LAS bf16x8*)(lds + PG8_SA(b, h) + aoff + m * 2048 + k * 1024); } while (0)
; #define PG8_LDB(dst, b, h) do { _Pragma("unroll") for (int n = 0; n < 2; ++n) _Pragma("unroll") for (int k = 0; k < 2; ++k) dst[n][k] = *(const PG8_LAS bf16x8*)(lds + PG8_SB(b, h) + boff + n * 2048 + k * 1024); } while (0)
; #define PG8_MMA(ai, bj, At, Bt) do { __builtin_amdgcn_s_setprio(1); _Pragma("unroll") for (int m = 0; m < 4; ++m) _Pragma("unroll") for (int n = 0; n < 2; ++n) _Pragma("unroll") for (int k = 0; k < 2; ++k) \
;         acc[ai][bj][m][n] = __builtin_amdgcn_mfma_f32_16x16x32_bf16(Bt[n][k], At[m][k], acc[ai][bj][m][n], 0, 0, 0); __builtin_amdgcn_s_setprio(0); } while (0)
; #define PG8_WAIT_V(n) asm volatile("s_waitcnt vmcnt(" #n ")" ::: "memory")
; #define PG8_WAIT_L(n) asm volatile("s_waitcnt lgkmcnt(" #n ")" ::: "memory")
; #define PG8_BAR __builtin_amdgcn_s_barrier()
; #define PG8_SCHED __builtin_amdgcn_sched_barrier(0)
; template <class Epi, class Sched, bool ALIGN_EPI = false, bool SP2 = false>
; __device__ __forceinline__ void gemm_phase(PG8_LAS unsigned char* lds, const Gemm g, const Sched& S, const Epi& E) {
;     ...
;             PG8_LDB(B0, 1, 0); PG8_LDB(B1, 1, 1); PG8_SCHED; PG8_LDA(At, 1, 0); PG8_STAGE(PG8_SA(0, 1), a2 + hstep, voffA);
;             PG8_WAIT_V(8); PG8_WAIT_L(0); PG8_BAR; PG8_MMA(0, 0, At, B0); PG8_MMA(0, 1, At, B1); PG8_BAR; PG8_SCHED;
	s_add_i32 s64, 0, 0x18000
	s_add_i32 s65, 0, 0x1c000
	v_add_u32_e32 v166, s64, v149
	v_add_u32_e32 v181, s65, v149
	ds_read_b128 v[154:157], v166
	ds_read_b128 v[158:161], v166 offset:1024
	ds_read_b128 v[162:165], v166 offset:2048
	ds_read_b128 v[166:169], v166 offset:3072
	ds_read_b128 v[170:173], v181
	ds_read_b128 v[174:177], v181 offset:1024
	ds_read_b128 v[182:185], v181 offset:2048
	ds_read_b128 v[186:189], v181 offset:3072
	s_add_u32 s30, s30, 0xb0000
	s_addc_u32 s31, s31, 0
	s_mov_b32 m0, s39
	ds_read_b128 v[190:193], v153 offset:32768
	ds_read_b128 v[194:197], v153 offset:33792
	ds_read_b128 v[198:201], v153 offset:34816
	ds_read_b128 v[202:205], v153 offset:35840
	ds_read_b128 v[206:209], v153 offset:36864
	ds_read_b128 v[210:213], v153 offset:37888
	ds_read_b128 v[214:217], v153 offset:38912
	ds_read_b128 v[218:221], v153 offset:39936
	global_load_lds_dwordx4 v130, s[30:31]
	v_lshl_add_u64 v[226:227], s[30:31], 0, v[134:135]
	s_mov_b32 m0, s40
	s_nop 0
	global_load_lds_dwordx4 v134, s[30:31]
	s_waitcnt vmcnt(8)
	s_waitcnt lgkmcnt(0)
	s_barrier
	s_setprio 1
	s_waitcnt lgkmcnt(0)
	v_mfma_f32_16x16x32_bf16 v[126:129], v[154:157], v[190:193], v[126:129]
	v_mfma_f32_16x16x32_bf16 v[122:125], v[162:165], v[190:193], v[122:125]
	v_mfma_f32_16x16x32_bf16 v[118:121], v[154:157], v[198:201], v[118:121]
	v_mfma_f32_16x16x32_bf16 v[110:113], v[162:165], v[198:201], v[110:113]
	v_mfma_f32_16x16x32_bf16 v[102:105], v[154:157], v[206:209], v[102:105]
	v_mfma_f32_16x16x32_bf16 v[94:97], v[162:165], v[206:209], v[94:97]
	v_mfma_f32_16x16x32_bf16 v[86:89], v[154:157], v[214:217], v[86:89]
	v_mfma_f32_16x16x32_bf16 v[78:81], v[162:165], v[214:217], v[78:81]
	v_mfma_f32_16x16x32_bf16 v[126:129], v[158:161], v[194:197], v[126:129]
	v_mfma_f32_16x16x32_bf16 v[122:125], v[166:169], v[194:197], v[122:125]
	v_mfma_f32_16x16x32_bf16 v[118:121], v[158:161], v[202:205], v[118:121]
	v_mfma_f32_16x16x32_bf16 v[110:113], v[166:169], v[202:205], v[110:113]
	v_mfma_f32_16x16x32_bf16 v[102:105], v[158:161], v[210:213], v[102:105]
	v_mfma_f32_16x16x32_bf16 v[94:97], v[166:169], v[210:213], v[94:97]
	v_mfma_f32_16x16x32_bf16 v[86:89], v[158:161], v[218:221], v[86:89]
	v_mfma_f32_16x16x32_bf16 v[78:81], v[166:169], v[218:221], v[78:81]
	s_setprio 0
	s_setprio 1
	v_mfma_f32_16x16x32_bf16 v[114:117], v[170:173], v[190:193], v[114:117]
	v_mfma_f32_16x16x32_bf16 v[106:109], v[182:185], v[190:193], v[106:109]
	v_mfma_f32_16x16x32_bf16 v[98:101], v[170:173], v[198:201], v[98:101]
	v_mfma_f32_16x16x32_bf16 v[90:93], v[182:185], v[198:201], v[90:93]
	v_mfma_f32_16x16x32_bf16 v[82:85], v[170:173], v[206:209], v[82:85]
	v_mfma_f32_16x16x32_bf16 v[74:77], v[182:185], v[206:209], v[74:77]
	v_mfma_f32_16x16x32_bf16 v[70:73], v[170:173], v[214:217], v[70:73]
	v_mfma_f32_16x16x32_bf16 v[66:69], v[182:185], v[214:217], v[66:69]
	v_mfma_f32_16x16x32_bf16 v[114:117], v[174:177], v[194:197], v[114:117]
	v_mfma_f32_16x16x32_bf16 v[106:109], v[186:189], v[194:197], v[106:109]
	v_mfma_f32_16x16x32_bf16 v[98:101], v[174:177], v[202:205], v[98:101]
	v_mfma_f32_16x16x32_bf16 v[90:93], v[186:189], v[202:205], v[90:93]
	v_mfma_f32_16x16x32_bf16 v[82:85], v[174:177], v[210:213], v[82:85]
	v_mfma_f32_16x16x32_bf16 v[74:77], v[186:189], v[210:213], v[74:77]
	v_mfma_f32_16x16x32_bf16 v[70:73], v[174:177], v[218:221], v[70:73]
	v_mfma_f32_16x16x32_bf16 v[66:69], v[186:189], v[218:221], v[66:69]
	s_setprio 0
	s_barrier
; #define PG8_STAGE(bufoff, gbase, voff) do { _Pragma("unroll") for (int _i = 0; _i < 2; ++_i) \
;         __builtin_amdgcn_global_load_lds((const unsigned*)((const char*)(gbase) + (voff)[_i]), (PG8_LAS unsigned*)(lds + (bufoff) + ldsw + _i * 8192), 16, 0, 0); } while (0)
; #define PG8_LDA(dst, b, h) do { _Pragma("unroll") for (int m = 0; m < 4; ++m) _Pragma("unroll") for (int k = 0; k < 2; ++k) dst[m][k] = *(const PG8_LAS bf16x8*)(lds + PG8_SA(b, h) + aoff + m * 2048 + k * 1024); } while (0)
; #define PG8_MMA(ai, bj, At, Bt) do { __builtin_amdgcn_s_setprio(1); _Pragma("unroll") for (int m = 0; m < 4; ++m) _Pragma("unroll") for (int n = 0; n < 2; ++n) _Pragma("unroll") for (int k = 0; k < 2; ++k) \
;         acc[ai][bj][m][n] = __builtin_amdgcn_mfma_f32_16x16x32_bf16(Bt[n][k], At[m][k], acc[ai][bj][m][n], 0, 0, 0); __builtin_amdgcn_s_setprio(0); } while (0)
; #define PG8_WAIT_V(n) asm volatile("s_waitcnt vmcnt(" #n ")" ::: "memory")
; #define PG8_WAIT_L(n) asm volatile("s_waitcnt lgkmcnt(" #n ")" ::: "memory")
; #define PG8_BAR __builtin_amdgcn_s_barrier()
; #define PG8_SCHED __builtin_amdgcn_sched_barrier(0)
; template <class Epi, class Sched, bool ALIGN_EPI = false, bool SP2 = false>
; __device__ __forceinline__ void gemm_phase(PG8_LAS unsigned char* lds, const Gemm g, const Sched& S, const Epi& E) {
;     ...
;         for (int t = 0; t < nt; t += 2) {
;             const bool last = (t == nt - 2);
;             const char* a1 = cA + (size_t)(t + 1) * kstep;
;             const char* a2 = last ? nA : cA + (size_t)(t + 2) * kstep; const char* b2 = last ? nB : cB + (size_t)(t + 2) * kstep;
;     ...
;             PG8_LDA(At, 1, 1); PG8_STAGE(PG8_SB(1, 0), b3, voffB); PG8_STAGE(PG8_SB(1, 1), b3 + hstep, voffB); PG8_STAGE(PG8_SA(1, 0), a3, voffA);
;             PG8_WAIT_V(8); PG8_WAIT_L(0); PG8_BAR; PG8_MMA(1, 0, At, B0); PG8_MMA(1, 1, At, B1); PG8_BAR; PG8_SCHED;
	s_add_i32 s30, s64, s36
	s_mov_b32 m0, s30
	ds_read_b128 v[190:193], v153 offset:49152
	ds_read_b128 v[194:197], v153 offset:50176
	ds_read_b128 v[198:201], v153 offset:51200
	ds_read_b128 v[202:205], v153 offset:52224
	ds_read_b128 v[206:209], v153 offset:53248
	ds_read_b128 v[210:213], v153 offset:54272
	ds_read_b128 v[214:217], v153 offset:55296
	ds_read_b128 v[218:221], v153 offset:56320
	s_add_u32 s98, s28, s12
	s_addc_u32 s99, s29, s13
	global_load_lds_dwordx4 v132, s[98:99]
	s_add_i32 m0, s30, 0x2000
	s_add_u32 s28, s28, 0xb0080
	v_lshl_add_u64 v[146:147], v[178:179], 0, s[12:13]
	s_addc_u32 s29, s29, 0
	s_add_i32 s30, s65, s36
	global_load_lds_dwordx4 v[146:147], off
	s_mov_b32 m0, s30
	s_nop 0
	global_load_lds_dwordx4 v132, s[28:29]
	s_add_i32 m0, s30, 0x2000
	s_nop 0
	global_load_lds_dwordx4 v136, s[28:29]
	v_lshl_add_u64 v[146:147], v[222:223], 0, s[12:13]
	s_mov_b32 m0, s42
	s_nop 0
	global_load_lds_dwordx4 v[146:147], off
	v_lshl_add_u64 v[146:147], v[224:225], 0, s[12:13]
	s_mov_b32 m0, s43
	s_nop 0
	global_load_lds_dwordx4 v[146:147], off
	s_waitcnt vmcnt(8)
	s_waitcnt lgkmcnt(0)
	s_barrier
	s_setprio 1
	s_waitcnt lgkmcnt(0)
	v_mfma_f32_16x16x32_bf16 v[62:65], v[154:157], v[190:193], v[62:65]
	v_mfma_f32_16x16x32_bf16 v[58:61], v[162:165], v[190:193], v[58:61]
	v_mfma_f32_16x16x32_bf16 v[54:57], v[154:157], v[198:201], v[54:57]
	v_mfma_f32_16x16x32_bf16 v[46:49], v[162:165], v[198:201], v[46:49]
	v_mfma_f32_16x16x32_bf16 v[38:41], v[154:157], v[206:209], v[38:41]
	v_mfma_f32_16x16x32_bf16 v[30:33], v[162:165], v[206:209], v[30:33]
	v_mfma_f32_16x16x32_bf16 v[22:25], v[154:157], v[214:217], v[22:25]
	v_mfma_f32_16x16x32_bf16 v[14:17], v[162:165], v[214:217], v[14:17]
	v_mfma_f32_16x16x32_bf16 v[62:65], v[158:161], v[194:197], v[62:65]
	v_mfma_f32_16x16x32_bf16 v[58:61], v[166:169], v[194:197], v[58:61]
	v_mfma_f32_16x16x32_bf16 v[54:57], v[158:161], v[202:205], v[54:57]
	v_mfma_f32_16x16x32_bf16 v[46:49], v[166:169], v[202:205], v[46:49]
	v_mfma_f32_16x16x32_bf16 v[38:41], v[158:161], v[210:213], v[38:41]
	v_mfma_f32_16x16x32_bf16 v[30:33], v[166:169], v[210:213], v[30:33]
	v_mfma_f32_16x16x32_bf16 v[22:25], v[158:161], v[218:221], v[22:25]
	v_mfma_f32_16x16x32_bf16 v[14:17], v[166:169], v[218:221], v[14:17]
	s_setprio 0
	s_setprio 1
	v_mfma_f32_16x16x32_bf16 v[50:53], v[170:173], v[190:193], v[50:53]
	v_mfma_f32_16x16x32_bf16 v[42:45], v[182:185], v[190:193], v[42:45]
	v_mfma_f32_16x16x32_bf16 v[34:37], v[170:173], v[198:201], v[34:37]
	v_mfma_f32_16x16x32_bf16 v[26:29], v[182:185], v[198:201], v[26:29]
	v_mfma_f32_16x16x32_bf16 v[18:21], v[170:173], v[206:209], v[18:21]
	v_mfma_f32_16x16x32_bf16 v[10:13], v[182:185], v[206:209], v[10:13]
	v_mfma_f32_16x16x32_bf16 v[6:9], v[170:173], v[214:217], v[6:9]
	v_mfma_f32_16x16x32_bf16 v[2:5], v[182:185], v[214:217], v[2:5]
	v_mfma_f32_16x16x32_bf16 v[50:53], v[174:177], v[194:197], v[50:53]
	v_mfma_f32_16x16x32_bf16 v[42:45], v[186:189], v[194:197], v[42:45]
	v_mfma_f32_16x16x32_bf16 v[34:37], v[174:177], v[202:205], v[34:37]
	v_mfma_f32_16x16x32_bf16 v[26:29], v[186:189], v[202:205], v[26:29]
	v_mfma_f32_16x16x32_bf16 v[18:21], v[174:177], v[210:213], v[18:21]
	v_mfma_f32_16x16x32_bf16 v[10:13], v[186:189], v[210:213], v[10:13]
	v_mfma_f32_16x16x32_bf16 v[6:9], v[174:177], v[218:221], v[6:9]
	v_mfma_f32_16x16x32_bf16 v[2:5], v[186:189], v[218:221], v[2:5]
	s_setprio 0
	s_barrier
	s_add_i32 s63, s63, 2
	s_add_u32 s26, s26, 0x100
	s_addc_u32 s27, s27, 0
	s_add_u32 s59, s59, 0x100
	s_addc_u32 s62, s62, 0
	s_cmp_gt_u32 s63, 41
	s_cbranch_scc0 .LBB0_1957
	s_and_b64 vcc, exec, s[14:15]
	s_cbranch_vccz .LBB0_1960
	s_barrier
